# hand-written fast-path epilogue for FFN-in GEMM interior tiles + DPP/permlane reductions
# speedup vs baseline: 1.0112x; 1.0112x over previous
; DI F8 unpack8(uint4 u) { F8 r; r.v[0] = lo16(u.x); r.v[1] = hi16(u.x); r.v[2] = lo16(u.y); r.v[3] = hi16(u.y); r.v[4] = lo16(u.z); r.v[5] = hi16(u.z); r.v[6] = lo16(u.w); r.v[7] = hi16(u.w); return r; }
; DI void stb8(bf16_t* p, const F8& f) { *(uint4*)p = pack8(f); }
; DI float gsum16(float v) { v += __shfl_xor(v, 8); v += __shfl_xor(v, 4); v += __shfl_xor(v, 2); v += __shfl_xor(v, 1); return v; }
; DI float siluf(float x) { return x / (1.f + __expf(-x)); }
; DI void odd_elem(const Params& p, int o) {
;     ...
;         const F8 w0 = ldf8(cw + c), w1 = ldf8(cw + 3072 + c), w2 = ldf8(cw + 2 * 3072 + c), w3 = ldf8(cw + 3 * 3072 + c);
;         const bool last = (pos0 + 16 == len);
;         const float nsc = gi < 2 ? 0.08838834764831845f : 1.f;
; #pragma unroll
;         for (int t = 0; t < 16; ++t) {
;             const F8 x0 = unpack8(xr[t]);
;             F8 acc; float ss = 0.f;
; #pragma unroll
;             for (int k = 0; k < 8; ++k) { const float a = w3.v[k] * x0.v[k] + w2.v[k] * h1.v[k] + w1.v[k] * h2.v[k] + w0.v[k] * h3.v[k]; acc.v[k] = siluf(a); ss += acc.v[k] * acc.v[k]; }
;             if (gi < 4) {
;                 const float rs = rsqrtf(gsum16(ss) + EPS) * nsc;
; #pragma unroll
;                 for (int k = 0; k < 8; ++k) acc.v[k] *= rs;
;             }
;             stb8(Q2 + (size_t)(r0 + t) * 3072 + c, acc);
.LBB0_167:
	s_or_b64 exec, exec, s[36:37]
	s_waitcnt vmcnt(18)
	v_lshlrev_b64 v[16:17], 2, v[130:131]
	s_waitcnt vmcnt(17)
	v_lshl_add_u64 v[8:9], s[14:15], 0, v[16:17]
	v_lshl_add_u64 v[12:13], s[22:23], 0, v[16:17]
	v_lshl_add_u64 v[18:19], s[26:27], 0, v[16:17]
	v_lshl_add_u64 v[32:33], s[30:31], 0, v[16:17]
	v_mad_u64_u32 v[132:133], s[36:37], v6, -6, v[120:121]
	global_load_dwordx4 v[4:7], v[8:9], off offset:16
	global_load_dwordx4 v[20:23], v[8:9], off
	s_nop 0
	global_load_dwordx4 v[8:11], v[12:13], off offset:16
	global_load_dwordx4 v[24:27], v[12:13], off
	s_nop 0
	global_load_dwordx4 v[12:15], v[18:19], off offset:16
	global_load_dwordx4 v[28:31], v[18:19], off
	s_nop 0
	global_load_dwordx4 v[16:19], v[32:33], off offset:16
	s_nop 0
	global_load_dwordx4 v[32:35], v[32:33], off
	s_waitcnt vmcnt(23)
	v_lshlrev_b32_e32 v168, 16, v112
	v_and_b32_e32 v151, 0xffff0000, v112
	v_lshlrev_b32_e32 v156, 16, v113
	v_and_b32_e32 v145, 0xffff0000, v113
	v_mov_b32_e32 v150, v149
	v_lshlrev_b32_e32 v133, 16, v114
	v_and_b32_e32 v141, 0xffff0000, v114
	v_lshlrev_b32_e32 v138, 16, v115
	v_and_b32_e32 v139, 0xffff0000, v115
	v_cmp_gt_i32_e32 vcc, 2, v132
	v_mov_b32_e32 v85, 0x3db504f3
	v_mov_b32_e32 v144, v147
	v_cndmask_b32_e32 v129, 1.0, v85, vcc
	v_mov_b32_e32 v140, v143
	s_waitcnt vmcnt(9)
	v_pk_mov_b32 v[170:171], v[108:109], v[142:143] op_sel:[1,0]
	v_cmp_gt_i32_e64 s[36:37], 4, v132
	s_waitcnt vmcnt(5)
	v_mov_b32_e32 v109, v9
	v_mul_f32_e32 v158, v116, v20
	s_waitcnt vmcnt(2)
	v_mov_b32_e32 v112, v29
	s_waitcnt vmcnt(0)
	v_mov_b32_e32 v113, v33
	v_pk_mul_f32 v[160:161], v[150:151], v[112:113]
	v_pk_mov_b32 v[116:117], v[116:117], v[148:149] op_sel:[1,0]
	v_mov_b32_e32 v114, v21
	v_mov_b32_e32 v115, v25
	v_mul_f32_e32 v136, v32, v168
	v_mul_f32_e32 v152, v92, v28
	v_pk_mul_f32 v[116:117], v[116:117], v[114:115]
	v_mov_b32_e32 v153, v160
	v_mov_b32_e32 v137, v161
	v_mul_f32_e32 v154, v104, v24
	v_pk_add_f32 v[136:137], v[152:153], v[136:137]
	v_mov_b32_e32 v155, v117
	v_pk_add_f32 v[136:137], v[154:155], v[136:137]
	v_mov_b32_e32 v159, v116
	v_pk_add_f32 v[116:117], v[158:159], v[136:137]
	v_pk_mov_b32 v[160:161], v[118:119], v[146:147] op_sel:[1,0]
	v_mul_f32_e32 v21, 0xbfb8aa3b, v116
	v_exp_f32_e32 v136, v21
	v_mul_f32_e32 v21, 0xbfb8aa3b, v117
	v_exp_f32_e32 v137, v21
	v_mov_b32_e32 v119, v27
	v_mul_f32_e32 v164, v34, v156
	v_mul_f32_e32 v166, v94, v30
	v_pk_add_f32 v[136:137], v[136:137], 1.0 op_sel_hi:[1,0]
	v_mul_f32_e32 v154, v106, v26
	v_mul_f32_e32 v162, v96, v8
	v_rcp_f32_e32 v21, v137
	s_nop 0
	v_mul_f32_e32 v153, v117, v21
	v_mov_b32_e32 v117, v35
	v_rcp_f32_e32 v21, v136
	s_nop 0
	v_mul_f32_e32 v152, v116, v21
	v_mov_b32_e32 v116, v31
	v_mul_f32_e32 v136, v118, v22
	v_pk_mul_f32 v[158:159], v[144:145], v[116:117]
	v_mov_b32_e32 v118, v23
	v_pk_mul_f32 v[160:161], v[160:161], v[118:119]
	v_mov_b32_e32 v167, v158
	v_mov_b32_e32 v165, v159
	v_pk_add_f32 v[158:159], v[166:167], v[164:165]
	v_mov_b32_e32 v155, v161
	v_pk_add_f32 v[154:155], v[154:155], v[158:159]
	v_mov_b32_e32 v137, v160
	v_pk_add_f32 v[136:137], v[136:137], v[154:155]
	v_mul_f32_e32 v164, v108, v4
	v_mul_f32_e32 v21, 0xbfb8aa3b, v136
	v_exp_f32_e32 v154, v21
	v_mul_f32_e32 v21, 0xbfb8aa3b, v137
	v_exp_f32_e32 v155, v21
	v_mov_b32_e32 v108, v5
	v_mul_f32_e32 v158, v16, v133
	v_mul_f32_e32 v160, v84, v12
	v_pk_add_f32 v[154:155], v[154:155], 1.0 op_sel_hi:[1,0]
	v_pk_mul_f32 v[170:171], v[170:171], v[108:109]
	s_nop 0
	v_mov_b32_e32 v163, v171
	v_mov_b32_e32 v165, v170
	v_rcp_f32_e32 v21, v155
	s_nop 0
	v_mul_f32_e32 v155, v137, v21
	v_mov_b32_e32 v137, v17
	v_rcp_f32_e32 v21, v154
	s_nop 0
	v_mul_f32_e32 v154, v136, v21
	v_mov_b32_e32 v136, v13
	v_pk_mul_f32 v[166:167], v[140:141], v[136:137]
	s_nop 0
	v_mov_b32_e32 v161, v166
	v_mov_b32_e32 v159, v167
	v_pk_add_f32 v[158:159], v[160:161], v[158:159]
	s_nop 0
	v_pk_add_f32 v[158:159], v[162:163], v[158:159]
	s_nop 0
	v_pk_add_f32 v[158:159], v[164:165], v[158:159]
	s_nop 0
	v_mul_f32_e32 v5, 0xbfb8aa3b, v158
	v_exp_f32_e32 v160, v5
	v_mul_f32_e32 v5, 0xbfb8aa3b, v159
	v_exp_f32_e32 v161, v5
	s_nop 0
	v_pk_add_f32 v[160:161], v[160:161], 1.0 op_sel_hi:[1,0]
	s_nop 0
	v_rcp_f32_e32 v5, v161
	s_nop 0
	v_mul_f32_e32 v165, v159, v5
	v_rcp_f32_e32 v5, v160
	s_nop 0
	v_mul_f32_e32 v164, v158, v5
	v_pk_mul_f32 v[158:159], v[18:19], v[138:139]
	s_nop 0
	v_pk_fma_f32 v[158:159], v[86:87], v[14:15], v[158:159]
	s_nop 0
	v_pk_fma_f32 v[158:159], v[98:99], v[10:11], v[158:159]
	s_nop 0
	v_pk_fma_f32 v[110:111], v[110:111], v[6:7], v[158:159]
	s_nop 0
	v_mul_f32_e32 v5, 0xbfb8aa3b, v110
	v_exp_f32_e32 v158, v5
	v_mul_f32_e32 v5, 0xbfb8aa3b, v111
	v_exp_f32_e32 v159, v5
	s_nop 0
	v_pk_add_f32 v[158:159], v[158:159], 1.0 op_sel_hi:[1,0]
	s_nop 0
	v_rcp_f32_e32 v5, v159
	s_nop 0
	v_mul_f32_e32 v167, v111, v5
	v_rcp_f32_e32 v5, v158
	s_nop 0
	v_mul_f32_e32 v166, v110, v5
	s_and_saveexec_b64 s[40:41], s[36:37]
	s_cbranch_execz .LBB0_169
	v_pk_mul_f32 v[110:111], v[152:153], v[152:153]
	v_pk_mul_f32 v[158:159], v[154:155], v[154:155]
	v_add_f32_e32 v5, v110, v111
	v_add_f32_e32 v5, v5, v158
	v_pk_mul_f32 v[160:161], v[164:165], v[164:165]
	v_add_f32_e32 v5, v5, v159
	v_and_b32_e32 v13, 64, v251
	v_add_f32_e32 v5, v5, v160
	v_add_u32_e32 v13, 64, v13
	v_pk_mul_f32 v[162:163], v[166:167], v[166:167]
	v_add_f32_e32 v5, v5, v161
	v_add_f32_e32 v5, v5, v162
	v_add_f32_e32 v5, v5, v163
	s_waitcnt lgkmcnt(0)
	s_nop 1
	v_add_f32_dpp v5, v5, v5 row_ror:8 row_mask:0xf bank_mask:0xf
	s_waitcnt lgkmcnt(0)
	s_nop 1
	v_add_f32_dpp v5, v5, v5 row_ror:4 row_mask:0xf bank_mask:0xf
	s_waitcnt lgkmcnt(0)
	s_nop 1
	v_add_f32_dpp v5, v5, v5 row_ror:2 row_mask:0xf bank_mask:0xf
	s_waitcnt lgkmcnt(0)
	s_nop 1
	v_add_f32_dpp v5, v5, v5 row_ror:1 row_mask:0xf bank_mask:0xf
	v_add_f32_e32 v5, 0x358637bd, v5
	v_mul_f32_e32 v9, 0x4b800000, v5
	v_cmp_gt_f32_e32 vcc, s2, v5
	s_nop 1
	v_cndmask_b32_e32 v5, v5, v9, vcc
	v_rsq_f32_e32 v5, v5
	s_nop 0
	v_mul_f32_e32 v9, 0x45800000, v5
	v_cndmask_b32_e32 v5, v5, v9, vcc
	v_mul_f32_e32 v110, v129, v5
	v_pk_mul_f32 v[152:153], v[152:153], v[110:111] op_sel_hi:[1,0]
	v_pk_mul_f32 v[154:155], v[154:155], v[110:111] op_sel_hi:[1,0]
	v_pk_mul_f32 v[164:165], v[164:165], v[110:111] op_sel_hi:[1,0]
	v_pk_mul_f32 v[166:167], v[166:167], v[110:111] op_sel_hi:[1,0]
; DI F8 unpack8(uint4 u) { F8 r; r.v[0] = lo16(u.x); r.v[1] = hi16(u.x); r.v[2] = lo16(u.y); r.v[3] = hi16(u.y); r.v[4] = lo16(u.z); r.v[5] = hi16(u.z); r.v[6] = lo16(u.w); r.v[7] = hi16(u.w); return r; }
; DI void stb8(bf16_t* p, const F8& f) { *(uint4*)p = pack8(f); }
; DI float gsum16(float v) { v += __shfl_xor(v, 8); v += __shfl_xor(v, 4); v += __shfl_xor(v, 2); v += __shfl_xor(v, 1); return v; }
; DI float siluf(float x) { return x / (1.f + __expf(-x)); }
; DI void odd_elem(const Params& p, int o) {
;     ...
;         for (int t = 0; t < 16; ++t) {
;             const F8 x0 = unpack8(xr[t]);
;             F8 acc; float ss = 0.f;
; #pragma unroll
;             for (int k = 0; k < 8; ++k) { const float a = w3.v[k] * x0.v[k] + w2.v[k] * h1.v[k] + w1.v[k] * h2.v[k] + w0.v[k] * h3.v[k]; acc.v[k] = siluf(a); ss += acc.v[k] * acc.v[k]; }
;             if (gi < 4) {
;                 const float rs = rsqrtf(gsum16(ss) + EPS) * nsc;
; #pragma unroll
;                 for (int k = 0; k < 8; ++k) acc.v[k] *= rs;
;             }
;             stb8(Q2 + (size_t)(r0 + t) * 3072 + c, acc);
.LBB0_169:
	s_or_b64 exec, exec, s[40:41]
	v_mad_i64_i32 v[158:159], s[40:41], v123, s33, 0
	v_lshl_add_u64 v[110:111], v[130:131], 1, s[76:77]
	v_lshl_add_u64 v[158:159], v[110:111], 0, v[158:159]
	v_cvt_pk_bf16_f32 v152, v152, v153
	v_cvt_pk_bf16_f32 v153, v154, v155
	v_cvt_pk_bf16_f32 v154, v164, v165
	v_cvt_pk_bf16_f32 v155, v166, v167
	global_store_dwordx4 v[158:159], v[152:155], off
	v_lshlrev_b32_e32 v29, 16, v100
	v_lshlrev_b32_e32 v21, 16, v101
	v_and_b32_e32 v153, 0xffff0000, v100
	v_mov_b32_e32 v152, v151
	v_pk_mul_f32 v[162:163], v[112:113], v[152:153]
	v_and_b32_e32 v105, 0xffff0000, v101
	v_lshlrev_b32_e32 v5, 16, v102
	v_and_b32_e32 v97, 0xffff0000, v102
	v_lshlrev_b32_e32 v100, 16, v103
	v_and_b32_e32 v101, 0xffff0000, v103
	v_mul_f32_e32 v102, v32, v29
	v_mul_f32_e32 v154, v28, v168
	v_pk_mul_f32 v[148:149], v[148:149], v[114:115]
	v_mov_b32_e32 v155, v162
	v_mov_b32_e32 v103, v163
	v_mul_f32_e32 v158, v92, v24
	v_pk_add_f32 v[102:103], v[154:155], v[102:103]
	v_mov_b32_e32 v159, v149
	v_mul_f32_e32 v160, v104, v20
	v_pk_add_f32 v[102:103], v[158:159], v[102:103]
	v_mov_b32_e32 v161, v148
	v_pk_add_f32 v[102:103], v[160:161], v[102:103]
	v_mov_b32_e32 v104, v145
	v_mul_f32_e32 v9, 0xbfb8aa3b, v102
	v_exp_f32_e32 v148, v9
	v_mul_f32_e32 v9, 0xbfb8aa3b, v103
	v_exp_f32_e32 v149, v9
	v_pk_mul_f32 v[160:161], v[116:117], v[104:105]
	v_mul_f32_e32 v154, v30, v156
	v_pk_mul_f32 v[146:147], v[146:147], v[118:119]
	v_pk_add_f32 v[148:149], v[148:149], 1.0 op_sel_hi:[1,0]
	v_mov_b32_e32 v155, v160
	v_mul_f32_e32 v158, v94, v26
	v_mov_b32_e32 v159, v147
	v_mul_f32_e32 v106, v106, v22
	v_rcp_f32_e32 v9, v149
	s_nop 0
	v_mul_f32_e32 v103, v103, v9
	v_mov_b32_e32 v149, v161
	v_mov_b32_e32 v107, v146
	v_pk_mul_f32 v[142:143], v[142:143], v[108:109]
	v_rcp_f32_e32 v9, v148
	s_nop 0
	v_mul_f32_e32 v102, v102, v9
	v_mul_f32_e32 v148, v34, v21
	v_pk_add_f32 v[148:149], v[154:155], v[148:149]
	v_mul_f32_e32 v154, v84, v8
	v_pk_add_f32 v[148:149], v[158:159], v[148:149]
	v_mul_f32_e32 v158, v96, v4
	v_pk_add_f32 v[106:107], v[106:107], v[148:149]
	v_mov_b32_e32 v96, v141
	v_mul_f32_e32 v9, 0xbfb8aa3b, v106
	v_exp_f32_e32 v146, v9
	v_mul_f32_e32 v9, 0xbfb8aa3b, v107
	v_exp_f32_e32 v147, v9
	v_pk_mul_f32 v[160:161], v[136:137], v[96:97]
	v_mul_f32_e32 v148, v12, v133
	v_mov_b32_e32 v149, v160
	v_pk_add_f32 v[146:147], v[146:147], 1.0 op_sel_hi:[1,0]
	v_mov_b32_e32 v155, v143
	v_mov_b32_e32 v159, v142
	v_rcp_f32_e32 v9, v147
	s_nop 0
	v_mul_f32_e32 v107, v107, v9
	v_mov_b32_e32 v147, v161
	v_rcp_f32_e32 v9, v146
	s_nop 0
	v_mul_f32_e32 v106, v106, v9
	v_mul_f32_e32 v146, v16, v5
	v_pk_add_f32 v[146:147], v[148:149], v[146:147]
	s_nop 0
	v_pk_add_f32 v[146:147], v[154:155], v[146:147]
	s_nop 0
	v_pk_add_f32 v[142:143], v[158:159], v[146:147]
	s_nop 0
	v_mul_f32_e32 v9, 0xbfb8aa3b, v142
	v_exp_f32_e32 v146, v9
	v_mul_f32_e32 v9, 0xbfb8aa3b, v143
	v_exp_f32_e32 v147, v9
	s_nop 0
	v_pk_add_f32 v[146:147], v[146:147], 1.0 op_sel_hi:[1,0]
	s_nop 0
	v_rcp_f32_e32 v9, v147
	s_nop 0
	v_mul_f32_e32 v143, v143, v9
	v_rcp_f32_e32 v9, v146
	s_nop 0
	v_mul_f32_e32 v142, v142, v9
	v_pk_mul_f32 v[146:147], v[18:19], v[100:101]
	s_nop 0
	v_pk_fma_f32 v[146:147], v[14:15], v[138:139], v[146:147]
	s_nop 0
	v_pk_fma_f32 v[146:147], v[86:87], v[10:11], v[146:147]
	s_nop 0
	v_pk_fma_f32 v[98:99], v[98:99], v[6:7], v[146:147]
	s_nop 0
	v_mul_f32_e32 v9, 0xbfb8aa3b, v98
	v_exp_f32_e32 v146, v9
	v_mul_f32_e32 v9, 0xbfb8aa3b, v99
	v_exp_f32_e32 v147, v9
	s_nop 0
	v_pk_add_f32 v[146:147], v[146:147], 1.0 op_sel_hi:[1,0]
	s_nop 0
	v_rcp_f32_e32 v9, v147
	s_nop 0
	v_mul_f32_e32 v99, v99, v9
	v_rcp_f32_e32 v9, v146
	s_nop 0
	v_mul_f32_e32 v98, v98, v9
	s_and_saveexec_b64 s[40:41], s[36:37]
	s_cbranch_execz .LBB0_171
	v_pk_mul_f32 v[146:147], v[102:103], v[102:103]
	v_pk_mul_f32 v[148:149], v[106:107], v[106:107]
	v_add_f32_e32 v9, v146, v147
	v_add_f32_e32 v9, v9, v148
	v_pk_mul_f32 v[154:155], v[142:143], v[142:143]
	v_add_f32_e32 v9, v9, v149
	v_and_b32_e32 v17, 64, v251
	v_add_f32_e32 v9, v9, v154
	v_add_u32_e32 v17, 64, v17
	v_pk_mul_f32 v[158:159], v[98:99], v[98:99]
	v_add_f32_e32 v9, v9, v155
	v_add_f32_e32 v9, v9, v158
	v_add_f32_e32 v9, v9, v159
	s_waitcnt lgkmcnt(0)
	s_nop 1
	v_add_f32_dpp v9, v9, v9 row_ror:8 row_mask:0xf bank_mask:0xf
	s_waitcnt lgkmcnt(0)
	s_nop 1
	v_add_f32_dpp v9, v9, v9 row_ror:4 row_mask:0xf bank_mask:0xf
	s_waitcnt lgkmcnt(0)
	s_nop 1
	v_add_f32_dpp v9, v9, v9 row_ror:2 row_mask:0xf bank_mask:0xf
	s_waitcnt lgkmcnt(0)
	s_nop 1
	v_add_f32_dpp v9, v9, v9 row_ror:1 row_mask:0xf bank_mask:0xf
	v_add_f32_e32 v9, 0x358637bd, v9
	v_mul_f32_e32 v13, 0x4b800000, v9
	v_cmp_gt_f32_e32 vcc, s2, v9
	s_nop 1
	v_cndmask_b32_e32 v9, v9, v13, vcc
	v_rsq_f32_e32 v9, v9
	s_nop 0
	v_mul_f32_e32 v13, 0x45800000, v9
	v_cndmask_b32_e32 v9, v9, v13, vcc
	v_mul_f32_e32 v146, v129, v9
	v_pk_mul_f32 v[102:103], v[102:103], v[146:147] op_sel_hi:[1,0]
	v_pk_mul_f32 v[106:107], v[106:107], v[146:147] op_sel_hi:[1,0]
	v_pk_mul_f32 v[142:143], v[142:143], v[146:147] op_sel_hi:[1,0]
	v_pk_mul_f32 v[98:99], v[98:99], v[146:147] op_sel_hi:[1,0]
; DI F8 unpack8(uint4 u) { F8 r; r.v[0] = lo16(u.x); r.v[1] = hi16(u.x); r.v[2] = lo16(u.y); r.v[3] = hi16(u.y); r.v[4] = lo16(u.z); r.v[5] = hi16(u.z); r.v[6] = lo16(u.w); r.v[7] = hi16(u.w); return r; }
; DI void stb8(bf16_t* p, const F8& f) { *(uint4*)p = pack8(f); }
; DI float gsum16(float v) { v += __shfl_xor(v, 8); v += __shfl_xor(v, 4); v += __shfl_xor(v, 2); v += __shfl_xor(v, 1); return v; }
; DI float siluf(float x) { return x / (1.f + __expf(-x)); }
; DI void odd_elem(const Params& p, int o) {
;     ...
;         for (int t = 0; t < 16; ++t) {
;             const F8 x0 = unpack8(xr[t]);
;             F8 acc; float ss = 0.f;
; #pragma unroll
;             for (int k = 0; k < 8; ++k) { const float a = w3.v[k] * x0.v[k] + w2.v[k] * h1.v[k] + w1.v[k] * h2.v[k] + w0.v[k] * h3.v[k]; acc.v[k] = siluf(a); ss += acc.v[k] * acc.v[k]; }
;             if (gi < 4) {
;                 const float rs = rsqrtf(gsum16(ss) + EPS) * nsc;
; #pragma unroll
;                 for (int k = 0; k < 8; ++k) acc.v[k] *= rs;
;             }
;             stb8(Q2 + (size_t)(r0 + t) * 3072 + c, acc);
.LBB0_171:
	s_or_b64 exec, exec, s[40:41]
	v_or_b32_e32 v9, 1, v123
	v_mad_i64_i32 v[154:155], s[40:41], v9, s33, v[110:111]
	v_cvt_pk_bf16_f32 v146, v102, v103
	v_cvt_pk_bf16_f32 v147, v106, v107
	v_cvt_pk_bf16_f32 v148, v142, v143
	v_cvt_pk_bf16_f32 v149, v98, v99
	v_and_b32_e32 v143, 0xffff0000, v88
	v_mov_b32_e32 v142, v153
	global_store_dwordx4 v[154:155], v[146:149], off
	v_lshlrev_b32_e32 v31, 16, v88
	v_lshlrev_b32_e32 v23, 16, v89
	v_pk_mul_f32 v[148:149], v[112:113], v[142:143]
	v_and_b32_e32 v103, 0xffff0000, v89
	v_lshlrev_b32_e32 v9, 16, v90
	v_and_b32_e32 v93, 0xffff0000, v90
	v_lshlrev_b32_e32 v88, 16, v91
	v_and_b32_e32 v89, 0xffff0000, v91
	v_mul_f32_e32 v90, v32, v31
	v_mul_f32_e32 v98, v28, v29
	v_pk_mul_f32 v[150:151], v[150:151], v[114:115]
	v_mov_b32_e32 v99, v148
	v_mov_b32_e32 v91, v149
	v_mul_f32_e32 v106, v24, v168
	v_pk_add_f32 v[90:91], v[98:99], v[90:91]
	v_mov_b32_e32 v107, v151
	v_mul_f32_e32 v146, v92, v20
	v_pk_add_f32 v[90:91], v[106:107], v[90:91]
	v_mov_b32_e32 v147, v150
	v_pk_add_f32 v[90:91], v[146:147], v[90:91]
	v_mov_b32_e32 v102, v105
	v_mul_f32_e32 v13, 0xbfb8aa3b, v90
	v_exp_f32_e32 v98, v13
	v_mul_f32_e32 v13, 0xbfb8aa3b, v91
	v_exp_f32_e32 v99, v13
	v_pk_mul_f32 v[148:149], v[116:117], v[102:103]
	v_mul_f32_e32 v106, v30, v21
	v_pk_mul_f32 v[144:145], v[144:145], v[118:119]
	v_pk_add_f32 v[98:99], v[98:99], 1.0 op_sel_hi:[1,0]
	v_mov_b32_e32 v107, v148
	v_mul_f32_e32 v146, v26, v156
	v_mov_b32_e32 v147, v145
	v_mul_f32_e32 v94, v94, v22
	v_rcp_f32_e32 v13, v99
	s_nop 0
	v_mul_f32_e32 v91, v91, v13
	v_mov_b32_e32 v99, v149
	v_mov_b32_e32 v95, v144
	v_mov_b32_e32 v92, v97
	v_rcp_f32_e32 v13, v98
	s_nop 0
	v_mul_f32_e32 v90, v90, v13
	v_mul_f32_e32 v98, v34, v23
	v_pk_add_f32 v[98:99], v[106:107], v[98:99]
	v_mul_f32_e32 v106, v12, v5
	v_pk_add_f32 v[98:99], v[146:147], v[98:99]
	v_pk_mul_f32 v[146:147], v[136:137], v[92:93]
	v_pk_add_f32 v[94:95], v[94:95], v[98:99]
	v_pk_mul_f32 v[140:141], v[140:141], v[108:109]
	v_mul_f32_e32 v13, 0xbfb8aa3b, v94
	v_exp_f32_e32 v98, v13
	v_mul_f32_e32 v13, 0xbfb8aa3b, v95
	v_exp_f32_e32 v99, v13
	v_mov_b32_e32 v107, v146
	v_mul_f32_e32 v144, v8, v133
	v_mov_b32_e32 v145, v141
	v_pk_add_f32 v[98:99], v[98:99], 1.0 op_sel_hi:[1,0]
	v_mul_f32_e32 v84, v84, v4
	v_mov_b32_e32 v85, v140
	v_rcp_f32_e32 v13, v99
	s_nop 0
	v_mul_f32_e32 v95, v95, v13
	v_mov_b32_e32 v99, v147
	v_rcp_f32_e32 v13, v98
	s_nop 0
	v_mul_f32_e32 v94, v94, v13
	v_mul_f32_e32 v98, v16, v9
	v_pk_add_f32 v[98:99], v[106:107], v[98:99]
	s_nop 0
	v_pk_add_f32 v[98:99], v[144:145], v[98:99]
	s_nop 0
	v_pk_add_f32 v[84:85], v[84:85], v[98:99]
	s_nop 0
	v_mul_f32_e32 v13, 0xbfb8aa3b, v84
	v_exp_f32_e32 v98, v13
	v_mul_f32_e32 v13, 0xbfb8aa3b, v85
	v_exp_f32_e32 v99, v13
	s_nop 0
	v_pk_add_f32 v[98:99], v[98:99], 1.0 op_sel_hi:[1,0]
	s_nop 0
	v_rcp_f32_e32 v13, v99
	s_nop 0
	v_mul_f32_e32 v85, v85, v13
	v_rcp_f32_e32 v13, v98
	s_nop 0
	v_mul_f32_e32 v84, v84, v13
	v_pk_mul_f32 v[98:99], v[18:19], v[88:89]
	s_nop 0
	v_pk_fma_f32 v[98:99], v[14:15], v[100:101], v[98:99]
	s_nop 0
	v_pk_fma_f32 v[98:99], v[10:11], v[138:139], v[98:99]
	s_nop 0
	v_pk_fma_f32 v[86:87], v[86:87], v[6:7], v[98:99]
	s_nop 0
	v_mul_f32_e32 v13, 0xbfb8aa3b, v86
	v_exp_f32_e32 v98, v13
	v_mul_f32_e32 v13, 0xbfb8aa3b, v87
	v_exp_f32_e32 v99, v13
	s_nop 0
	v_pk_add_f32 v[98:99], v[98:99], 1.0 op_sel_hi:[1,0]
	s_nop 0
	v_rcp_f32_e32 v13, v99
	s_nop 0
	v_mul_f32_e32 v87, v87, v13
	v_rcp_f32_e32 v13, v98
	s_nop 0
	v_mul_f32_e32 v86, v86, v13
	s_and_saveexec_b64 s[40:41], s[36:37]
	s_cbranch_execz .LBB0_173
	v_pk_mul_f32 v[98:99], v[90:91], v[90:91]
	v_pk_mul_f32 v[106:107], v[94:95], v[94:95]
	v_add_f32_e32 v13, v98, v99
	v_add_f32_e32 v13, v13, v106
	v_pk_mul_f32 v[140:141], v[84:85], v[84:85]
	v_add_f32_e32 v13, v13, v107
	v_and_b32_e32 v25, 64, v251
	v_add_f32_e32 v13, v13, v140
	v_add_u32_e32 v25, 64, v25
	v_pk_mul_f32 v[144:145], v[86:87], v[86:87]
	v_add_f32_e32 v13, v13, v141
	v_add_f32_e32 v13, v13, v144
	v_add_f32_e32 v13, v13, v145
	s_waitcnt lgkmcnt(0)
	s_nop 1
	v_add_f32_dpp v13, v13, v13 row_ror:8 row_mask:0xf bank_mask:0xf
	s_waitcnt lgkmcnt(0)
	s_nop 1
	v_add_f32_dpp v13, v13, v13 row_ror:4 row_mask:0xf bank_mask:0xf
	s_waitcnt lgkmcnt(0)
	s_nop 1
	v_add_f32_dpp v13, v13, v13 row_ror:2 row_mask:0xf bank_mask:0xf
	s_waitcnt lgkmcnt(0)
	s_nop 1
	v_add_f32_dpp v13, v13, v13 row_ror:1 row_mask:0xf bank_mask:0xf
	v_add_f32_e32 v13, 0x358637bd, v13
	v_mul_f32_e32 v17, 0x4b800000, v13
	v_cmp_gt_f32_e32 vcc, s2, v13
	s_nop 1
	v_cndmask_b32_e32 v13, v13, v17, vcc
	v_rsq_f32_e32 v13, v13
	s_nop 0
	v_mul_f32_e32 v17, 0x45800000, v13
	v_cndmask_b32_e32 v13, v13, v17, vcc
	v_mul_f32_e32 v98, v129, v13
	v_pk_mul_f32 v[90:91], v[90:91], v[98:99] op_sel_hi:[1,0]
	v_pk_mul_f32 v[94:95], v[94:95], v[98:99] op_sel_hi:[1,0]
	v_pk_mul_f32 v[84:85], v[84:85], v[98:99] op_sel_hi:[1,0]
	v_pk_mul_f32 v[86:87], v[86:87], v[98:99] op_sel_hi:[1,0]
; DI F8 unpack8(uint4 u) { F8 r; r.v[0] = lo16(u.x); r.v[1] = hi16(u.x); r.v[2] = lo16(u.y); r.v[3] = hi16(u.y); r.v[4] = lo16(u.z); r.v[5] = hi16(u.z); r.v[6] = lo16(u.w); r.v[7] = hi16(u.w); return r; }
; DI void stb8(bf16_t* p, const F8& f) { *(uint4*)p = pack8(f); }
; DI float gsum16(float v) { v += __shfl_xor(v, 8); v += __shfl_xor(v, 4); v += __shfl_xor(v, 2); v += __shfl_xor(v, 1); return v; }
; DI float siluf(float x) { return x / (1.f + __expf(-x)); }
; DI void odd_elem(const Params& p, int o) {
;     ...
;         for (int t = 0; t < 16; ++t) {
;             const F8 x0 = unpack8(xr[t]);
;             F8 acc; float ss = 0.f;
; #pragma unroll
;             for (int k = 0; k < 8; ++k) { const float a = w3.v[k] * x0.v[k] + w2.v[k] * h1.v[k] + w1.v[k] * h2.v[k] + w0.v[k] * h3.v[k]; acc.v[k] = siluf(a); ss += acc.v[k] * acc.v[k]; }
;             if (gi < 4) {
;                 const float rs = rsqrtf(gsum16(ss) + EPS) * nsc;
; #pragma unroll
;                 for (int k = 0; k < 8; ++k) acc.v[k] *= rs;
;             }
;             stb8(Q2 + (size_t)(r0 + t) * 3072 + c, acc);
.LBB0_173:
	s_or_b64 exec, exec, s[40:41]
	v_or_b32_e32 v13, 2, v123
	v_and_b32_e32 v107, 0xffff0000, v80
	v_mov_b32_e32 v106, v143
	v_mad_i64_i32 v[98:99], s[40:41], v13, s33, v[110:111]
	v_cvt_pk_bf16_f32 v144, v90, v91
	v_cvt_pk_bf16_f32 v145, v94, v95
	v_cvt_pk_bf16_f32 v146, v84, v85
	v_cvt_pk_bf16_f32 v147, v86, v87
	v_lshlrev_b32_e32 v33, 16, v80
	v_pk_mul_f32 v[140:141], v[112:113], v[106:107]
	global_store_dwordx4 v[98:99], v[144:147], off
	v_lshlrev_b32_e32 v25, 16, v81
	v_and_b32_e32 v99, 0xffff0000, v81
	v_lshlrev_b32_e32 v13, 16, v82
	v_and_b32_e32 v87, 0xffff0000, v82
	v_lshlrev_b32_e32 v80, 16, v83
	v_and_b32_e32 v81, 0xffff0000, v83
	v_mul_f32_e32 v82, v32, v33
	v_mul_f32_e32 v84, v28, v31
	v_pk_mul_f32 v[144:145], v[114:115], v[152:153]
	v_mov_b32_e32 v85, v140
	v_mov_b32_e32 v83, v141
	v_mul_f32_e32 v90, v24, v29
	v_pk_add_f32 v[82:83], v[84:85], v[82:83]
	v_mov_b32_e32 v91, v145
	v_mul_f32_e32 v94, v20, v168
	v_pk_add_f32 v[82:83], v[90:91], v[82:83]
	v_mov_b32_e32 v95, v144
	v_pk_add_f32 v[82:83], v[94:95], v[82:83]
	v_mov_b32_e32 v98, v103
	v_mul_f32_e32 v17, 0xbfb8aa3b, v82
	v_exp_f32_e32 v84, v17
	v_mul_f32_e32 v17, 0xbfb8aa3b, v83
	v_exp_f32_e32 v85, v17
	v_pk_mul_f32 v[144:145], v[116:117], v[98:99]
	v_pk_mul_f32 v[104:105], v[118:119], v[104:105]
	v_mov_b32_e32 v91, v144
	v_pk_add_f32 v[84:85], v[84:85], 1.0 op_sel_hi:[1,0]
	v_mul_f32_e32 v94, v26, v21
	v_mov_b32_e32 v95, v105
	v_mul_f32_e32 v140, v22, v156
	v_mov_b32_e32 v141, v104
	v_rcp_f32_e32 v17, v85
	s_nop 0
	v_mul_f32_e32 v83, v83, v17
	v_mul_f32_e32 v90, v30, v23
	v_pk_mul_f32 v[96:97], v[108:109], v[96:97]
	v_mul_f32_e32 v104, v8, v5
	v_rcp_f32_e32 v17, v84
	s_nop 0
	v_mul_f32_e32 v82, v82, v17
	v_mul_f32_e32 v84, v34, v25
	v_mov_b32_e32 v85, v145
	v_pk_add_f32 v[84:85], v[90:91], v[84:85]
	v_mov_b32_e32 v105, v97
	v_pk_add_f32 v[84:85], v[94:95], v[84:85]
	s_nop 0
	v_pk_add_f32 v[84:85], v[140:141], v[84:85]
	v_mul_f32_e32 v140, v4, v133
	v_mul_f32_e32 v17, 0xbfb8aa3b, v84
	v_exp_f32_e32 v90, v17
	v_mul_f32_e32 v17, 0xbfb8aa3b, v85
	v_exp_f32_e32 v91, v17
	v_mov_b32_e32 v141, v96
	v_pk_add_f32 v[90:91], v[90:91], 1.0 op_sel_hi:[1,0]
	s_nop 0
	v_rcp_f32_e32 v17, v91
	s_nop 0
	v_mul_f32_e32 v85, v85, v17
	v_mul_f32_e32 v94, v12, v9
	v_mov_b32_e32 v86, v93
	v_pk_mul_f32 v[144:145], v[136:137], v[86:87]
	v_rcp_f32_e32 v17, v90
	s_nop 0
	v_mul_f32_e32 v84, v84, v17
	v_mul_f32_e32 v90, v16, v13
	v_mov_b32_e32 v95, v144
	v_mov_b32_e32 v91, v145
	v_pk_add_f32 v[90:91], v[94:95], v[90:91]
	s_nop 0
	v_pk_add_f32 v[90:91], v[104:105], v[90:91]
	s_nop 0
	v_pk_add_f32 v[90:91], v[140:141], v[90:91]
	s_nop 0
	v_mul_f32_e32 v17, 0xbfb8aa3b, v90
	v_exp_f32_e32 v94, v17
	v_mul_f32_e32 v17, 0xbfb8aa3b, v91
	v_exp_f32_e32 v95, v17
	s_nop 0
	v_pk_add_f32 v[94:95], v[94:95], 1.0 op_sel_hi:[1,0]
	s_nop 0
	v_rcp_f32_e32 v17, v95
	s_nop 0
	v_mul_f32_e32 v91, v91, v17
	v_rcp_f32_e32 v17, v94
	s_nop 0
	v_mul_f32_e32 v90, v90, v17
	v_pk_mul_f32 v[94:95], v[18:19], v[80:81]
	s_nop 0
	v_pk_fma_f32 v[94:95], v[14:15], v[88:89], v[94:95]
	s_nop 0
	v_pk_fma_f32 v[94:95], v[10:11], v[100:101], v[94:95]
	s_nop 0
	v_pk_fma_f32 v[94:95], v[6:7], v[138:139], v[94:95]
	s_nop 0
	v_mul_f32_e32 v17, 0xbfb8aa3b, v94
	v_exp_f32_e32 v96, v17
	v_mul_f32_e32 v17, 0xbfb8aa3b, v95
	v_exp_f32_e32 v97, v17
	s_nop 0
	v_pk_add_f32 v[96:97], v[96:97], 1.0 op_sel_hi:[1,0]
	s_nop 0
	v_rcp_f32_e32 v17, v97
	s_nop 0
	v_mul_f32_e32 v95, v95, v17
	v_rcp_f32_e32 v17, v96
	s_nop 0
	v_mul_f32_e32 v94, v94, v17
	s_and_saveexec_b64 s[40:41], s[36:37]
	s_cbranch_execz .LBB0_175
	v_pk_mul_f32 v[96:97], v[82:83], v[82:83]
	v_pk_mul_f32 v[104:105], v[84:85], v[84:85]
	v_add_f32_e32 v17, v96, v97
	v_add_f32_e32 v17, v17, v104
	v_pk_mul_f32 v[138:139], v[90:91], v[90:91]
	v_add_f32_e32 v17, v17, v105
	v_and_b32_e32 v35, 64, v251
	v_add_f32_e32 v17, v17, v138
	v_add_u32_e32 v35, 64, v35
	v_pk_mul_f32 v[140:141], v[94:95], v[94:95]
	v_add_f32_e32 v17, v17, v139
	v_add_f32_e32 v17, v17, v140
	v_add_f32_e32 v17, v17, v141
	s_waitcnt lgkmcnt(0)
	s_nop 1
	v_add_f32_dpp v17, v17, v17 row_ror:8 row_mask:0xf bank_mask:0xf
	s_waitcnt lgkmcnt(0)
	s_nop 1
	v_add_f32_dpp v17, v17, v17 row_ror:4 row_mask:0xf bank_mask:0xf
	s_waitcnt lgkmcnt(0)
	s_nop 1
	v_add_f32_dpp v17, v17, v17 row_ror:2 row_mask:0xf bank_mask:0xf
	s_waitcnt lgkmcnt(0)
	s_nop 1
	v_add_f32_dpp v17, v17, v17 row_ror:1 row_mask:0xf bank_mask:0xf
	v_add_f32_e32 v17, 0x358637bd, v17
	v_mul_f32_e32 v27, 0x4b800000, v17
	v_cmp_gt_f32_e32 vcc, s2, v17
	s_nop 1
	v_cndmask_b32_e32 v17, v17, v27, vcc
	v_rsq_f32_e32 v17, v17
	s_nop 0
	v_mul_f32_e32 v27, 0x45800000, v17
	v_cndmask_b32_e32 v17, v17, v27, vcc
	v_mul_f32_e32 v96, v129, v17
	v_pk_mul_f32 v[82:83], v[82:83], v[96:97] op_sel_hi:[1,0]
	v_pk_mul_f32 v[84:85], v[84:85], v[96:97] op_sel_hi:[1,0]
	v_pk_mul_f32 v[90:91], v[90:91], v[96:97] op_sel_hi:[1,0]
	v_pk_mul_f32 v[94:95], v[94:95], v[96:97] op_sel_hi:[1,0]
; DI F8 unpack8(uint4 u) { F8 r; r.v[0] = lo16(u.x); r.v[1] = hi16(u.x); r.v[2] = lo16(u.y); r.v[3] = hi16(u.y); r.v[4] = lo16(u.z); r.v[5] = hi16(u.z); r.v[6] = lo16(u.w); r.v[7] = hi16(u.w); return r; }
; DI void stb8(bf16_t* p, const F8& f) { *(uint4*)p = pack8(f); }
; DI float gsum16(float v) { v += __shfl_xor(v, 8); v += __shfl_xor(v, 4); v += __shfl_xor(v, 2); v += __shfl_xor(v, 1); return v; }
; DI float siluf(float x) { return x / (1.f + __expf(-x)); }
; DI void odd_elem(const Params& p, int o) {
;     ...
;         for (int t = 0; t < 16; ++t) {
;             const F8 x0 = unpack8(xr[t]);
;             F8 acc; float ss = 0.f;
; #pragma unroll
;             for (int k = 0; k < 8; ++k) { const float a = w3.v[k] * x0.v[k] + w2.v[k] * h1.v[k] + w1.v[k] * h2.v[k] + w0.v[k] * h3.v[k]; acc.v[k] = siluf(a); ss += acc.v[k] * acc.v[k]; }
;             if (gi < 4) {
;                 const float rs = rsqrtf(gsum16(ss) + EPS) * nsc;
; #pragma unroll
;                 for (int k = 0; k < 8; ++k) acc.v[k] *= rs;
;             }
;             stb8(Q2 + (size_t)(r0 + t) * 3072 + c, acc);
.LBB0_175:
	s_or_b64 exec, exec, s[40:41]
	v_or_b32_e32 v17, 3, v123
	v_and_b32_e32 v105, 0xffff0000, v76
	v_mov_b32_e32 v104, v107
	v_mad_i64_i32 v[96:97], s[40:41], v17, s33, v[110:111]
	v_cvt_pk_bf16_f32 v82, v82, v83
	v_cvt_pk_bf16_f32 v83, v84, v85
	v_cvt_pk_bf16_f32 v84, v90, v91
	v_cvt_pk_bf16_f32 v85, v94, v95
	v_lshlrev_b32_e32 v35, 16, v76
	v_pk_mul_f32 v[138:139], v[112:113], v[104:105]
	global_store_dwordx4 v[96:97], v[82:85], off
	v_lshlrev_b32_e32 v27, 16, v77
	v_and_b32_e32 v95, 0xffff0000, v77
	v_lshlrev_b32_e32 v17, 16, v78
	v_and_b32_e32 v85, 0xffff0000, v78
	v_lshlrev_b32_e32 v76, 16, v79
	v_and_b32_e32 v77, 0xffff0000, v79
	v_mul_f32_e32 v78, v32, v35
	v_mul_f32_e32 v82, v28, v33
	v_pk_mul_f32 v[140:141], v[114:115], v[142:143]
	v_mov_b32_e32 v83, v138
	v_mov_b32_e32 v79, v139
	v_mul_f32_e32 v90, v24, v31
	v_pk_add_f32 v[78:79], v[82:83], v[78:79]
	v_mov_b32_e32 v91, v141
	v_mul_f32_e32 v96, v20, v29
	v_pk_add_f32 v[78:79], v[90:91], v[78:79]
	v_mov_b32_e32 v97, v140
	v_pk_add_f32 v[78:79], v[96:97], v[78:79]
	v_pk_mul_f32 v[102:103], v[118:119], v[102:103]
	v_mul_f32_e32 v29, 0xbfb8aa3b, v78
	v_exp_f32_e32 v82, v29
	v_mul_f32_e32 v29, 0xbfb8aa3b, v79
	v_exp_f32_e32 v83, v29
	v_mul_f32_e32 v96, v26, v23
	v_mov_b32_e32 v97, v103
	v_mul_f32_e32 v138, v22, v21
	v_pk_add_f32 v[82:83], v[82:83], 1.0 op_sel_hi:[1,0]
	v_mov_b32_e32 v139, v102
	v_pk_mul_f32 v[92:93], v[108:109], v[92:93]
	v_mul_f32_e32 v102, v8, v9
	v_mov_b32_e32 v103, v93
	v_rcp_f32_e32 v29, v83
	s_nop 0
	v_mul_f32_e32 v79, v79, v29
	v_mov_b32_e32 v94, v99
	v_pk_mul_f32 v[140:141], v[116:117], v[94:95]
	v_rcp_f32_e32 v29, v82
	s_nop 0
	v_mul_f32_e32 v78, v78, v29
	v_mul_f32_e32 v82, v34, v27
	v_mul_f32_e32 v90, v30, v25
	v_mov_b32_e32 v91, v140
	v_mov_b32_e32 v83, v141
	v_pk_add_f32 v[82:83], v[90:91], v[82:83]
	s_nop 0
	v_pk_add_f32 v[82:83], v[96:97], v[82:83]
	s_nop 0
	v_pk_add_f32 v[82:83], v[138:139], v[82:83]
	v_mul_f32_e32 v138, v4, v5
	v_mul_f32_e32 v21, 0xbfb8aa3b, v82
	v_exp_f32_e32 v90, v21
	v_mul_f32_e32 v21, 0xbfb8aa3b, v83
	v_exp_f32_e32 v91, v21
	v_mov_b32_e32 v139, v92
	v_pk_add_f32 v[90:91], v[90:91], 1.0 op_sel_hi:[1,0]
	s_nop 0
	v_rcp_f32_e32 v21, v91
	s_nop 0
	v_mul_f32_e32 v83, v83, v21
	v_mov_b32_e32 v84, v87
	v_pk_mul_f32 v[140:141], v[136:137], v[84:85]
	v_rcp_f32_e32 v21, v90
	s_nop 0
	v_mul_f32_e32 v82, v82, v21
	v_mul_f32_e32 v90, v16, v17
	v_mul_f32_e32 v96, v12, v13
	v_mov_b32_e32 v97, v140
	v_mov_b32_e32 v91, v141
	v_pk_add_f32 v[90:91], v[96:97], v[90:91]
	s_nop 0
	v_pk_add_f32 v[90:91], v[102:103], v[90:91]
	s_nop 0
	v_pk_add_f32 v[90:91], v[138:139], v[90:91]
	s_nop 0
	v_mul_f32_e32 v5, 0xbfb8aa3b, v90
	v_exp_f32_e32 v92, v5
	v_mul_f32_e32 v5, 0xbfb8aa3b, v91
	v_exp_f32_e32 v93, v5
	s_nop 0
	v_pk_add_f32 v[92:93], v[92:93], 1.0 op_sel_hi:[1,0]
	s_nop 0
	v_rcp_f32_e32 v5, v93
	s_nop 0
	v_mul_f32_e32 v91, v91, v5
	v_rcp_f32_e32 v5, v92
	s_nop 0
	v_mul_f32_e32 v90, v90, v5
	v_pk_mul_f32 v[92:93], v[18:19], v[76:77]
	s_nop 0
	v_pk_fma_f32 v[92:93], v[14:15], v[80:81], v[92:93]
	s_nop 0
	v_pk_fma_f32 v[92:93], v[10:11], v[88:89], v[92:93]
	s_nop 0
	v_pk_fma_f32 v[92:93], v[6:7], v[100:101], v[92:93]
	s_nop 0
	v_mul_f32_e32 v5, 0xbfb8aa3b, v92
	v_exp_f32_e32 v96, v5
	v_mul_f32_e32 v5, 0xbfb8aa3b, v93
	v_exp_f32_e32 v97, v5
	s_nop 0
	v_pk_add_f32 v[96:97], v[96:97], 1.0 op_sel_hi:[1,0]
	s_nop 0
	v_rcp_f32_e32 v5, v97
	s_nop 0
	v_mul_f32_e32 v93, v93, v5
	v_rcp_f32_e32 v5, v96
	s_nop 0
	v_mul_f32_e32 v92, v92, v5
	s_and_saveexec_b64 s[40:41], s[36:37]
	s_cbranch_execz .LBB0_177
	v_pk_mul_f32 v[96:97], v[78:79], v[78:79]
	v_pk_mul_f32 v[100:101], v[82:83], v[82:83]
	v_add_f32_e32 v5, v96, v97
	v_add_f32_e32 v5, v5, v100
	v_pk_mul_f32 v[102:103], v[90:91], v[90:91]
	v_add_f32_e32 v5, v5, v101
	v_and_b32_e32 v29, 64, v251
	v_add_f32_e32 v5, v5, v102
	v_add_u32_e32 v29, 64, v29
	v_pk_mul_f32 v[138:139], v[92:93], v[92:93]
	v_add_f32_e32 v5, v5, v103
	v_add_f32_e32 v5, v5, v138
	v_add_f32_e32 v5, v5, v139
	s_waitcnt lgkmcnt(0)
	s_nop 1
	v_add_f32_dpp v5, v5, v5 row_ror:8 row_mask:0xf bank_mask:0xf
	s_waitcnt lgkmcnt(0)
	s_nop 1
	v_add_f32_dpp v5, v5, v5 row_ror:4 row_mask:0xf bank_mask:0xf
	s_waitcnt lgkmcnt(0)
	s_nop 1
	v_add_f32_dpp v5, v5, v5 row_ror:2 row_mask:0xf bank_mask:0xf
	s_waitcnt lgkmcnt(0)
	s_nop 1
	v_add_f32_dpp v5, v5, v5 row_ror:1 row_mask:0xf bank_mask:0xf
	v_add_f32_e32 v5, 0x358637bd, v5
	v_mul_f32_e32 v21, 0x4b800000, v5
	v_cmp_gt_f32_e32 vcc, s2, v5
	s_nop 1
	v_cndmask_b32_e32 v5, v5, v21, vcc
	v_rsq_f32_e32 v5, v5
	s_nop 0
	v_mul_f32_e32 v21, 0x45800000, v5
	v_cndmask_b32_e32 v5, v5, v21, vcc
	v_mul_f32_e32 v96, v129, v5
	v_pk_mul_f32 v[78:79], v[78:79], v[96:97] op_sel_hi:[1,0]
	v_pk_mul_f32 v[82:83], v[82:83], v[96:97] op_sel_hi:[1,0]
	v_pk_mul_f32 v[90:91], v[90:91], v[96:97] op_sel_hi:[1,0]
	v_pk_mul_f32 v[92:93], v[92:93], v[96:97] op_sel_hi:[1,0]
; DI F8 unpack8(uint4 u) { F8 r; r.v[0] = lo16(u.x); r.v[1] = hi16(u.x); r.v[2] = lo16(u.y); r.v[3] = hi16(u.y); r.v[4] = lo16(u.z); r.v[5] = hi16(u.z); r.v[6] = lo16(u.w); r.v[7] = hi16(u.w); return r; }
; DI void stb8(bf16_t* p, const F8& f) { *(uint4*)p = pack8(f); }
; DI float gsum16(float v) { v += __shfl_xor(v, 8); v += __shfl_xor(v, 4); v += __shfl_xor(v, 2); v += __shfl_xor(v, 1); return v; }
; DI float siluf(float x) { return x / (1.f + __expf(-x)); }
; DI void odd_elem(const Params& p, int o) {
;     ...
;         for (int t = 0; t < 16; ++t) {
;             const F8 x0 = unpack8(xr[t]);
;             F8 acc; float ss = 0.f;
; #pragma unroll
;             for (int k = 0; k < 8; ++k) { const float a = w3.v[k] * x0.v[k] + w2.v[k] * h1.v[k] + w1.v[k] * h2.v[k] + w0.v[k] * h3.v[k]; acc.v[k] = siluf(a); ss += acc.v[k] * acc.v[k]; }
;             if (gi < 4) {
;                 const float rs = rsqrtf(gsum16(ss) + EPS) * nsc;
; #pragma unroll
;                 for (int k = 0; k < 8; ++k) acc.v[k] *= rs;
;             }
;             stb8(Q2 + (size_t)(r0 + t) * 3072 + c, acc);
.LBB0_177:
	s_or_b64 exec, exec, s[40:41]
	v_or_b32_e32 v5, 4, v123
	v_mad_i64_i32 v[96:97], s[40:41], v5, s33, v[110:111]
	v_cvt_pk_bf16_f32 v100, v78, v79
	v_cvt_pk_bf16_f32 v101, v82, v83
	v_cvt_pk_bf16_f32 v102, v90, v91
	v_cvt_pk_bf16_f32 v103, v92, v93
	global_store_dwordx4 v[96:97], v[100:103], off
	v_lshlrev_b32_e32 v29, 16, v72
	v_lshlrev_b32_e32 v21, 16, v73
	v_and_b32_e32 v101, 0xffff0000, v72
	v_mov_b32_e32 v100, v105
	v_pk_mul_f32 v[102:103], v[112:113], v[100:101]
	v_and_b32_e32 v91, 0xffff0000, v73
	v_lshlrev_b32_e32 v5, 16, v74
	v_and_b32_e32 v83, 0xffff0000, v74
	v_lshlrev_b32_e32 v72, 16, v75
	v_and_b32_e32 v73, 0xffff0000, v75
	v_mul_f32_e32 v74, v32, v29
	v_mul_f32_e32 v78, v28, v35
	v_pk_mul_f32 v[106:107], v[114:115], v[106:107]
	v_mov_b32_e32 v79, v102
	v_mov_b32_e32 v75, v103
	v_mul_f32_e32 v92, v24, v33
	v_pk_add_f32 v[74:75], v[78:79], v[74:75]
	v_mov_b32_e32 v93, v107
	v_mul_f32_e32 v96, v20, v31
	v_pk_add_f32 v[74:75], v[92:93], v[74:75]
	v_mov_b32_e32 v97, v106
	v_pk_add_f32 v[74:75], v[96:97], v[74:75]
	v_pk_mul_f32 v[98:99], v[118:119], v[98:99]
	v_mul_f32_e32 v31, 0xbfb8aa3b, v74
	v_exp_f32_e32 v78, v31
	v_mul_f32_e32 v31, 0xbfb8aa3b, v75
	v_exp_f32_e32 v79, v31
	v_mul_f32_e32 v96, v26, v25
	v_mov_b32_e32 v97, v99
	v_mul_f32_e32 v102, v22, v23
	v_pk_add_f32 v[78:79], v[78:79], 1.0 op_sel_hi:[1,0]
	v_mov_b32_e32 v103, v98
	v_pk_mul_f32 v[86:87], v[108:109], v[86:87]
	v_mul_f32_e32 v98, v8, v13
	v_mov_b32_e32 v99, v87
	v_rcp_f32_e32 v31, v79
	s_nop 0
	v_mul_f32_e32 v75, v75, v31
	v_mov_b32_e32 v90, v95
	v_pk_mul_f32 v[106:107], v[116:117], v[90:91]
	v_rcp_f32_e32 v31, v78
	s_nop 0
	v_mul_f32_e32 v74, v74, v31
	v_mul_f32_e32 v78, v34, v21
	v_mul_f32_e32 v92, v30, v27
	v_mov_b32_e32 v93, v106
	v_mov_b32_e32 v79, v107
	v_pk_add_f32 v[78:79], v[92:93], v[78:79]
	s_nop 0
	v_pk_add_f32 v[78:79], v[96:97], v[78:79]
	s_nop 0
	v_pk_add_f32 v[78:79], v[102:103], v[78:79]
	v_mul_f32_e32 v102, v4, v9
	v_mul_f32_e32 v23, 0xbfb8aa3b, v78
	v_exp_f32_e32 v92, v23
	v_mul_f32_e32 v23, 0xbfb8aa3b, v79
	v_exp_f32_e32 v93, v23
	v_mov_b32_e32 v103, v86
	v_pk_add_f32 v[92:93], v[92:93], 1.0 op_sel_hi:[1,0]
	s_nop 0
	v_rcp_f32_e32 v23, v93
	s_nop 0
	v_mul_f32_e32 v79, v79, v23
	v_mov_b32_e32 v82, v85
	v_pk_mul_f32 v[106:107], v[136:137], v[82:83]
	v_rcp_f32_e32 v23, v92
	s_nop 0
	v_mul_f32_e32 v78, v78, v23
	v_mul_f32_e32 v92, v16, v5
	v_mul_f32_e32 v96, v12, v17
	v_mov_b32_e32 v97, v106
	v_mov_b32_e32 v93, v107
	v_pk_add_f32 v[92:93], v[96:97], v[92:93]
	s_nop 0
	v_pk_add_f32 v[92:93], v[98:99], v[92:93]
	s_nop 0
	v_pk_add_f32 v[86:87], v[102:103], v[92:93]
	s_nop 0
	v_mul_f32_e32 v9, 0xbfb8aa3b, v86
	v_exp_f32_e32 v92, v9
	v_mul_f32_e32 v9, 0xbfb8aa3b, v87
	v_exp_f32_e32 v93, v9
	s_nop 0
	v_pk_add_f32 v[92:93], v[92:93], 1.0 op_sel_hi:[1,0]
	s_nop 0
	v_rcp_f32_e32 v9, v93
	s_nop 0
	v_mul_f32_e32 v87, v87, v9
	v_rcp_f32_e32 v9, v92
	s_nop 0
	v_mul_f32_e32 v86, v86, v9
	v_pk_mul_f32 v[92:93], v[18:19], v[72:73]
	s_nop 0
	v_pk_fma_f32 v[92:93], v[14:15], v[76:77], v[92:93]
	s_nop 0
	v_pk_fma_f32 v[92:93], v[10:11], v[80:81], v[92:93]
	s_nop 0
	v_pk_fma_f32 v[88:89], v[6:7], v[88:89], v[92:93]
	s_nop 0
	v_mul_f32_e32 v9, 0xbfb8aa3b, v88
	v_exp_f32_e32 v92, v9
	v_mul_f32_e32 v9, 0xbfb8aa3b, v89
	v_exp_f32_e32 v93, v9
	s_nop 0
	v_pk_add_f32 v[92:93], v[92:93], 1.0 op_sel_hi:[1,0]
	s_nop 0
	v_rcp_f32_e32 v9, v93
	s_nop 0
	v_mul_f32_e32 v89, v89, v9
	v_rcp_f32_e32 v9, v92
	s_nop 0
	v_mul_f32_e32 v88, v88, v9
	s_and_saveexec_b64 s[40:41], s[36:37]
	s_cbranch_execz .LBB0_179
	v_pk_mul_f32 v[92:93], v[74:75], v[74:75]
	v_pk_mul_f32 v[96:97], v[78:79], v[78:79]
	v_add_f32_e32 v9, v92, v93
	v_add_f32_e32 v9, v9, v96
	v_pk_mul_f32 v[98:99], v[86:87], v[86:87]
	v_add_f32_e32 v9, v9, v97
	v_and_b32_e32 v31, 64, v251
	v_add_f32_e32 v9, v9, v98
	v_add_u32_e32 v31, 64, v31
	v_pk_mul_f32 v[102:103], v[88:89], v[88:89]
	v_add_f32_e32 v9, v9, v99
	v_add_f32_e32 v9, v9, v102
	v_add_f32_e32 v9, v9, v103
	s_waitcnt lgkmcnt(0)
	s_nop 1
	v_add_f32_dpp v9, v9, v9 row_ror:8 row_mask:0xf bank_mask:0xf
	s_waitcnt lgkmcnt(0)
	s_nop 1
	v_add_f32_dpp v9, v9, v9 row_ror:4 row_mask:0xf bank_mask:0xf
	s_waitcnt lgkmcnt(0)
	s_nop 1
	v_add_f32_dpp v9, v9, v9 row_ror:2 row_mask:0xf bank_mask:0xf
	s_waitcnt lgkmcnt(0)
	s_nop 1
	v_add_f32_dpp v9, v9, v9 row_ror:1 row_mask:0xf bank_mask:0xf
	v_add_f32_e32 v9, 0x358637bd, v9
	v_mul_f32_e32 v23, 0x4b800000, v9
	v_cmp_gt_f32_e32 vcc, s2, v9
	s_nop 1
	v_cndmask_b32_e32 v9, v9, v23, vcc
	v_rsq_f32_e32 v9, v9
	s_nop 0
	v_mul_f32_e32 v23, 0x45800000, v9
	v_cndmask_b32_e32 v9, v9, v23, vcc
	v_mul_f32_e32 v92, v129, v9
	v_pk_mul_f32 v[74:75], v[74:75], v[92:93] op_sel_hi:[1,0]
	v_pk_mul_f32 v[78:79], v[78:79], v[92:93] op_sel_hi:[1,0]
	v_pk_mul_f32 v[86:87], v[86:87], v[92:93] op_sel_hi:[1,0]
	v_pk_mul_f32 v[88:89], v[88:89], v[92:93] op_sel_hi:[1,0]
; DI F8 unpack8(uint4 u) { F8 r; r.v[0] = lo16(u.x); r.v[1] = hi16(u.x); r.v[2] = lo16(u.y); r.v[3] = hi16(u.y); r.v[4] = lo16(u.z); r.v[5] = hi16(u.z); r.v[6] = lo16(u.w); r.v[7] = hi16(u.w); return r; }
; DI void stb8(bf16_t* p, const F8& f) { *(uint4*)p = pack8(f); }
; DI float gsum16(float v) { v += __shfl_xor(v, 8); v += __shfl_xor(v, 4); v += __shfl_xor(v, 2); v += __shfl_xor(v, 1); return v; }
; DI float siluf(float x) { return x / (1.f + __expf(-x)); }
; DI void odd_elem(const Params& p, int o) {
;     ...
;         for (int t = 0; t < 16; ++t) {
;             const F8 x0 = unpack8(xr[t]);
;             F8 acc; float ss = 0.f;
; #pragma unroll
;             for (int k = 0; k < 8; ++k) { const float a = w3.v[k] * x0.v[k] + w2.v[k] * h1.v[k] + w1.v[k] * h2.v[k] + w0.v[k] * h3.v[k]; acc.v[k] = siluf(a); ss += acc.v[k] * acc.v[k]; }
;             if (gi < 4) {
;                 const float rs = rsqrtf(gsum16(ss) + EPS) * nsc;
; #pragma unroll
;                 for (int k = 0; k < 8; ++k) acc.v[k] *= rs;
;             }
;             stb8(Q2 + (size_t)(r0 + t) * 3072 + c, acc);
.LBB0_179:
	s_or_b64 exec, exec, s[40:41]
	v_or_b32_e32 v9, 5, v123
	v_mad_i64_i32 v[92:93], s[40:41], v9, s33, v[110:111]
	v_cvt_pk_bf16_f32 v96, v74, v75
	v_cvt_pk_bf16_f32 v97, v78, v79
	v_cvt_pk_bf16_f32 v98, v86, v87
	v_cvt_pk_bf16_f32 v99, v88, v89
	global_store_dwordx4 v[92:93], v[96:99], off
	v_lshlrev_b32_e32 v31, 16, v68
	v_lshlrev_b32_e32 v23, 16, v69
	v_and_b32_e32 v97, 0xffff0000, v68
	v_mov_b32_e32 v96, v101
	v_pk_mul_f32 v[98:99], v[112:113], v[96:97]
	v_and_b32_e32 v87, 0xffff0000, v69
	v_lshlrev_b32_e32 v9, 16, v70
	v_and_b32_e32 v79, 0xffff0000, v70
	v_lshlrev_b32_e32 v68, 16, v71
	v_and_b32_e32 v69, 0xffff0000, v71
	v_mul_f32_e32 v70, v32, v31
	v_mul_f32_e32 v74, v28, v29
	v_pk_mul_f32 v[102:103], v[114:115], v[104:105]
	v_mov_b32_e32 v75, v98
	v_mov_b32_e32 v71, v99
	v_mul_f32_e32 v88, v24, v35
	v_pk_add_f32 v[70:71], v[74:75], v[70:71]
	v_mov_b32_e32 v89, v103
	v_mul_f32_e32 v92, v20, v33
	v_pk_add_f32 v[70:71], v[88:89], v[70:71]
	v_mov_b32_e32 v93, v102
	v_pk_add_f32 v[70:71], v[92:93], v[70:71]
	v_pk_mul_f32 v[94:95], v[118:119], v[94:95]
	v_mul_f32_e32 v33, 0xbfb8aa3b, v70
	v_exp_f32_e32 v74, v33
	v_mul_f32_e32 v33, 0xbfb8aa3b, v71
	v_exp_f32_e32 v75, v33
	v_mul_f32_e32 v92, v26, v27
	v_mov_b32_e32 v93, v95
	v_mul_f32_e32 v98, v22, v25
	v_pk_add_f32 v[74:75], v[74:75], 1.0 op_sel_hi:[1,0]
	v_mov_b32_e32 v99, v94
	v_pk_mul_f32 v[84:85], v[108:109], v[84:85]
	v_mul_f32_e32 v94, v8, v17
	v_mov_b32_e32 v95, v85
	v_rcp_f32_e32 v33, v75
	s_nop 0
	v_mul_f32_e32 v71, v71, v33
	v_mov_b32_e32 v86, v91
	v_pk_mul_f32 v[102:103], v[116:117], v[86:87]
	v_rcp_f32_e32 v33, v74
	s_nop 0
	v_mul_f32_e32 v70, v70, v33
	v_mul_f32_e32 v74, v34, v23
	v_mul_f32_e32 v88, v30, v21
	v_mov_b32_e32 v89, v102
	v_mov_b32_e32 v75, v103
	v_pk_add_f32 v[74:75], v[88:89], v[74:75]
	s_nop 0
	v_pk_add_f32 v[74:75], v[92:93], v[74:75]
	s_nop 0
	v_pk_add_f32 v[74:75], v[98:99], v[74:75]
	v_mul_f32_e32 v98, v4, v13
	v_mul_f32_e32 v25, 0xbfb8aa3b, v74
	v_exp_f32_e32 v88, v25
	v_mul_f32_e32 v25, 0xbfb8aa3b, v75
	v_exp_f32_e32 v89, v25
	v_mov_b32_e32 v99, v84
	v_pk_add_f32 v[88:89], v[88:89], 1.0 op_sel_hi:[1,0]
	s_nop 0
	v_rcp_f32_e32 v25, v89
	s_nop 0
	v_mul_f32_e32 v75, v75, v25
	v_mov_b32_e32 v78, v83
	v_pk_mul_f32 v[102:103], v[136:137], v[78:79]
	v_rcp_f32_e32 v25, v88
	s_nop 0
	v_mul_f32_e32 v74, v74, v25
	v_mul_f32_e32 v88, v16, v9
	v_mul_f32_e32 v92, v12, v5
	v_mov_b32_e32 v93, v102
	v_mov_b32_e32 v89, v103
	v_pk_add_f32 v[88:89], v[92:93], v[88:89]
	s_nop 0
	v_pk_add_f32 v[88:89], v[94:95], v[88:89]
	s_nop 0
	v_pk_add_f32 v[84:85], v[98:99], v[88:89]
	s_nop 0
	v_mul_f32_e32 v13, 0xbfb8aa3b, v84
	v_exp_f32_e32 v88, v13
	v_mul_f32_e32 v13, 0xbfb8aa3b, v85
	v_exp_f32_e32 v89, v13
	s_nop 0
	v_pk_add_f32 v[88:89], v[88:89], 1.0 op_sel_hi:[1,0]
	s_nop 0
	v_rcp_f32_e32 v13, v89
	s_nop 0
	v_mul_f32_e32 v85, v85, v13
	v_rcp_f32_e32 v13, v88
	s_nop 0
	v_mul_f32_e32 v84, v84, v13
	v_pk_mul_f32 v[88:89], v[18:19], v[68:69]
	s_nop 0
	v_pk_fma_f32 v[88:89], v[14:15], v[72:73], v[88:89]
	s_nop 0
	v_pk_fma_f32 v[88:89], v[10:11], v[76:77], v[88:89]
	s_nop 0
	v_pk_fma_f32 v[80:81], v[6:7], v[80:81], v[88:89]
	s_nop 0
	v_mul_f32_e32 v13, 0xbfb8aa3b, v80
	v_exp_f32_e32 v88, v13
	v_mul_f32_e32 v13, 0xbfb8aa3b, v81
	v_exp_f32_e32 v89, v13
	s_nop 0
	v_pk_add_f32 v[88:89], v[88:89], 1.0 op_sel_hi:[1,0]
	s_nop 0
	v_rcp_f32_e32 v13, v89
	s_nop 0
	v_mul_f32_e32 v81, v81, v13
	v_rcp_f32_e32 v13, v88
	s_nop 0
	v_mul_f32_e32 v80, v80, v13
	s_and_saveexec_b64 s[40:41], s[36:37]
	s_cbranch_execz .LBB0_181
	v_pk_mul_f32 v[88:89], v[70:71], v[70:71]
	v_pk_mul_f32 v[92:93], v[74:75], v[74:75]
	v_add_f32_e32 v13, v88, v89
	v_add_f32_e32 v13, v13, v92
	v_pk_mul_f32 v[94:95], v[84:85], v[84:85]
	v_add_f32_e32 v13, v13, v93
	v_and_b32_e32 v33, 64, v251
	v_add_f32_e32 v13, v13, v94
	v_add_u32_e32 v33, 64, v33
	v_pk_mul_f32 v[98:99], v[80:81], v[80:81]
	v_add_f32_e32 v13, v13, v95
	v_add_f32_e32 v13, v13, v98
	v_add_f32_e32 v13, v13, v99
	s_waitcnt lgkmcnt(0)
	s_nop 1
	v_add_f32_dpp v13, v13, v13 row_ror:8 row_mask:0xf bank_mask:0xf
	s_waitcnt lgkmcnt(0)
	s_nop 1
	v_add_f32_dpp v13, v13, v13 row_ror:4 row_mask:0xf bank_mask:0xf
	s_waitcnt lgkmcnt(0)
	s_nop 1
	v_add_f32_dpp v13, v13, v13 row_ror:2 row_mask:0xf bank_mask:0xf
	s_waitcnt lgkmcnt(0)
	s_nop 1
	v_add_f32_dpp v13, v13, v13 row_ror:1 row_mask:0xf bank_mask:0xf
	v_add_f32_e32 v13, 0x358637bd, v13
	v_mul_f32_e32 v25, 0x4b800000, v13
	v_cmp_gt_f32_e32 vcc, s2, v13
	s_nop 1
	v_cndmask_b32_e32 v13, v13, v25, vcc
	v_rsq_f32_e32 v13, v13
	s_nop 0
	v_mul_f32_e32 v25, 0x45800000, v13
	v_cndmask_b32_e32 v13, v13, v25, vcc
	v_mul_f32_e32 v88, v129, v13
	v_pk_mul_f32 v[70:71], v[70:71], v[88:89] op_sel_hi:[1,0]
	v_pk_mul_f32 v[74:75], v[74:75], v[88:89] op_sel_hi:[1,0]
	v_pk_mul_f32 v[84:85], v[84:85], v[88:89] op_sel_hi:[1,0]
	v_pk_mul_f32 v[80:81], v[80:81], v[88:89] op_sel_hi:[1,0]
; DI F8 unpack8(uint4 u) { F8 r; r.v[0] = lo16(u.x); r.v[1] = hi16(u.x); r.v[2] = lo16(u.y); r.v[3] = hi16(u.y); r.v[4] = lo16(u.z); r.v[5] = hi16(u.z); r.v[6] = lo16(u.w); r.v[7] = hi16(u.w); return r; }
; DI void stb8(bf16_t* p, const F8& f) { *(uint4*)p = pack8(f); }
; DI float gsum16(float v) { v += __shfl_xor(v, 8); v += __shfl_xor(v, 4); v += __shfl_xor(v, 2); v += __shfl_xor(v, 1); return v; }
; DI float siluf(float x) { return x / (1.f + __expf(-x)); }
; DI void odd_elem(const Params& p, int o) {
;     ...
;         for (int t = 0; t < 16; ++t) {
;             const F8 x0 = unpack8(xr[t]);
;             F8 acc; float ss = 0.f;
; #pragma unroll
;             for (int k = 0; k < 8; ++k) { const float a = w3.v[k] * x0.v[k] + w2.v[k] * h1.v[k] + w1.v[k] * h2.v[k] + w0.v[k] * h3.v[k]; acc.v[k] = siluf(a); ss += acc.v[k] * acc.v[k]; }
;             if (gi < 4) {
;                 const float rs = rsqrtf(gsum16(ss) + EPS) * nsc;
; #pragma unroll
;                 for (int k = 0; k < 8; ++k) acc.v[k] *= rs;
;             }
;             stb8(Q2 + (size_t)(r0 + t) * 3072 + c, acc);
.LBB0_181:
	s_or_b64 exec, exec, s[40:41]
	v_or_b32_e32 v13, 6, v123
	v_mad_i64_i32 v[88:89], s[40:41], v13, s33, v[110:111]
	v_cvt_pk_bf16_f32 v92, v70, v71
	v_cvt_pk_bf16_f32 v93, v74, v75
	v_cvt_pk_bf16_f32 v94, v84, v85
	v_cvt_pk_bf16_f32 v95, v80, v81
	global_store_dwordx4 v[88:89], v[92:95], off
	v_lshlrev_b32_e32 v33, 16, v64
	v_lshlrev_b32_e32 v25, 16, v65
	v_and_b32_e32 v93, 0xffff0000, v64
	v_mov_b32_e32 v92, v97
	v_pk_mul_f32 v[94:95], v[112:113], v[92:93]
	v_and_b32_e32 v85, 0xffff0000, v65
	v_lshlrev_b32_e32 v13, 16, v66
	v_and_b32_e32 v75, 0xffff0000, v66
	v_lshlrev_b32_e32 v64, 16, v67
	v_and_b32_e32 v65, 0xffff0000, v67
	v_mul_f32_e32 v66, v32, v33
	v_mul_f32_e32 v70, v28, v31
	v_pk_mul_f32 v[98:99], v[114:115], v[100:101]
	v_mov_b32_e32 v71, v94
	v_mov_b32_e32 v67, v95
	v_mul_f32_e32 v80, v24, v29
	v_pk_add_f32 v[66:67], v[70:71], v[66:67]
	v_mov_b32_e32 v81, v99
	v_mul_f32_e32 v88, v20, v35
	v_pk_add_f32 v[66:67], v[80:81], v[66:67]
	v_mov_b32_e32 v89, v98
	v_pk_add_f32 v[66:67], v[88:89], v[66:67]
	v_pk_mul_f32 v[90:91], v[118:119], v[90:91]
	v_mul_f32_e32 v35, 0xbfb8aa3b, v66
	v_exp_f32_e32 v70, v35
	v_mul_f32_e32 v35, 0xbfb8aa3b, v67
	v_exp_f32_e32 v71, v35
	v_mul_f32_e32 v88, v26, v21
	v_mov_b32_e32 v89, v91
	v_mul_f32_e32 v94, v22, v27
	v_pk_add_f32 v[70:71], v[70:71], 1.0 op_sel_hi:[1,0]
	v_mov_b32_e32 v95, v90
	v_pk_mul_f32 v[82:83], v[108:109], v[82:83]
	v_mul_f32_e32 v90, v8, v5
	v_mov_b32_e32 v91, v83
	v_rcp_f32_e32 v35, v71
	s_nop 0
	v_mul_f32_e32 v67, v67, v35
	v_mov_b32_e32 v84, v87
	v_pk_mul_f32 v[98:99], v[116:117], v[84:85]
	v_rcp_f32_e32 v35, v70
	s_nop 0
	v_mul_f32_e32 v66, v66, v35
	v_mul_f32_e32 v70, v34, v25
	v_mul_f32_e32 v80, v30, v23
	v_mov_b32_e32 v81, v98
	v_mov_b32_e32 v71, v99
	v_pk_add_f32 v[70:71], v[80:81], v[70:71]
	s_nop 0
	v_pk_add_f32 v[70:71], v[88:89], v[70:71]
	s_nop 0
	v_pk_add_f32 v[70:71], v[94:95], v[70:71]
	v_mul_f32_e32 v94, v4, v17
	v_mul_f32_e32 v27, 0xbfb8aa3b, v70
	v_exp_f32_e32 v80, v27
	v_mul_f32_e32 v27, 0xbfb8aa3b, v71
	v_exp_f32_e32 v81, v27
	v_mov_b32_e32 v95, v82
	v_pk_add_f32 v[80:81], v[80:81], 1.0 op_sel_hi:[1,0]
	s_nop 0
	v_rcp_f32_e32 v27, v81
	s_nop 0
	v_mul_f32_e32 v71, v71, v27
	v_mov_b32_e32 v74, v79
	v_pk_mul_f32 v[98:99], v[136:137], v[74:75]
	v_rcp_f32_e32 v27, v80
	s_nop 0
	v_mul_f32_e32 v70, v70, v27
	v_mul_f32_e32 v80, v16, v13
	v_mul_f32_e32 v88, v12, v9
	v_mov_b32_e32 v89, v98
	v_mov_b32_e32 v81, v99
	v_pk_add_f32 v[80:81], v[88:89], v[80:81]
	s_nop 0
	v_pk_add_f32 v[80:81], v[90:91], v[80:81]
	s_nop 0
	v_pk_add_f32 v[80:81], v[94:95], v[80:81]
	s_nop 0
	v_mul_f32_e32 v17, 0xbfb8aa3b, v80
	v_exp_f32_e32 v82, v17
	v_mul_f32_e32 v17, 0xbfb8aa3b, v81
	v_exp_f32_e32 v83, v17
	s_nop 0
	v_pk_add_f32 v[82:83], v[82:83], 1.0 op_sel_hi:[1,0]
	s_nop 0
	v_rcp_f32_e32 v17, v83
	s_nop 0
	v_mul_f32_e32 v81, v81, v17
	v_rcp_f32_e32 v17, v82
	s_nop 0
	v_mul_f32_e32 v80, v80, v17
	v_pk_mul_f32 v[82:83], v[18:19], v[64:65]
	s_nop 0
	v_pk_fma_f32 v[82:83], v[14:15], v[68:69], v[82:83]
	s_nop 0
	v_pk_fma_f32 v[82:83], v[10:11], v[72:73], v[82:83]
	s_nop 0
	v_pk_fma_f32 v[76:77], v[6:7], v[76:77], v[82:83]
	s_nop 0
	v_mul_f32_e32 v17, 0xbfb8aa3b, v76
	v_exp_f32_e32 v82, v17
	v_mul_f32_e32 v17, 0xbfb8aa3b, v77
	v_exp_f32_e32 v83, v17
	s_nop 0
	v_pk_add_f32 v[82:83], v[82:83], 1.0 op_sel_hi:[1,0]
	s_nop 0
	v_rcp_f32_e32 v17, v83
	s_nop 0
	v_mul_f32_e32 v77, v77, v17
	v_rcp_f32_e32 v17, v82
	s_nop 0
	v_mul_f32_e32 v76, v76, v17
	s_and_saveexec_b64 s[40:41], s[36:37]
	s_cbranch_execz .LBB0_183
	v_pk_mul_f32 v[82:83], v[66:67], v[66:67]
	v_pk_mul_f32 v[88:89], v[70:71], v[70:71]
	v_add_f32_e32 v17, v82, v83
	v_add_f32_e32 v17, v17, v88
	v_pk_mul_f32 v[90:91], v[80:81], v[80:81]
	v_add_f32_e32 v17, v17, v89
	v_and_b32_e32 v35, 64, v251
	v_add_f32_e32 v17, v17, v90
	v_add_u32_e32 v35, 64, v35
	v_pk_mul_f32 v[94:95], v[76:77], v[76:77]
	v_add_f32_e32 v17, v17, v91
	v_add_f32_e32 v17, v17, v94
	v_add_f32_e32 v17, v17, v95
	s_waitcnt lgkmcnt(0)
	s_nop 1
	v_add_f32_dpp v17, v17, v17 row_ror:8 row_mask:0xf bank_mask:0xf
	s_waitcnt lgkmcnt(0)
	s_nop 1
	v_add_f32_dpp v17, v17, v17 row_ror:4 row_mask:0xf bank_mask:0xf
	s_waitcnt lgkmcnt(0)
	s_nop 1
	v_add_f32_dpp v17, v17, v17 row_ror:2 row_mask:0xf bank_mask:0xf
	s_waitcnt lgkmcnt(0)
	s_nop 1
	v_add_f32_dpp v17, v17, v17 row_ror:1 row_mask:0xf bank_mask:0xf
	v_add_f32_e32 v17, 0x358637bd, v17
	v_mul_f32_e32 v27, 0x4b800000, v17
	v_cmp_gt_f32_e32 vcc, s2, v17
	s_nop 1
	v_cndmask_b32_e32 v17, v17, v27, vcc
	v_rsq_f32_e32 v17, v17
	s_nop 0
	v_mul_f32_e32 v27, 0x45800000, v17
	v_cndmask_b32_e32 v17, v17, v27, vcc
	v_mul_f32_e32 v82, v129, v17
	v_pk_mul_f32 v[66:67], v[66:67], v[82:83] op_sel_hi:[1,0]
	v_pk_mul_f32 v[70:71], v[70:71], v[82:83] op_sel_hi:[1,0]
	v_pk_mul_f32 v[80:81], v[80:81], v[82:83] op_sel_hi:[1,0]
	v_pk_mul_f32 v[76:77], v[76:77], v[82:83] op_sel_hi:[1,0]
; DI F8 unpack8(uint4 u) { F8 r; r.v[0] = lo16(u.x); r.v[1] = hi16(u.x); r.v[2] = lo16(u.y); r.v[3] = hi16(u.y); r.v[4] = lo16(u.z); r.v[5] = hi16(u.z); r.v[6] = lo16(u.w); r.v[7] = hi16(u.w); return r; }
; DI void stb8(bf16_t* p, const F8& f) { *(uint4*)p = pack8(f); }
; DI float gsum16(float v) { v += __shfl_xor(v, 8); v += __shfl_xor(v, 4); v += __shfl_xor(v, 2); v += __shfl_xor(v, 1); return v; }
; DI float siluf(float x) { return x / (1.f + __expf(-x)); }
; DI void odd_elem(const Params& p, int o) {
;     ...
;         for (int t = 0; t < 16; ++t) {
;             const F8 x0 = unpack8(xr[t]);
;             F8 acc; float ss = 0.f;
; #pragma unroll
;             for (int k = 0; k < 8; ++k) { const float a = w3.v[k] * x0.v[k] + w2.v[k] * h1.v[k] + w1.v[k] * h2.v[k] + w0.v[k] * h3.v[k]; acc.v[k] = siluf(a); ss += acc.v[k] * acc.v[k]; }
;             if (gi < 4) {
;                 const float rs = rsqrtf(gsum16(ss) + EPS) * nsc;
; #pragma unroll
;                 for (int k = 0; k < 8; ++k) acc.v[k] *= rs;
;             }
;             stb8(Q2 + (size_t)(r0 + t) * 3072 + c, acc);
.LBB0_183:
	s_or_b64 exec, exec, s[40:41]
	v_or_b32_e32 v17, 7, v123
	v_mad_i64_i32 v[82:83], s[40:41], v17, s33, v[110:111]
	v_cvt_pk_bf16_f32 v88, v66, v67
	v_cvt_pk_bf16_f32 v89, v70, v71
	v_cvt_pk_bf16_f32 v90, v80, v81
	v_cvt_pk_bf16_f32 v91, v76, v77
	global_store_dwordx4 v[82:83], v[88:91], off
	v_lshlrev_b32_e32 v35, 16, v60
	v_lshlrev_b32_e32 v27, 16, v61
	v_and_b32_e32 v89, 0xffff0000, v60
	v_mov_b32_e32 v88, v93
	v_pk_mul_f32 v[90:91], v[112:113], v[88:89]
	v_and_b32_e32 v81, 0xffff0000, v61
	v_lshlrev_b32_e32 v17, 16, v62
	v_and_b32_e32 v71, 0xffff0000, v62
	v_lshlrev_b32_e32 v60, 16, v63
	v_and_b32_e32 v61, 0xffff0000, v63
	v_mul_f32_e32 v62, v32, v35
	v_mul_f32_e32 v66, v28, v33
	v_pk_mul_f32 v[94:95], v[114:115], v[96:97]
	v_mov_b32_e32 v67, v90
	v_mov_b32_e32 v63, v91
	v_mul_f32_e32 v76, v24, v31
	v_pk_add_f32 v[62:63], v[66:67], v[62:63]
	v_mov_b32_e32 v77, v95
	v_mul_f32_e32 v82, v20, v29
	v_pk_add_f32 v[62:63], v[76:77], v[62:63]
	v_mov_b32_e32 v83, v94
	v_pk_add_f32 v[62:63], v[82:83], v[62:63]
	v_pk_mul_f32 v[86:87], v[118:119], v[86:87]
	v_mul_f32_e32 v29, 0xbfb8aa3b, v62
	v_exp_f32_e32 v66, v29
	v_mul_f32_e32 v29, 0xbfb8aa3b, v63
	v_exp_f32_e32 v67, v29
	v_mul_f32_e32 v82, v26, v23
	v_mov_b32_e32 v83, v87
	v_mul_f32_e32 v90, v22, v21
	v_pk_add_f32 v[66:67], v[66:67], 1.0 op_sel_hi:[1,0]
	v_mov_b32_e32 v91, v86
	v_pk_mul_f32 v[78:79], v[108:109], v[78:79]
	v_mul_f32_e32 v86, v8, v9
	v_mov_b32_e32 v87, v79
	v_rcp_f32_e32 v29, v67
	s_nop 0
	v_mul_f32_e32 v63, v63, v29
	v_mov_b32_e32 v80, v85
	v_pk_mul_f32 v[94:95], v[116:117], v[80:81]
	v_rcp_f32_e32 v29, v66
	s_nop 0
	v_mul_f32_e32 v62, v62, v29
	v_mul_f32_e32 v66, v34, v27
	v_mul_f32_e32 v76, v30, v25
	v_mov_b32_e32 v77, v94
	v_mov_b32_e32 v67, v95
	v_pk_add_f32 v[66:67], v[76:77], v[66:67]
	s_nop 0
	v_pk_add_f32 v[66:67], v[82:83], v[66:67]
	s_nop 0
	v_pk_add_f32 v[66:67], v[90:91], v[66:67]
	v_mul_f32_e32 v90, v4, v5
	v_mul_f32_e32 v21, 0xbfb8aa3b, v66
	v_exp_f32_e32 v76, v21
	v_mul_f32_e32 v21, 0xbfb8aa3b, v67
	v_exp_f32_e32 v77, v21
	v_mov_b32_e32 v91, v78
	v_pk_add_f32 v[76:77], v[76:77], 1.0 op_sel_hi:[1,0]
	s_nop 0
	v_rcp_f32_e32 v21, v77
	s_nop 0
	v_mul_f32_e32 v67, v67, v21
	v_mov_b32_e32 v70, v75
	v_pk_mul_f32 v[94:95], v[136:137], v[70:71]
	v_rcp_f32_e32 v21, v76
	s_nop 0
	v_mul_f32_e32 v66, v66, v21
	v_mul_f32_e32 v76, v16, v17
	v_mul_f32_e32 v82, v12, v13
	v_mov_b32_e32 v83, v94
	v_mov_b32_e32 v77, v95
	v_pk_add_f32 v[76:77], v[82:83], v[76:77]
	s_nop 0
	v_pk_add_f32 v[76:77], v[86:87], v[76:77]
	s_nop 0
	v_pk_add_f32 v[76:77], v[90:91], v[76:77]
	s_nop 0
	v_mul_f32_e32 v5, 0xbfb8aa3b, v76
	v_exp_f32_e32 v78, v5
	v_mul_f32_e32 v5, 0xbfb8aa3b, v77
	v_exp_f32_e32 v79, v5
	s_nop 0
	v_pk_add_f32 v[78:79], v[78:79], 1.0 op_sel_hi:[1,0]
	s_nop 0
	v_rcp_f32_e32 v5, v79
	s_nop 0
	v_mul_f32_e32 v77, v77, v5
	v_rcp_f32_e32 v5, v78
	s_nop 0
	v_mul_f32_e32 v76, v76, v5
	v_pk_mul_f32 v[78:79], v[18:19], v[60:61]
	s_nop 0
	v_pk_fma_f32 v[78:79], v[14:15], v[64:65], v[78:79]
	s_nop 0
	v_pk_fma_f32 v[78:79], v[10:11], v[68:69], v[78:79]
	s_nop 0
	v_pk_fma_f32 v[72:73], v[6:7], v[72:73], v[78:79]
	s_nop 0
	v_mul_f32_e32 v5, 0xbfb8aa3b, v72
	v_exp_f32_e32 v78, v5
	v_mul_f32_e32 v5, 0xbfb8aa3b, v73
	v_exp_f32_e32 v79, v5
	s_nop 0
	v_pk_add_f32 v[78:79], v[78:79], 1.0 op_sel_hi:[1,0]
	s_nop 0
	v_rcp_f32_e32 v5, v79
	s_nop 0
	v_mul_f32_e32 v73, v73, v5
	v_rcp_f32_e32 v5, v78
	s_nop 0
	v_mul_f32_e32 v72, v72, v5
	s_and_saveexec_b64 s[40:41], s[36:37]
	s_cbranch_execz .LBB0_185
	v_pk_mul_f32 v[78:79], v[62:63], v[62:63]
	v_pk_mul_f32 v[82:83], v[66:67], v[66:67]
	v_add_f32_e32 v5, v78, v79
	v_add_f32_e32 v5, v5, v82
	v_pk_mul_f32 v[86:87], v[76:77], v[76:77]
	v_add_f32_e32 v5, v5, v83
	v_and_b32_e32 v29, 64, v251
	v_add_f32_e32 v5, v5, v86
	v_add_u32_e32 v29, 64, v29
	v_pk_mul_f32 v[90:91], v[72:73], v[72:73]
	v_add_f32_e32 v5, v5, v87
	v_add_f32_e32 v5, v5, v90
	v_add_f32_e32 v5, v5, v91
	s_waitcnt lgkmcnt(0)
	s_nop 1
	v_add_f32_dpp v5, v5, v5 row_ror:8 row_mask:0xf bank_mask:0xf
	s_waitcnt lgkmcnt(0)
	s_nop 1
	v_add_f32_dpp v5, v5, v5 row_ror:4 row_mask:0xf bank_mask:0xf
	s_waitcnt lgkmcnt(0)
	s_nop 1
	v_add_f32_dpp v5, v5, v5 row_ror:2 row_mask:0xf bank_mask:0xf
	s_waitcnt lgkmcnt(0)
	s_nop 1
	v_add_f32_dpp v5, v5, v5 row_ror:1 row_mask:0xf bank_mask:0xf
	v_add_f32_e32 v5, 0x358637bd, v5
	v_mul_f32_e32 v21, 0x4b800000, v5
	v_cmp_gt_f32_e32 vcc, s2, v5
	s_nop 1
	v_cndmask_b32_e32 v5, v5, v21, vcc
	v_rsq_f32_e32 v5, v5
	s_nop 0
	v_mul_f32_e32 v21, 0x45800000, v5
	v_cndmask_b32_e32 v5, v5, v21, vcc
	v_mul_f32_e32 v78, v129, v5
	v_pk_mul_f32 v[62:63], v[62:63], v[78:79] op_sel_hi:[1,0]
	v_pk_mul_f32 v[66:67], v[66:67], v[78:79] op_sel_hi:[1,0]
	v_pk_mul_f32 v[76:77], v[76:77], v[78:79] op_sel_hi:[1,0]
	v_pk_mul_f32 v[72:73], v[72:73], v[78:79] op_sel_hi:[1,0]
; DI F8 unpack8(uint4 u) { F8 r; r.v[0] = lo16(u.x); r.v[1] = hi16(u.x); r.v[2] = lo16(u.y); r.v[3] = hi16(u.y); r.v[4] = lo16(u.z); r.v[5] = hi16(u.z); r.v[6] = lo16(u.w); r.v[7] = hi16(u.w); return r; }
; DI void stb8(bf16_t* p, const F8& f) { *(uint4*)p = pack8(f); }
; DI float gsum16(float v) { v += __shfl_xor(v, 8); v += __shfl_xor(v, 4); v += __shfl_xor(v, 2); v += __shfl_xor(v, 1); return v; }
; DI float siluf(float x) { return x / (1.f + __expf(-x)); }
; DI void odd_elem(const Params& p, int o) {
;     ...
;         for (int t = 0; t < 16; ++t) {
;             const F8 x0 = unpack8(xr[t]);
;             F8 acc; float ss = 0.f;
; #pragma unroll
;             for (int k = 0; k < 8; ++k) { const float a = w3.v[k] * x0.v[k] + w2.v[k] * h1.v[k] + w1.v[k] * h2.v[k] + w0.v[k] * h3.v[k]; acc.v[k] = siluf(a); ss += acc.v[k] * acc.v[k]; }
;             if (gi < 4) {
;                 const float rs = rsqrtf(gsum16(ss) + EPS) * nsc;
; #pragma unroll
;                 for (int k = 0; k < 8; ++k) acc.v[k] *= rs;
;             }
;             stb8(Q2 + (size_t)(r0 + t) * 3072 + c, acc);
.LBB0_185:
	s_or_b64 exec, exec, s[40:41]
	v_and_b32_e32 v83, 0xffff0000, v56
	v_mov_b32_e32 v82, v89
	v_lshlrev_b32_e32 v86, 16, v56
	v_pk_mul_f32 v[90:91], v[112:113], v[82:83]
	v_or_b32_e32 v5, 8, v123
	v_cvt_pk_bf16_f32 v94, v62, v63
	v_cvt_pk_bf16_f32 v95, v66, v67
	v_cvt_pk_bf16_f32 v96, v76, v77
	v_lshlrev_b32_e32 v29, 16, v57
	v_and_b32_e32 v77, 0xffff0000, v57
	v_lshlrev_b32_e32 v21, 16, v58
	v_and_b32_e32 v67, 0xffff0000, v58
	v_lshlrev_b32_e32 v56, 16, v59
	v_and_b32_e32 v57, 0xffff0000, v59
	v_mul_f32_e32 v58, v32, v86
	v_mul_f32_e32 v62, v28, v35
	v_pk_mul_f32 v[92:93], v[114:115], v[92:93]
	v_mov_b32_e32 v63, v90
	v_mov_b32_e32 v59, v91
	v_mad_i64_i32 v[78:79], s[40:41], v5, s33, v[110:111]
	v_cvt_pk_bf16_f32 v97, v72, v73
	v_mul_f32_e32 v72, v24, v33
	v_pk_add_f32 v[58:59], v[62:63], v[58:59]
	v_mov_b32_e32 v73, v93
	global_store_dwordx4 v[78:79], v[94:97], off
	v_mul_f32_e32 v78, v20, v31
	v_pk_add_f32 v[58:59], v[72:73], v[58:59]
	v_mov_b32_e32 v79, v92
	v_pk_add_f32 v[58:59], v[78:79], v[58:59]
	v_mov_b32_e32 v76, v81
	v_mul_f32_e32 v5, 0xbfb8aa3b, v58
	v_exp_f32_e32 v62, v5
	v_mul_f32_e32 v5, 0xbfb8aa3b, v59
	v_exp_f32_e32 v63, v5
	v_pk_mul_f32 v[92:93], v[116:117], v[76:77]
	v_pk_mul_f32 v[84:85], v[118:119], v[84:85]
	v_mul_f32_e32 v78, v26, v25
	v_pk_add_f32 v[62:63], v[62:63], 1.0 op_sel_hi:[1,0]
	v_mov_b32_e32 v79, v85
	v_mul_f32_e32 v90, v22, v23
	v_mov_b32_e32 v91, v84
	v_pk_mul_f32 v[74:75], v[108:109], v[74:75]
	v_rcp_f32_e32 v5, v63
	s_nop 0
	v_mul_f32_e32 v59, v59, v5
	v_mov_b32_e32 v73, v92
	v_mul_f32_e32 v84, v8, v13
	v_mov_b32_e32 v85, v75
	v_rcp_f32_e32 v5, v62
	s_nop 0
	v_mul_f32_e32 v58, v58, v5
	v_mul_f32_e32 v62, v34, v29
	v_mul_f32_e32 v72, v30, v27
	v_mov_b32_e32 v63, v93
	v_pk_add_f32 v[62:63], v[72:73], v[62:63]
	s_nop 0
	v_pk_add_f32 v[62:63], v[78:79], v[62:63]
	s_nop 0
	v_pk_add_f32 v[62:63], v[90:91], v[62:63]
	v_mul_f32_e32 v90, v4, v9
	v_mul_f32_e32 v5, 0xbfb8aa3b, v62
	v_exp_f32_e32 v72, v5
	v_mul_f32_e32 v5, 0xbfb8aa3b, v63
	v_exp_f32_e32 v73, v5
	v_mov_b32_e32 v91, v74
	v_pk_add_f32 v[72:73], v[72:73], 1.0 op_sel_hi:[1,0]
	s_nop 0
	v_rcp_f32_e32 v5, v73
	s_nop 0
	v_mul_f32_e32 v63, v63, v5
	v_mul_f32_e32 v78, v12, v17
	v_mov_b32_e32 v66, v71
	v_pk_mul_f32 v[92:93], v[136:137], v[66:67]
	v_rcp_f32_e32 v5, v72
	s_nop 0
	v_mul_f32_e32 v62, v62, v5
	v_mul_f32_e32 v72, v16, v21
	v_mov_b32_e32 v79, v92
	v_mov_b32_e32 v73, v93
	v_pk_add_f32 v[72:73], v[78:79], v[72:73]
	s_nop 0
	v_pk_add_f32 v[72:73], v[84:85], v[72:73]
	s_nop 0
	v_pk_add_f32 v[72:73], v[90:91], v[72:73]
	s_nop 0
	v_mul_f32_e32 v5, 0xbfb8aa3b, v72
	v_exp_f32_e32 v74, v5
	v_mul_f32_e32 v5, 0xbfb8aa3b, v73
	v_exp_f32_e32 v75, v5
	s_nop 0
	v_pk_add_f32 v[74:75], v[74:75], 1.0 op_sel_hi:[1,0]
	s_nop 0
	v_rcp_f32_e32 v5, v75
	s_nop 0
	v_mul_f32_e32 v73, v73, v5
	v_rcp_f32_e32 v5, v74
	s_nop 0
	v_mul_f32_e32 v72, v72, v5
	v_pk_mul_f32 v[74:75], v[18:19], v[56:57]
	s_nop 0
	v_pk_fma_f32 v[74:75], v[14:15], v[60:61], v[74:75]
	s_nop 0
	v_pk_fma_f32 v[74:75], v[10:11], v[64:65], v[74:75]
	s_nop 0
	v_pk_fma_f32 v[68:69], v[6:7], v[68:69], v[74:75]
	s_nop 0
	v_mul_f32_e32 v5, 0xbfb8aa3b, v68
	v_exp_f32_e32 v74, v5
	v_mul_f32_e32 v5, 0xbfb8aa3b, v69
	v_exp_f32_e32 v75, v5
	s_nop 0
	v_pk_add_f32 v[74:75], v[74:75], 1.0 op_sel_hi:[1,0]
	s_nop 0
	v_rcp_f32_e32 v5, v75
	s_nop 0
	v_mul_f32_e32 v69, v69, v5
	v_rcp_f32_e32 v5, v74
	s_nop 0
	v_mul_f32_e32 v68, v68, v5
	s_and_saveexec_b64 s[40:41], s[36:37]
	s_cbranch_execz .LBB0_187
	v_pk_mul_f32 v[74:75], v[58:59], v[58:59]
	v_pk_mul_f32 v[78:79], v[62:63], v[62:63]
	v_add_f32_e32 v5, v74, v75
	v_add_f32_e32 v5, v5, v78
	v_pk_mul_f32 v[84:85], v[72:73], v[72:73]
	v_add_f32_e32 v5, v5, v79
	v_and_b32_e32 v23, 64, v251
	v_add_f32_e32 v5, v5, v84
	v_add_u32_e32 v23, 64, v23
	v_pk_mul_f32 v[90:91], v[68:69], v[68:69]
	v_add_f32_e32 v5, v5, v85
	v_add_f32_e32 v5, v5, v90
	v_add_f32_e32 v5, v5, v91
	s_waitcnt lgkmcnt(0)
	s_nop 1
	v_add_f32_dpp v5, v5, v5 row_ror:8 row_mask:0xf bank_mask:0xf
	s_waitcnt lgkmcnt(0)
	s_nop 1
	v_add_f32_dpp v5, v5, v5 row_ror:4 row_mask:0xf bank_mask:0xf
	s_waitcnt lgkmcnt(0)
	s_nop 1
	v_add_f32_dpp v5, v5, v5 row_ror:2 row_mask:0xf bank_mask:0xf
	s_waitcnt lgkmcnt(0)
	s_nop 1
	v_add_f32_dpp v5, v5, v5 row_ror:1 row_mask:0xf bank_mask:0xf
	v_add_f32_e32 v5, 0x358637bd, v5
	v_mul_f32_e32 v9, 0x4b800000, v5
	v_cmp_gt_f32_e32 vcc, s2, v5
	s_nop 1
	v_cndmask_b32_e32 v5, v5, v9, vcc
	v_rsq_f32_e32 v5, v5
	s_nop 0
	v_mul_f32_e32 v9, 0x45800000, v5
	v_cndmask_b32_e32 v5, v5, v9, vcc
	v_mul_f32_e32 v74, v129, v5
	v_pk_mul_f32 v[58:59], v[58:59], v[74:75] op_sel_hi:[1,0]
	v_pk_mul_f32 v[62:63], v[62:63], v[74:75] op_sel_hi:[1,0]
	v_pk_mul_f32 v[72:73], v[72:73], v[74:75] op_sel_hi:[1,0]
	v_pk_mul_f32 v[68:69], v[68:69], v[74:75] op_sel_hi:[1,0]
; DI F8 unpack8(uint4 u) { F8 r; r.v[0] = lo16(u.x); r.v[1] = hi16(u.x); r.v[2] = lo16(u.y); r.v[3] = hi16(u.y); r.v[4] = lo16(u.z); r.v[5] = hi16(u.z); r.v[6] = lo16(u.w); r.v[7] = hi16(u.w); return r; }
; DI void stb8(bf16_t* p, const F8& f) { *(uint4*)p = pack8(f); }
; DI float gsum16(float v) { v += __shfl_xor(v, 8); v += __shfl_xor(v, 4); v += __shfl_xor(v, 2); v += __shfl_xor(v, 1); return v; }
; DI float siluf(float x) { return x / (1.f + __expf(-x)); }
; DI void odd_elem(const Params& p, int o) {
;     ...
;         for (int t = 0; t < 16; ++t) {
;             const F8 x0 = unpack8(xr[t]);
;             F8 acc; float ss = 0.f;
; #pragma unroll
;             for (int k = 0; k < 8; ++k) { const float a = w3.v[k] * x0.v[k] + w2.v[k] * h1.v[k] + w1.v[k] * h2.v[k] + w0.v[k] * h3.v[k]; acc.v[k] = siluf(a); ss += acc.v[k] * acc.v[k]; }
;             if (gi < 4) {
;                 const float rs = rsqrtf(gsum16(ss) + EPS) * nsc;
; #pragma unroll
;                 for (int k = 0; k < 8; ++k) acc.v[k] *= rs;
;             }
;             stb8(Q2 + (size_t)(r0 + t) * 3072 + c, acc);
.LBB0_187:
	s_or_b64 exec, exec, s[40:41]
	v_or_b32_e32 v5, 9, v123
	v_mad_i64_i32 v[74:75], s[40:41], v5, s33, v[110:111]
	v_cvt_pk_bf16_f32 v90, v58, v59
	v_cvt_pk_bf16_f32 v91, v62, v63
	v_cvt_pk_bf16_f32 v92, v72, v73
	v_cvt_pk_bf16_f32 v93, v68, v69
	v_and_b32_e32 v79, 0xffff0000, v52
	v_mov_b32_e32 v78, v83
	global_store_dwordx4 v[74:75], v[90:93], off
	v_lshlrev_b32_e32 v84, 16, v52
	v_lshlrev_b32_e32 v31, 16, v53
	v_pk_mul_f32 v[90:91], v[112:113], v[78:79]
	v_and_b32_e32 v73, 0xffff0000, v53
	v_mul_f32_e32 v52, v32, v84
	v_mul_f32_e32 v58, v28, v86
	v_pk_mul_f32 v[88:89], v[114:115], v[88:89]
	v_mov_b32_e32 v59, v90
	v_mov_b32_e32 v53, v91
	v_mul_f32_e32 v68, v24, v35
	v_pk_add_f32 v[52:53], v[58:59], v[52:53]
	v_mov_b32_e32 v69, v89
	v_mul_f32_e32 v74, v20, v33
	v_pk_add_f32 v[52:53], v[68:69], v[52:53]
	v_mov_b32_e32 v75, v88
	v_pk_add_f32 v[52:53], v[74:75], v[52:53]
	v_mov_b32_e32 v72, v77
	v_mul_f32_e32 v5, 0xbfb8aa3b, v52
	v_exp_f32_e32 v58, v5
	v_mul_f32_e32 v5, 0xbfb8aa3b, v53
	v_exp_f32_e32 v59, v5
	v_pk_mul_f32 v[90:91], v[116:117], v[72:73]
	v_pk_mul_f32 v[80:81], v[118:119], v[80:81]
	v_mov_b32_e32 v69, v90
	v_pk_add_f32 v[58:59], v[58:59], 1.0 op_sel_hi:[1,0]
	v_mul_f32_e32 v74, v26, v27
	v_mov_b32_e32 v75, v81
	v_mul_f32_e32 v88, v22, v25
	v_mov_b32_e32 v89, v80
	v_rcp_f32_e32 v5, v59
	s_nop 0
	v_mul_f32_e32 v53, v53, v5
	v_mul_f32_e32 v68, v30, v29
	v_and_b32_e32 v63, 0xffff0000, v54
	v_lshlrev_b32_e32 v23, 16, v54
	v_rcp_f32_e32 v5, v58
	s_nop 0
	v_mul_f32_e32 v52, v52, v5
	v_mul_f32_e32 v58, v34, v31
	v_mov_b32_e32 v59, v91
	v_pk_add_f32 v[58:59], v[68:69], v[58:59]
	v_pk_mul_f32 v[70:71], v[108:109], v[70:71]
	v_pk_add_f32 v[58:59], v[74:75], v[58:59]
	v_mul_f32_e32 v74, v12, v21
	v_pk_add_f32 v[58:59], v[88:89], v[58:59]
	v_mul_f32_e32 v80, v8, v17
	v_mul_f32_e32 v5, 0xbfb8aa3b, v58
	v_exp_f32_e32 v68, v5
	v_mul_f32_e32 v5, 0xbfb8aa3b, v59
	v_exp_f32_e32 v69, v5
	v_mov_b32_e32 v81, v71
	v_mul_f32_e32 v88, v4, v13
	v_mov_b32_e32 v89, v70
	v_pk_add_f32 v[68:69], v[68:69], 1.0 op_sel_hi:[1,0]
	v_lshlrev_b32_e32 v54, 16, v55
	v_and_b32_e32 v55, 0xffff0000, v55
	v_rcp_f32_e32 v5, v69
	s_nop 0
	v_mul_f32_e32 v59, v59, v5
	v_mov_b32_e32 v62, v67
	v_pk_mul_f32 v[90:91], v[136:137], v[62:63]
	v_rcp_f32_e32 v5, v68
	s_nop 0
	v_mul_f32_e32 v58, v58, v5
	v_mul_f32_e32 v68, v16, v23
	v_mov_b32_e32 v75, v90
	v_mov_b32_e32 v69, v91
	v_pk_add_f32 v[68:69], v[74:75], v[68:69]
	s_nop 0
	v_pk_add_f32 v[68:69], v[80:81], v[68:69]
	s_nop 0
	v_pk_add_f32 v[68:69], v[88:89], v[68:69]
	s_nop 0
	v_mul_f32_e32 v5, 0xbfb8aa3b, v68
	v_exp_f32_e32 v70, v5
	v_mul_f32_e32 v5, 0xbfb8aa3b, v69
	v_exp_f32_e32 v71, v5
	s_nop 0
	v_pk_add_f32 v[70:71], v[70:71], 1.0 op_sel_hi:[1,0]
	s_nop 0
	v_rcp_f32_e32 v5, v71
	s_nop 0
	v_mul_f32_e32 v69, v69, v5
	v_rcp_f32_e32 v5, v70
	s_nop 0
	v_mul_f32_e32 v68, v68, v5
	v_pk_mul_f32 v[70:71], v[18:19], v[54:55]
	s_nop 0
	v_pk_fma_f32 v[70:71], v[14:15], v[56:57], v[70:71]
	s_nop 0
	v_pk_fma_f32 v[70:71], v[10:11], v[60:61], v[70:71]
	s_nop 0
	v_pk_fma_f32 v[64:65], v[6:7], v[64:65], v[70:71]
	s_nop 0
	v_mul_f32_e32 v5, 0xbfb8aa3b, v64
	v_exp_f32_e32 v70, v5
	v_mul_f32_e32 v5, 0xbfb8aa3b, v65
	v_exp_f32_e32 v71, v5
	s_nop 0
	v_pk_add_f32 v[70:71], v[70:71], 1.0 op_sel_hi:[1,0]
	s_nop 0
	v_rcp_f32_e32 v5, v71
	s_nop 0
	v_mul_f32_e32 v65, v65, v5
	v_rcp_f32_e32 v5, v70
	s_nop 0
	v_mul_f32_e32 v64, v64, v5
	s_and_saveexec_b64 s[40:41], s[36:37]
	s_cbranch_execz .LBB0_189
	v_pk_mul_f32 v[70:71], v[52:53], v[52:53]
	v_pk_mul_f32 v[74:75], v[58:59], v[58:59]
	v_add_f32_e32 v5, v70, v71
	v_add_f32_e32 v5, v5, v74
	v_pk_mul_f32 v[80:81], v[68:69], v[68:69]
	v_add_f32_e32 v5, v5, v75
	v_and_b32_e32 v13, 64, v251
	v_add_f32_e32 v5, v5, v80
	v_add_u32_e32 v13, 64, v13
	v_pk_mul_f32 v[88:89], v[64:65], v[64:65]
	v_add_f32_e32 v5, v5, v81
	v_add_f32_e32 v5, v5, v88
	v_add_f32_e32 v5, v5, v89
	s_waitcnt lgkmcnt(0)
	s_nop 1
	v_add_f32_dpp v5, v5, v5 row_ror:8 row_mask:0xf bank_mask:0xf
	s_waitcnt lgkmcnt(0)
	s_nop 1
	v_add_f32_dpp v5, v5, v5 row_ror:4 row_mask:0xf bank_mask:0xf
	s_waitcnt lgkmcnt(0)
	s_nop 1
	v_add_f32_dpp v5, v5, v5 row_ror:2 row_mask:0xf bank_mask:0xf
	s_waitcnt lgkmcnt(0)
	s_nop 1
	v_add_f32_dpp v5, v5, v5 row_ror:1 row_mask:0xf bank_mask:0xf
	v_add_f32_e32 v5, 0x358637bd, v5
	v_mul_f32_e32 v9, 0x4b800000, v5
	v_cmp_gt_f32_e32 vcc, s2, v5
	s_nop 1
	v_cndmask_b32_e32 v5, v5, v9, vcc
	v_rsq_f32_e32 v5, v5
	s_nop 0
	v_mul_f32_e32 v9, 0x45800000, v5
	v_cndmask_b32_e32 v5, v5, v9, vcc
	v_mul_f32_e32 v70, v129, v5
	v_pk_mul_f32 v[52:53], v[52:53], v[70:71] op_sel_hi:[1,0]
	v_pk_mul_f32 v[58:59], v[58:59], v[70:71] op_sel_hi:[1,0]
	v_pk_mul_f32 v[68:69], v[68:69], v[70:71] op_sel_hi:[1,0]
	v_pk_mul_f32 v[64:65], v[64:65], v[70:71] op_sel_hi:[1,0]
; DI F8 unpack8(uint4 u) { F8 r; r.v[0] = lo16(u.x); r.v[1] = hi16(u.x); r.v[2] = lo16(u.y); r.v[3] = hi16(u.y); r.v[4] = lo16(u.z); r.v[5] = hi16(u.z); r.v[6] = lo16(u.w); r.v[7] = hi16(u.w); return r; }
; DI void stb8(bf16_t* p, const F8& f) { *(uint4*)p = pack8(f); }
; DI float gsum16(float v) { v += __shfl_xor(v, 8); v += __shfl_xor(v, 4); v += __shfl_xor(v, 2); v += __shfl_xor(v, 1); return v; }
; DI float siluf(float x) { return x / (1.f + __expf(-x)); }
; DI void odd_elem(const Params& p, int o) {
;     ...
;         for (int t = 0; t < 16; ++t) {
;             const F8 x0 = unpack8(xr[t]);
;             F8 acc; float ss = 0.f;
; #pragma unroll
;             for (int k = 0; k < 8; ++k) { const float a = w3.v[k] * x0.v[k] + w2.v[k] * h1.v[k] + w1.v[k] * h2.v[k] + w0.v[k] * h3.v[k]; acc.v[k] = siluf(a); ss += acc.v[k] * acc.v[k]; }
;             if (gi < 4) {
;                 const float rs = rsqrtf(gsum16(ss) + EPS) * nsc;
; #pragma unroll
;                 for (int k = 0; k < 8; ++k) acc.v[k] *= rs;
;             }
;             stb8(Q2 + (size_t)(r0 + t) * 3072 + c, acc);
.LBB0_189:
	s_or_b64 exec, exec, s[40:41]
	v_and_b32_e32 v75, 0xffff0000, v48
	v_mov_b32_e32 v74, v79
	v_or_b32_e32 v5, 10, v123
	v_lshlrev_b32_e32 v33, 16, v48
	v_pk_mul_f32 v[80:81], v[112:113], v[74:75]
	v_mad_i64_i32 v[70:71], s[40:41], v5, s33, v[110:111]
	v_cvt_pk_bf16_f32 v88, v52, v53
	v_cvt_pk_bf16_f32 v89, v58, v59
	v_cvt_pk_bf16_f32 v90, v68, v69
	v_lshlrev_b32_e32 v25, 16, v49
	v_and_b32_e32 v69, 0xffff0000, v49
	v_lshlrev_b32_e32 v5, 16, v50
	v_and_b32_e32 v49, 0xffff0000, v50
	v_lshlrev_b32_e32 v52, 16, v51
	v_and_b32_e32 v53, 0xffff0000, v51
	v_mul_f32_e32 v50, v32, v33
	v_mul_f32_e32 v58, v28, v84
	v_pk_mul_f32 v[82:83], v[114:115], v[82:83]
	v_mov_b32_e32 v59, v80
	v_mov_b32_e32 v51, v81
	v_cvt_pk_bf16_f32 v91, v64, v65
	v_mul_f32_e32 v64, v24, v86
	v_pk_add_f32 v[50:51], v[58:59], v[50:51]
	v_mov_b32_e32 v65, v83
	global_store_dwordx4 v[70:71], v[88:91], off
	v_mul_f32_e32 v70, v20, v35
	v_pk_add_f32 v[50:51], v[64:65], v[50:51]
	v_mov_b32_e32 v71, v82
	v_pk_add_f32 v[50:51], v[70:71], v[50:51]
	v_mov_b32_e32 v68, v73
	v_mul_f32_e32 v9, 0xbfb8aa3b, v50
	v_exp_f32_e32 v58, v9
	v_mul_f32_e32 v9, 0xbfb8aa3b, v51
	v_exp_f32_e32 v59, v9
	v_pk_mul_f32 v[82:83], v[116:117], v[68:69]
	v_pk_mul_f32 v[76:77], v[118:119], v[76:77]
	v_mov_b32_e32 v65, v82
	v_pk_add_f32 v[58:59], v[58:59], 1.0 op_sel_hi:[1,0]
	v_mul_f32_e32 v70, v26, v29
	v_mov_b32_e32 v71, v77
	v_mul_f32_e32 v80, v22, v27
	v_mov_b32_e32 v81, v76
	v_rcp_f32_e32 v9, v59
	s_nop 0
	v_mul_f32_e32 v51, v51, v9
	v_mul_f32_e32 v64, v30, v31
	v_pk_mul_f32 v[66:67], v[108:109], v[66:67]
	v_mul_f32_e32 v76, v8, v21
	v_rcp_f32_e32 v9, v58
	s_nop 0
	v_mul_f32_e32 v50, v50, v9
	v_mul_f32_e32 v58, v34, v25
	v_mov_b32_e32 v59, v83
	v_pk_add_f32 v[58:59], v[64:65], v[58:59]
	v_mov_b32_e32 v77, v67
	v_pk_add_f32 v[58:59], v[70:71], v[58:59]
	v_mul_f32_e32 v70, v12, v23
	v_pk_add_f32 v[58:59], v[80:81], v[58:59]
	v_mul_f32_e32 v80, v4, v17
	v_mul_f32_e32 v9, 0xbfb8aa3b, v58
	v_exp_f32_e32 v64, v9
	v_mul_f32_e32 v9, 0xbfb8aa3b, v59
	v_exp_f32_e32 v65, v9
	v_mov_b32_e32 v81, v66
	v_pk_add_f32 v[64:65], v[64:65], 1.0 op_sel_hi:[1,0]
	s_nop 0
	v_rcp_f32_e32 v9, v65
	s_nop 0
	v_mul_f32_e32 v59, v59, v9
	v_mov_b32_e32 v48, v63
	v_pk_mul_f32 v[82:83], v[136:137], v[48:49]
	v_rcp_f32_e32 v9, v64
	s_nop 0
	v_mul_f32_e32 v58, v58, v9
	v_mul_f32_e32 v64, v16, v5
	v_mov_b32_e32 v71, v82
	v_mov_b32_e32 v65, v83
	v_pk_add_f32 v[64:65], v[70:71], v[64:65]
	s_nop 0
	v_pk_add_f32 v[64:65], v[76:77], v[64:65]
	s_nop 0
	v_pk_add_f32 v[64:65], v[80:81], v[64:65]
	s_nop 0
	v_mul_f32_e32 v9, 0xbfb8aa3b, v64
	v_exp_f32_e32 v66, v9
	v_mul_f32_e32 v9, 0xbfb8aa3b, v65
	v_exp_f32_e32 v67, v9
	s_nop 0
	v_pk_add_f32 v[66:67], v[66:67], 1.0 op_sel_hi:[1,0]
	s_nop 0
	v_rcp_f32_e32 v9, v67
	s_nop 0
	v_mul_f32_e32 v65, v65, v9
	v_rcp_f32_e32 v9, v66
	s_nop 0
	v_mul_f32_e32 v64, v64, v9
	v_pk_mul_f32 v[66:67], v[18:19], v[52:53]
	s_nop 0
	v_pk_fma_f32 v[66:67], v[14:15], v[54:55], v[66:67]
	s_nop 0
	v_pk_fma_f32 v[66:67], v[10:11], v[56:57], v[66:67]
	s_nop 0
	v_pk_fma_f32 v[60:61], v[6:7], v[60:61], v[66:67]
	s_nop 0
	v_mul_f32_e32 v9, 0xbfb8aa3b, v60
	v_exp_f32_e32 v66, v9
	v_mul_f32_e32 v9, 0xbfb8aa3b, v61
	v_exp_f32_e32 v67, v9
	s_nop 0
	v_pk_add_f32 v[66:67], v[66:67], 1.0 op_sel_hi:[1,0]
	s_nop 0
	v_rcp_f32_e32 v9, v67
	s_nop 0
	v_mul_f32_e32 v61, v61, v9
	v_rcp_f32_e32 v9, v66
	s_nop 0
	v_mul_f32_e32 v60, v60, v9
	s_and_saveexec_b64 s[40:41], s[36:37]
	s_cbranch_execz .LBB0_191
	v_pk_mul_f32 v[66:67], v[50:51], v[50:51]
	v_pk_mul_f32 v[70:71], v[58:59], v[58:59]
	v_add_f32_e32 v9, v66, v67
	v_add_f32_e32 v9, v9, v70
	v_pk_mul_f32 v[76:77], v[64:65], v[64:65]
	v_add_f32_e32 v9, v9, v71
	v_and_b32_e32 v17, 64, v251
	v_add_f32_e32 v9, v9, v76
	v_add_u32_e32 v17, 64, v17
	v_pk_mul_f32 v[80:81], v[60:61], v[60:61]
	v_add_f32_e32 v9, v9, v77
	v_add_f32_e32 v9, v9, v80
	v_add_f32_e32 v9, v9, v81
	s_waitcnt lgkmcnt(0)
	s_nop 1
	v_add_f32_dpp v9, v9, v9 row_ror:8 row_mask:0xf bank_mask:0xf
	s_waitcnt lgkmcnt(0)
	s_nop 1
	v_add_f32_dpp v9, v9, v9 row_ror:4 row_mask:0xf bank_mask:0xf
	s_waitcnt lgkmcnt(0)
	s_nop 1
	v_add_f32_dpp v9, v9, v9 row_ror:2 row_mask:0xf bank_mask:0xf
	s_waitcnt lgkmcnt(0)
	s_nop 1
	v_add_f32_dpp v9, v9, v9 row_ror:1 row_mask:0xf bank_mask:0xf
	v_add_f32_e32 v9, 0x358637bd, v9
	v_mul_f32_e32 v13, 0x4b800000, v9
	v_cmp_gt_f32_e32 vcc, s2, v9
	s_nop 1
	v_cndmask_b32_e32 v9, v9, v13, vcc
	v_rsq_f32_e32 v9, v9
	s_nop 0
	v_mul_f32_e32 v13, 0x45800000, v9
	v_cndmask_b32_e32 v9, v9, v13, vcc
	v_mul_f32_e32 v66, v129, v9
	v_pk_mul_f32 v[50:51], v[50:51], v[66:67] op_sel_hi:[1,0]
	v_pk_mul_f32 v[58:59], v[58:59], v[66:67] op_sel_hi:[1,0]
	v_pk_mul_f32 v[64:65], v[64:65], v[66:67] op_sel_hi:[1,0]
	v_pk_mul_f32 v[60:61], v[60:61], v[66:67] op_sel_hi:[1,0]
; DI F8 unpack8(uint4 u) { F8 r; r.v[0] = lo16(u.x); r.v[1] = hi16(u.x); r.v[2] = lo16(u.y); r.v[3] = hi16(u.y); r.v[4] = lo16(u.z); r.v[5] = hi16(u.z); r.v[6] = lo16(u.w); r.v[7] = hi16(u.w); return r; }
; DI void stb8(bf16_t* p, const F8& f) { *(uint4*)p = pack8(f); }
; DI float gsum16(float v) { v += __shfl_xor(v, 8); v += __shfl_xor(v, 4); v += __shfl_xor(v, 2); v += __shfl_xor(v, 1); return v; }
; DI float siluf(float x) { return x / (1.f + __expf(-x)); }
; DI void odd_elem(const Params& p, int o) {
;     ...
;         for (int t = 0; t < 16; ++t) {
;             const F8 x0 = unpack8(xr[t]);
;             F8 acc; float ss = 0.f;
; #pragma unroll
;             for (int k = 0; k < 8; ++k) { const float a = w3.v[k] * x0.v[k] + w2.v[k] * h1.v[k] + w1.v[k] * h2.v[k] + w0.v[k] * h3.v[k]; acc.v[k] = siluf(a); ss += acc.v[k] * acc.v[k]; }
;             if (gi < 4) {
;                 const float rs = rsqrtf(gsum16(ss) + EPS) * nsc;
; #pragma unroll
;                 for (int k = 0; k < 8; ++k) acc.v[k] *= rs;
;             }
;             stb8(Q2 + (size_t)(r0 + t) * 3072 + c, acc);
.LBB0_191:
	s_or_b64 exec, exec, s[40:41]
	v_or_b32_e32 v9, 11, v123
	v_and_b32_e32 v71, 0xffff0000, v44
	v_mov_b32_e32 v70, v75
	v_mad_i64_i32 v[66:67], s[40:41], v9, s33, v[110:111]
	v_cvt_pk_bf16_f32 v80, v50, v51
	v_cvt_pk_bf16_f32 v81, v58, v59
	v_cvt_pk_bf16_f32 v82, v64, v65
	v_cvt_pk_bf16_f32 v83, v60, v61
	v_lshlrev_b32_e32 v17, 16, v44
	v_pk_mul_f32 v[76:77], v[112:113], v[70:71]
	global_store_dwordx4 v[66:67], v[80:83], off
	v_lshlrev_b32_e32 v13, 16, v45
	v_and_b32_e32 v67, 0xffff0000, v45
	v_lshlrev_b32_e32 v9, 16, v46
	v_and_b32_e32 v59, 0xffff0000, v46
	v_lshlrev_b32_e32 v60, 16, v47
	v_and_b32_e32 v61, 0xffff0000, v47
	v_mul_f32_e32 v44, v32, v17
	v_mul_f32_e32 v46, v28, v33
	v_pk_mul_f32 v[78:79], v[114:115], v[78:79]
	v_mov_b32_e32 v47, v76
	v_mov_b32_e32 v45, v77
	v_mul_f32_e32 v50, v24, v84
	v_pk_add_f32 v[44:45], v[46:47], v[44:45]
	v_mov_b32_e32 v51, v79
	v_mul_f32_e32 v64, v20, v86
	v_pk_add_f32 v[44:45], v[50:51], v[44:45]
	v_mov_b32_e32 v65, v78
	v_pk_add_f32 v[44:45], v[64:65], v[44:45]
	v_mov_b32_e32 v66, v69
	v_mul_f32_e32 v27, 0xbfb8aa3b, v44
	v_exp_f32_e32 v46, v27
	v_mul_f32_e32 v27, 0xbfb8aa3b, v45
	v_exp_f32_e32 v47, v27
	v_pk_mul_f32 v[78:79], v[116:117], v[66:67]
	v_pk_mul_f32 v[72:73], v[118:119], v[72:73]
	v_mul_f32_e32 v64, v26, v31
	v_pk_add_f32 v[46:47], v[46:47], 1.0 op_sel_hi:[1,0]
	v_mov_b32_e32 v65, v73
	v_mul_f32_e32 v76, v22, v29
	v_mov_b32_e32 v77, v72
	v_pk_mul_f32 v[62:63], v[108:109], v[62:63]
	v_rcp_f32_e32 v27, v47
	s_nop 0
	v_mul_f32_e32 v45, v45, v27
	v_mul_f32_e32 v72, v8, v23
	v_mov_b32_e32 v73, v63
	v_rcp_f32_e32 v27, v46
	s_nop 0
	v_mul_f32_e32 v44, v44, v27
	v_mul_f32_e32 v46, v34, v13
	v_mul_f32_e32 v50, v30, v25
	v_mov_b32_e32 v51, v78
	v_mov_b32_e32 v47, v79
	v_pk_add_f32 v[46:47], v[50:51], v[46:47]
	s_nop 0
	v_pk_add_f32 v[46:47], v[64:65], v[46:47]
	s_nop 0
	v_pk_add_f32 v[46:47], v[76:77], v[46:47]
	v_mul_f32_e32 v76, v4, v21
	v_mul_f32_e32 v27, 0xbfb8aa3b, v46
	v_exp_f32_e32 v50, v27
	v_mul_f32_e32 v27, 0xbfb8aa3b, v47
	v_exp_f32_e32 v51, v27
	v_mov_b32_e32 v77, v62
	v_pk_add_f32 v[50:51], v[50:51], 1.0 op_sel_hi:[1,0]
	s_nop 0
	v_rcp_f32_e32 v27, v51
	s_nop 0
	v_mul_f32_e32 v47, v47, v27
	v_mul_f32_e32 v64, v12, v5
	v_mov_b32_e32 v58, v49
	v_pk_mul_f32 v[78:79], v[136:137], v[58:59]
	v_rcp_f32_e32 v27, v50
	s_nop 0
	v_mul_f32_e32 v46, v46, v27
	v_mul_f32_e32 v50, v16, v9
	v_mov_b32_e32 v65, v78
	v_mov_b32_e32 v51, v79
	v_pk_add_f32 v[50:51], v[64:65], v[50:51]
	s_nop 0
	v_pk_add_f32 v[50:51], v[72:73], v[50:51]
	s_nop 0
	v_pk_add_f32 v[50:51], v[76:77], v[50:51]
	s_nop 0
	v_mul_f32_e32 v21, 0xbfb8aa3b, v50
	v_exp_f32_e32 v62, v21
	v_mul_f32_e32 v21, 0xbfb8aa3b, v51
	v_exp_f32_e32 v63, v21
	s_nop 0
	v_pk_add_f32 v[62:63], v[62:63], 1.0 op_sel_hi:[1,0]
	s_nop 0
	v_rcp_f32_e32 v21, v63
	s_nop 0
	v_mul_f32_e32 v51, v51, v21
	v_rcp_f32_e32 v21, v62
	s_nop 0
	v_mul_f32_e32 v50, v50, v21
	v_pk_mul_f32 v[62:63], v[18:19], v[60:61]
	s_nop 0
	v_pk_fma_f32 v[62:63], v[14:15], v[52:53], v[62:63]
	s_nop 0
	v_pk_fma_f32 v[62:63], v[10:11], v[54:55], v[62:63]
	s_nop 0
	v_pk_fma_f32 v[56:57], v[6:7], v[56:57], v[62:63]
	s_nop 0
	v_mul_f32_e32 v21, 0xbfb8aa3b, v56
	v_exp_f32_e32 v62, v21
	v_mul_f32_e32 v21, 0xbfb8aa3b, v57
	v_exp_f32_e32 v63, v21
	s_nop 0
	v_pk_add_f32 v[62:63], v[62:63], 1.0 op_sel_hi:[1,0]
	s_nop 0
	v_rcp_f32_e32 v21, v63
	s_nop 0
	v_mul_f32_e32 v57, v57, v21
	v_rcp_f32_e32 v21, v62
	s_nop 0
	v_mul_f32_e32 v56, v56, v21
	s_and_saveexec_b64 s[40:41], s[36:37]
	s_cbranch_execz .LBB0_193
	v_pk_mul_f32 v[62:63], v[44:45], v[44:45]
	v_pk_mul_f32 v[64:65], v[46:47], v[46:47]
	v_add_f32_e32 v21, v62, v63
	v_add_f32_e32 v21, v21, v64
	v_pk_mul_f32 v[72:73], v[50:51], v[50:51]
	v_add_f32_e32 v21, v21, v65
	v_and_b32_e32 v29, 64, v251
	v_add_f32_e32 v21, v21, v72
	v_add_u32_e32 v29, 64, v29
	v_pk_mul_f32 v[76:77], v[56:57], v[56:57]
	v_add_f32_e32 v21, v21, v73
	v_add_f32_e32 v21, v21, v76
	v_add_f32_e32 v21, v21, v77
	s_waitcnt lgkmcnt(0)
	s_nop 1
	v_add_f32_dpp v21, v21, v21 row_ror:8 row_mask:0xf bank_mask:0xf
	s_waitcnt lgkmcnt(0)
	s_nop 1
	v_add_f32_dpp v21, v21, v21 row_ror:4 row_mask:0xf bank_mask:0xf
	s_waitcnt lgkmcnt(0)
	s_nop 1
	v_add_f32_dpp v21, v21, v21 row_ror:2 row_mask:0xf bank_mask:0xf
	s_waitcnt lgkmcnt(0)
	s_nop 1
	v_add_f32_dpp v21, v21, v21 row_ror:1 row_mask:0xf bank_mask:0xf
	v_add_f32_e32 v21, 0x358637bd, v21
	v_mul_f32_e32 v27, 0x4b800000, v21
	v_cmp_gt_f32_e32 vcc, s2, v21
	s_nop 1
	v_cndmask_b32_e32 v21, v21, v27, vcc
	v_rsq_f32_e32 v21, v21
	s_nop 0
	v_mul_f32_e32 v27, 0x45800000, v21
	v_cndmask_b32_e32 v21, v21, v27, vcc
	v_mul_f32_e32 v62, v129, v21
	v_pk_mul_f32 v[44:45], v[44:45], v[62:63] op_sel_hi:[1,0]
	v_pk_mul_f32 v[46:47], v[46:47], v[62:63] op_sel_hi:[1,0]
	v_pk_mul_f32 v[50:51], v[50:51], v[62:63] op_sel_hi:[1,0]
	v_pk_mul_f32 v[56:57], v[56:57], v[62:63] op_sel_hi:[1,0]
; DI F8 unpack8(uint4 u) { F8 r; r.v[0] = lo16(u.x); r.v[1] = hi16(u.x); r.v[2] = lo16(u.y); r.v[3] = hi16(u.y); r.v[4] = lo16(u.z); r.v[5] = hi16(u.z); r.v[6] = lo16(u.w); r.v[7] = hi16(u.w); return r; }
; DI void stb8(bf16_t* p, const F8& f) { *(uint4*)p = pack8(f); }
; DI float gsum16(float v) { v += __shfl_xor(v, 8); v += __shfl_xor(v, 4); v += __shfl_xor(v, 2); v += __shfl_xor(v, 1); return v; }
; DI float siluf(float x) { return x / (1.f + __expf(-x)); }
; DI void odd_elem(const Params& p, int o) {
;     ...
;         for (int t = 0; t < 16; ++t) {
;             const F8 x0 = unpack8(xr[t]);
;             F8 acc; float ss = 0.f;
; #pragma unroll
;             for (int k = 0; k < 8; ++k) { const float a = w3.v[k] * x0.v[k] + w2.v[k] * h1.v[k] + w1.v[k] * h2.v[k] + w0.v[k] * h3.v[k]; acc.v[k] = siluf(a); ss += acc.v[k] * acc.v[k]; }
;             if (gi < 4) {
;                 const float rs = rsqrtf(gsum16(ss) + EPS) * nsc;
; #pragma unroll
;                 for (int k = 0; k < 8; ++k) acc.v[k] *= rs;
;             }
;             stb8(Q2 + (size_t)(r0 + t) * 3072 + c, acc);
.LBB0_193:
	s_or_b64 exec, exec, s[40:41]
	v_or_b32_e32 v21, 12, v123
	v_mad_i64_i32 v[62:63], s[40:41], v21, s33, v[110:111]
	v_cvt_pk_bf16_f32 v44, v44, v45
	v_cvt_pk_bf16_f32 v45, v46, v47
	v_cvt_pk_bf16_f32 v46, v50, v51
	v_cvt_pk_bf16_f32 v47, v56, v57
	v_and_b32_e32 v57, 0xffff0000, v40
	v_mov_b32_e32 v56, v71
	global_store_dwordx4 v[62:63], v[44:47], off
	v_pk_mul_f32 v[80:81], v[112:113], v[56:57]
	v_mul_f32_e32 v72, v28, v17
	v_lshlrev_b32_e32 v44, 16, v40
	v_mul_f32_e32 v50, v32, v44
	v_pk_mul_f32 v[74:75], v[114:115], v[74:75]
	v_mov_b32_e32 v73, v80
	v_mov_b32_e32 v51, v81
	v_mul_f32_e32 v76, v24, v33
	v_pk_add_f32 v[50:51], v[72:73], v[50:51]
	v_mov_b32_e32 v77, v75
	v_mul_f32_e32 v78, v20, v84
	v_pk_add_f32 v[50:51], v[76:77], v[50:51]
	v_mov_b32_e32 v79, v74
	v_pk_add_f32 v[50:51], v[78:79], v[50:51]
	v_lshlrev_b32_e32 v46, 16, v41
	v_mul_f32_e32 v21, 0xbfb8aa3b, v50
	v_exp_f32_e32 v72, v21
	v_mul_f32_e32 v21, 0xbfb8aa3b, v51
	v_exp_f32_e32 v73, v21
	v_and_b32_e32 v65, 0xffff0000, v41
	v_mov_b32_e32 v64, v67
	v_pk_mul_f32 v[80:81], v[116:117], v[64:65]
	v_pk_add_f32 v[72:73], v[72:73], 1.0 op_sel_hi:[1,0]
	v_mul_f32_e32 v74, v30, v13
	v_pk_mul_f32 v[68:69], v[118:119], v[68:69]
	v_mov_b32_e32 v75, v80
	v_mul_f32_e32 v76, v26, v25
	v_rcp_f32_e32 v21, v73
	s_nop 0
	v_mul_f32_e32 v51, v51, v21
	v_mov_b32_e32 v73, v81
	v_mov_b32_e32 v77, v69
	v_mul_f32_e32 v78, v22, v31
	v_rcp_f32_e32 v21, v72
	s_nop 0
	v_mul_f32_e32 v50, v50, v21
	v_mul_f32_e32 v72, v34, v46
	v_pk_add_f32 v[72:73], v[74:75], v[72:73]
	v_mov_b32_e32 v79, v68
	v_pk_add_f32 v[72:73], v[76:77], v[72:73]
	v_and_b32_e32 v63, 0xffff0000, v42
	v_pk_add_f32 v[68:69], v[78:79], v[72:73]
	v_mov_b32_e32 v62, v59
	v_mul_f32_e32 v21, 0xbfb8aa3b, v68
	v_exp_f32_e32 v72, v21
	v_mul_f32_e32 v21, 0xbfb8aa3b, v69
	v_exp_f32_e32 v73, v21
	v_lshlrev_b32_e32 v40, 16, v42
	v_pk_mul_f32 v[80:81], v[136:137], v[62:63]
	v_mul_f32_e32 v74, v12, v9
	v_pk_add_f32 v[72:73], v[72:73], 1.0 op_sel_hi:[1,0]
	v_pk_mul_f32 v[48:49], v[108:109], v[48:49]
	v_mov_b32_e32 v75, v80
	v_mul_f32_e32 v76, v8, v5
	v_mov_b32_e32 v77, v49
	v_rcp_f32_e32 v21, v73
	s_nop 0
	v_mul_f32_e32 v69, v69, v21
	v_mov_b32_e32 v73, v81
	v_mul_f32_e32 v78, v4, v23
	v_mov_b32_e32 v79, v48
	v_rcp_f32_e32 v21, v72
	s_nop 0
	v_mul_f32_e32 v68, v68, v21
	v_mul_f32_e32 v72, v16, v40
	v_pk_add_f32 v[72:73], v[74:75], v[72:73]
	v_lshlrev_b32_e32 v42, 16, v43
	v_pk_add_f32 v[72:73], v[76:77], v[72:73]
	v_and_b32_e32 v43, 0xffff0000, v43
	v_pk_add_f32 v[48:49], v[78:79], v[72:73]
	s_nop 0
	v_mul_f32_e32 v21, 0xbfb8aa3b, v48
	v_exp_f32_e32 v72, v21
	v_mul_f32_e32 v21, 0xbfb8aa3b, v49
	v_exp_f32_e32 v73, v21
	s_nop 0
	v_pk_add_f32 v[72:73], v[72:73], 1.0 op_sel_hi:[1,0]
	s_nop 0
	v_rcp_f32_e32 v21, v73
	s_nop 0
	v_mul_f32_e32 v49, v49, v21
	v_rcp_f32_e32 v21, v72
	s_nop 0
	v_mul_f32_e32 v48, v48, v21
	v_pk_mul_f32 v[72:73], v[18:19], v[42:43]
	s_nop 0
	v_pk_fma_f32 v[72:73], v[14:15], v[60:61], v[72:73]
	s_nop 0
	v_pk_fma_f32 v[72:73], v[10:11], v[52:53], v[72:73]
	s_nop 0
	v_pk_fma_f32 v[54:55], v[6:7], v[54:55], v[72:73]
	s_nop 0
	v_mul_f32_e32 v21, 0xbfb8aa3b, v54
	v_exp_f32_e32 v72, v21
	v_mul_f32_e32 v21, 0xbfb8aa3b, v55
	v_exp_f32_e32 v73, v21
	s_nop 0
	v_pk_add_f32 v[72:73], v[72:73], 1.0 op_sel_hi:[1,0]
	s_nop 0
	v_rcp_f32_e32 v21, v73
	s_nop 0
	v_mul_f32_e32 v55, v55, v21
	v_rcp_f32_e32 v21, v72
	s_nop 0
	v_mul_f32_e32 v54, v54, v21
	s_and_saveexec_b64 s[40:41], s[36:37]
	s_cbranch_execz .LBB0_195
	v_pk_mul_f32 v[72:73], v[50:51], v[50:51]
	v_pk_mul_f32 v[74:75], v[68:69], v[68:69]
	v_add_f32_e32 v21, v72, v73
	v_add_f32_e32 v21, v21, v74
	v_pk_mul_f32 v[76:77], v[48:49], v[48:49]
	v_add_f32_e32 v21, v21, v75
	v_and_b32_e32 v27, 64, v251
	v_add_f32_e32 v21, v21, v76
	v_add_u32_e32 v27, 64, v27
	v_pk_mul_f32 v[78:79], v[54:55], v[54:55]
	v_add_f32_e32 v21, v21, v77
	v_add_f32_e32 v21, v21, v78
	v_add_f32_e32 v21, v21, v79
	s_waitcnt lgkmcnt(0)
	s_nop 1
	v_add_f32_dpp v21, v21, v21 row_ror:8 row_mask:0xf bank_mask:0xf
	s_waitcnt lgkmcnt(0)
	s_nop 1
	v_add_f32_dpp v21, v21, v21 row_ror:4 row_mask:0xf bank_mask:0xf
	s_waitcnt lgkmcnt(0)
	s_nop 1
	v_add_f32_dpp v21, v21, v21 row_ror:2 row_mask:0xf bank_mask:0xf
	s_waitcnt lgkmcnt(0)
	s_nop 1
	v_add_f32_dpp v21, v21, v21 row_ror:1 row_mask:0xf bank_mask:0xf
	v_add_f32_e32 v21, 0x358637bd, v21
	v_mul_f32_e32 v23, 0x4b800000, v21
	v_cmp_gt_f32_e32 vcc, s2, v21
	s_nop 1
	v_cndmask_b32_e32 v21, v21, v23, vcc
	v_rsq_f32_e32 v21, v21
	s_nop 0
	v_mul_f32_e32 v23, 0x45800000, v21
	v_cndmask_b32_e32 v21, v21, v23, vcc
	v_mul_f32_e32 v72, v129, v21
	v_pk_mul_f32 v[50:51], v[50:51], v[72:73] op_sel_hi:[1,0]
	v_pk_mul_f32 v[68:69], v[68:69], v[72:73] op_sel_hi:[1,0]
	v_pk_mul_f32 v[48:49], v[48:49], v[72:73] op_sel_hi:[1,0]
	v_pk_mul_f32 v[54:55], v[54:55], v[72:73] op_sel_hi:[1,0]

; DI F8 unpack8(uint4 u) { F8 r; r.v[0] = lo16(u.x); r.v[1] = hi16(u.x); r.v[2] = lo16(u.y); r.v[3] = hi16(u.y); r.v[4] = lo16(u.z); r.v[5] = hi16(u.z); r.v[6] = lo16(u.w); r.v[7] = hi16(u.w); return r; }
; DI void stb8(bf16_t* p, const F8& f) { *(uint4*)p = pack8(f); }
; DI float gsum16(float v) { v += __shfl_xor(v, 8); v += __shfl_xor(v, 4); v += __shfl_xor(v, 2); v += __shfl_xor(v, 1); return v; }
; DI float siluf(float x) { return x / (1.f + __expf(-x)); }
; DI void odd_elem(const Params& p, int o) {
;     ...
;         for (int t = 0; t < 16; ++t) {
;             const F8 x0 = unpack8(xr[t]);
;             F8 acc; float ss = 0.f;
; #pragma unroll
;             for (int k = 0; k < 8; ++k) { const float a = w3.v[k] * x0.v[k] + w2.v[k] * h1.v[k] + w1.v[k] * h2.v[k] + w0.v[k] * h3.v[k]; acc.v[k] = siluf(a); ss += acc.v[k] * acc.v[k]; }
;             if (gi < 4) {
;                 const float rs = rsqrtf(gsum16(ss) + EPS) * nsc;
; #pragma unroll
;                 for (int k = 0; k < 8; ++k) acc.v[k] *= rs;
;             }
;             stb8(Q2 + (size_t)(r0 + t) * 3072 + c, acc);
.LBB0_197:
	s_or_b64 exec, exec, s[44:45]
	v_and_b32_e32 v73, 0xffff0000, v36
	v_mov_b32_e32 v72, v57
	v_lshlrev_b32_e32 v48, 16, v36
	v_pk_mul_f32 v[82:83], v[112:113], v[72:73]
	v_mul_f32_e32 v74, v32, v48
	v_mul_f32_e32 v76, v28, v44
	v_pk_mul_f32 v[70:71], v[114:115], v[70:71]
	v_mov_b32_e32 v77, v82
	v_mov_b32_e32 v75, v83
	v_mul_f32_e32 v78, v24, v17
	v_pk_add_f32 v[74:75], v[76:77], v[74:75]
	v_mov_b32_e32 v79, v71
	v_mul_f32_e32 v80, v20, v33
	v_pk_add_f32 v[74:75], v[78:79], v[74:75]
	v_mov_b32_e32 v81, v70
	v_pk_add_f32 v[70:71], v[80:81], v[74:75]
	v_and_b32_e32 v69, 0xffff0000, v37
	v_mul_f32_e32 v21, 0xbfb8aa3b, v70
	v_exp_f32_e32 v74, v21
	v_mul_f32_e32 v21, 0xbfb8aa3b, v71
	v_exp_f32_e32 v75, v21
	v_mov_b32_e32 v68, v65
	v_lshlrev_b32_e32 v50, 16, v37
	v_pk_mul_f32 v[82:83], v[116:117], v[68:69]
	v_pk_add_f32 v[74:75], v[74:75], 1.0 op_sel_hi:[1,0]
	v_mul_f32_e32 v76, v30, v46
	v_pk_mul_f32 v[66:67], v[118:119], v[66:67]
	v_mov_b32_e32 v77, v82
	v_mul_f32_e32 v78, v26, v13
	v_rcp_f32_e32 v21, v75
	s_nop 0
	v_mul_f32_e32 v71, v71, v21
	v_mov_b32_e32 v75, v83
	v_mov_b32_e32 v79, v67
	v_mul_f32_e32 v80, v22, v25
	v_rcp_f32_e32 v21, v74
	s_nop 0
	v_mul_f32_e32 v70, v70, v21
	v_mul_f32_e32 v74, v34, v50
	v_pk_add_f32 v[74:75], v[76:77], v[74:75]
	v_mov_b32_e32 v81, v66
	v_pk_add_f32 v[74:75], v[78:79], v[74:75]
	v_and_b32_e32 v55, 0xffff0000, v38
	v_pk_add_f32 v[66:67], v[80:81], v[74:75]
	v_mov_b32_e32 v54, v63
	v_mul_f32_e32 v21, 0xbfb8aa3b, v66
	v_exp_f32_e32 v74, v21
	v_mul_f32_e32 v21, 0xbfb8aa3b, v67
	v_exp_f32_e32 v75, v21
	v_lshlrev_b32_e32 v36, 16, v38
	v_pk_mul_f32 v[82:83], v[136:137], v[54:55]
	v_mul_f32_e32 v76, v12, v40
	v_pk_add_f32 v[74:75], v[74:75], 1.0 op_sel_hi:[1,0]
	v_pk_mul_f32 v[58:59], v[108:109], v[58:59]
	v_mov_b32_e32 v77, v82
	v_mul_f32_e32 v78, v8, v9
	v_mov_b32_e32 v79, v59
	v_rcp_f32_e32 v21, v75
	s_nop 0
	v_mul_f32_e32 v67, v67, v21
	v_mov_b32_e32 v75, v83
	v_mul_f32_e32 v80, v4, v5
	v_mov_b32_e32 v81, v58
	v_rcp_f32_e32 v21, v74
	s_nop 0
	v_mul_f32_e32 v66, v66, v21
	v_mul_f32_e32 v74, v16, v36
	v_pk_add_f32 v[74:75], v[76:77], v[74:75]
	v_lshlrev_b32_e32 v38, 16, v39
	v_pk_add_f32 v[74:75], v[78:79], v[74:75]
	v_and_b32_e32 v39, 0xffff0000, v39
	v_pk_add_f32 v[58:59], v[80:81], v[74:75]
	s_nop 0
	v_mul_f32_e32 v5, 0xbfb8aa3b, v58
	v_exp_f32_e32 v74, v5
	v_mul_f32_e32 v5, 0xbfb8aa3b, v59
	v_exp_f32_e32 v75, v5
	s_nop 0
	v_pk_add_f32 v[74:75], v[74:75], 1.0 op_sel_hi:[1,0]
	s_nop 0
	v_rcp_f32_e32 v5, v75
	s_nop 0
	v_mul_f32_e32 v59, v59, v5
	v_rcp_f32_e32 v5, v74
	s_nop 0
	v_mul_f32_e32 v58, v58, v5
	v_pk_mul_f32 v[74:75], v[18:19], v[38:39]
	s_nop 0
	v_pk_fma_f32 v[74:75], v[14:15], v[42:43], v[74:75]
	s_nop 0
	v_pk_fma_f32 v[74:75], v[10:11], v[60:61], v[74:75]
	s_nop 0
	v_pk_fma_f32 v[52:53], v[6:7], v[52:53], v[74:75]
	s_nop 0
	v_mul_f32_e32 v5, 0xbfb8aa3b, v52
	v_exp_f32_e32 v74, v5
	v_mul_f32_e32 v5, 0xbfb8aa3b, v53
	v_exp_f32_e32 v75, v5
	s_nop 0
	v_pk_add_f32 v[74:75], v[74:75], 1.0 op_sel_hi:[1,0]
	s_nop 0
	v_rcp_f32_e32 v5, v75
	s_nop 0
	v_mul_f32_e32 v53, v53, v5
	v_rcp_f32_e32 v5, v74
	s_nop 0
	v_mul_f32_e32 v52, v52, v5
	s_and_saveexec_b64 s[44:45], s[36:37]
	s_cbranch_execz .LBB0_199
	v_pk_mul_f32 v[74:75], v[70:71], v[70:71]
	v_pk_mul_f32 v[76:77], v[66:67], v[66:67]
	v_add_f32_e32 v5, v74, v75
	v_add_f32_e32 v5, v5, v76
	v_pk_mul_f32 v[78:79], v[58:59], v[58:59]
	v_add_f32_e32 v5, v5, v77
	v_and_b32_e32 v23, 64, v251
	v_add_f32_e32 v5, v5, v78
	v_add_u32_e32 v23, 64, v23
	v_pk_mul_f32 v[80:81], v[52:53], v[52:53]
	v_add_f32_e32 v5, v5, v79
	v_add_f32_e32 v5, v5, v80
	v_add_f32_e32 v5, v5, v81
	s_waitcnt lgkmcnt(0)
	s_nop 1
	v_add_f32_dpp v5, v5, v5 row_ror:8 row_mask:0xf bank_mask:0xf
	s_waitcnt lgkmcnt(0)
	s_nop 1
	v_add_f32_dpp v5, v5, v5 row_ror:4 row_mask:0xf bank_mask:0xf
	s_waitcnt lgkmcnt(0)
	s_nop 1
	v_add_f32_dpp v5, v5, v5 row_ror:2 row_mask:0xf bank_mask:0xf
	s_waitcnt lgkmcnt(0)
	s_nop 1
	v_add_f32_dpp v5, v5, v5 row_ror:1 row_mask:0xf bank_mask:0xf
	v_add_f32_e32 v5, 0x358637bd, v5
	v_mul_f32_e32 v21, 0x4b800000, v5
	v_cmp_gt_f32_e32 vcc, s2, v5
	s_nop 1
	v_cndmask_b32_e32 v5, v5, v21, vcc
	v_rsq_f32_e32 v5, v5
	s_nop 0
	v_mul_f32_e32 v21, 0x45800000, v5
	v_cndmask_b32_e32 v5, v5, v21, vcc
	v_mul_f32_e32 v54, v129, v5
	v_pk_mul_f32 v[70:71], v[70:71], v[54:55] op_sel_hi:[1,0]
	v_pk_mul_f32 v[66:67], v[66:67], v[54:55] op_sel_hi:[1,0]
	v_pk_mul_f32 v[58:59], v[58:59], v[54:55] op_sel_hi:[1,0]
	v_pk_mul_f32 v[52:53], v[52:53], v[54:55] op_sel_hi:[1,0]

; DI F8 unpack8(uint4 u) { F8 r; r.v[0] = lo16(u.x); r.v[1] = hi16(u.x); r.v[2] = lo16(u.y); r.v[3] = hi16(u.y); r.v[4] = lo16(u.z); r.v[5] = hi16(u.z); r.v[6] = lo16(u.w); r.v[7] = hi16(u.w); return r; }
; DI void stb8(bf16_t* p, const F8& f) { *(uint4*)p = pack8(f); }
; DI float gsum16(float v) { v += __shfl_xor(v, 8); v += __shfl_xor(v, 4); v += __shfl_xor(v, 2); v += __shfl_xor(v, 1); return v; }
; DI float siluf(float x) { return x / (1.f + __expf(-x)); }
; DI void odd_elem(const Params& p, int o) {
;     ...
;         for (int t = 0; t < 16; ++t) {
;             const F8 x0 = unpack8(xr[t]);
;             F8 acc; float ss = 0.f;
; #pragma unroll
;             for (int k = 0; k < 8; ++k) { const float a = w3.v[k] * x0.v[k] + w2.v[k] * h1.v[k] + w1.v[k] * h2.v[k] + w0.v[k] * h3.v[k]; acc.v[k] = siluf(a); ss += acc.v[k] * acc.v[k]; }
;             if (gi < 4) {
;                 const float rs = rsqrtf(gsum16(ss) + EPS) * nsc;
; #pragma unroll
;                 for (int k = 0; k < 8; ++k) acc.v[k] *= rs;
;             }
;             stb8(Q2 + (size_t)(r0 + t) * 3072 + c, acc);
.LBB0_201:
	s_or_b64 exec, exec, s[44:45]
	v_and_b32_e32 v21, 0xffff0000, v0
	v_mul_f32_e32 v24, v24, v44
	v_mul_f32_e32 v44, v20, v17
	v_mov_b32_e32 v20, v73
	v_lshlrev_b32_e32 v52, 16, v0
	v_pk_mul_f32 v[58:59], v[112:113], v[20:21]
	v_mul_f32_e32 v32, v32, v52
	v_mul_f32_e32 v48, v28, v48
	v_pk_mul_f32 v[56:57], v[114:115], v[56:57]
	v_mov_b32_e32 v49, v58
	v_mov_b32_e32 v33, v59
	v_pk_add_f32 v[32:33], v[48:49], v[32:33]
	v_mov_b32_e32 v25, v57
	v_pk_add_f32 v[24:25], v[24:25], v[32:33]
	v_mov_b32_e32 v45, v56
	v_pk_add_f32 v[24:25], v[44:45], v[24:25]
	v_lshlrev_b32_e32 v58, 16, v3
	v_mul_f32_e32 v0, 0xbfb8aa3b, v24
	v_exp_f32_e32 v32, v0
	v_mul_f32_e32 v0, 0xbfb8aa3b, v25
	v_exp_f32_e32 v33, v0
	v_lshlrev_b32_e32 v56, 16, v2
	v_and_b32_e32 v59, 0xffff0000, v3
	v_and_b32_e32 v3, 0xffff0000, v2
	v_pk_add_f32 v[32:33], v[32:33], 1.0 op_sel_hi:[1,0]
	v_lshlrev_b32_e32 v54, 16, v1
	v_div_scale_f32 v0, s[44:45], v33, v33, v25
	v_rcp_f32_e32 v5, v0
	v_and_b32_e32 v1, 0xffff0000, v1
	v_mul_f32_e32 v34, v34, v54
	v_mul_f32_e32 v30, v30, v50
	v_fma_f32 v2, -v0, v5, 1.0
	v_fmac_f32_e32 v5, v2, v5
	v_div_scale_f32 v2, vcc, v25, v33, v25
	v_mul_f32_e32 v17, v2, v5
	v_fma_f32 v20, -v0, v17, v2
	v_fmac_f32_e32 v17, v20, v5
	v_fma_f32 v0, -v0, v17, v2
	v_div_scale_f32 v2, s[44:45], v32, v32, v24
	v_rcp_f32_e32 v20, v2
	v_div_fmas_f32 v0, v0, v5, v17
	v_div_fixup_f32 v23, v0, v33, v25
	v_pk_mul_f32 v[50:51], v[118:119], v[64:65]
	v_fma_f32 v0, -v2, v20, 1.0
	v_fmac_f32_e32 v20, v0, v20
	v_mov_b32_e32 v0, v69
	v_pk_mul_f32 v[48:49], v[116:117], v[0:1]
	v_mul_f32_e32 v44, v26, v46
	v_mov_b32_e32 v31, v48
	v_mov_b32_e32 v35, v49
	v_pk_add_f32 v[30:31], v[30:31], v[34:35]
	v_mov_b32_e32 v45, v51
	v_mul_f32_e32 v46, v22, v13
	v_pk_add_f32 v[30:31], v[44:45], v[30:31]
	v_mov_b32_e32 v47, v50
	v_pk_add_f32 v[30:31], v[46:47], v[30:31]
	v_div_scale_f32 v5, vcc, v24, v32, v24
	v_mul_f32_e32 v0, 0xbfb8aa3b, v30
	v_exp_f32_e32 v34, v0
	v_mul_f32_e32 v0, 0xbfb8aa3b, v31
	v_exp_f32_e32 v35, v0
	v_mul_f32_e32 v17, v5, v20
	v_fma_f32 v0, -v2, v17, v5
	v_fmac_f32_e32 v17, v0, v20
	v_pk_add_f32 v[34:35], v[34:35], 1.0 op_sel_hi:[1,0]
	v_fma_f32 v0, -v2, v17, v5
	v_div_fmas_f32 v0, v0, v20, v17
	v_div_fixup_f32 v22, v0, v32, v24
	v_mul_f32_e32 v16, v16, v56
	v_mov_b32_e32 v2, v55
	v_pk_mul_f32 v[32:33], v[136:137], v[2:3]
	v_mul_f32_e32 v12, v12, v36
	v_pk_mul_f32 v[36:37], v[108:109], v[62:63]
	v_mov_b32_e32 v13, v32
	v_mov_b32_e32 v17, v33
	v_mul_f32_e32 v8, v8, v40
	v_mul_f32_e32 v24, v4, v9
	v_pk_add_f32 v[12:13], v[12:13], v[16:17]
	v_mov_b32_e32 v9, v37
	v_div_scale_f32 v20, s[44:45], v34, v34, v30
	v_pk_add_f32 v[8:9], v[8:9], v[12:13]
	v_mov_b32_e32 v25, v36
	v_rcp_f32_e32 v26, v20
	v_pk_add_f32 v[8:9], v[24:25], v[8:9]
	v_rcp_f32_e32 v0, v35
	s_nop 0
	v_mul_f32_e32 v5, v31, v0
	v_mul_f32_e32 v2, 0xbfb8aa3b, v8
	v_exp_f32_e32 v12, v2
	v_mul_f32_e32 v2, 0xbfb8aa3b, v9
	v_exp_f32_e32 v13, v2
	v_fma_f32 v0, -v20, v26, 1.0
	v_fmac_f32_e32 v26, v0, v26
	v_div_scale_f32 v0, vcc, v30, v34, v30
	v_mul_f32_e32 v28, v0, v26
	v_fma_f32 v2, -v20, v28, v0
	v_pk_add_f32 v[12:13], v[12:13], 1.0 op_sel_hi:[1,0]
	v_fmac_f32_e32 v28, v2, v26
	v_div_scale_f32 v2, s[44:45], v13, v13, v9
	v_rcp_f32_e32 v16, v2
	v_fma_f32 v0, -v20, v28, v0
	v_div_fmas_f32 v0, v0, v26, v28
	v_div_fixup_f32 v4, v0, v34, v30
	v_fma_f32 v0, -v2, v16, 1.0
	v_fmac_f32_e32 v16, v0, v16
	v_div_scale_f32 v0, vcc, v9, v13, v9
	v_mul_f32_e32 v17, v0, v16
	v_fma_f32 v20, -v2, v17, v0
	v_fmac_f32_e32 v17, v20, v16
	v_fma_f32 v0, -v2, v17, v0
	v_div_scale_f32 v2, s[44:45], v12, v12, v8
	v_div_fmas_f32 v0, v0, v16, v17
	v_pk_mul_f32 v[16:17], v[18:19], v[58:59]
	v_rcp_f32_e32 v20, v2
	v_pk_fma_f32 v[14:15], v[14:15], v[38:39], v[16:17]
	v_div_fixup_f32 v9, v0, v13, v9
	v_pk_fma_f32 v[10:11], v[10:11], v[42:43], v[14:15]
	v_fma_f32 v0, -v2, v20, 1.0
	v_pk_fma_f32 v[6:7], v[6:7], v[60:61], v[10:11]
	v_fmac_f32_e32 v20, v0, v20
	v_mul_f32_e32 v10, 0xbfb8aa3b, v6
	v_mul_f32_e32 v11, 0xbfb8aa3b, v7
	v_exp_f32_e32 v10, v10
	v_exp_f32_e32 v11, v11
	v_div_scale_f32 v0, vcc, v8, v12, v8
	v_mul_f32_e32 v13, v0, v20
	v_fma_f32 v14, -v2, v13, v0
	v_fmac_f32_e32 v13, v14, v20
	v_pk_add_f32 v[10:11], v[10:11], 1.0 op_sel_hi:[1,0]
	v_fma_f32 v0, -v2, v13, v0
	v_div_scale_f32 v2, s[44:45], v11, v11, v7
	v_rcp_f32_e32 v14, v2
	v_div_fmas_f32 v0, v0, v20, v13
	v_div_fixup_f32 v8, v0, v12, v8
	v_fma_f32 v0, -v2, v14, 1.0
	v_fmac_f32_e32 v14, v0, v14
	v_div_scale_f32 v0, vcc, v7, v11, v7
	v_mul_f32_e32 v12, v0, v14
	v_fma_f32 v13, -v2, v12, v0
	v_fmac_f32_e32 v12, v13, v14
	v_fma_f32 v0, -v2, v12, v0
	s_nop 0
	v_div_fmas_f32 v0, v0, v14, v12
	v_div_fixup_f32 v7, v0, v11, v7
	v_rcp_f32_e32 v0, v10
	s_nop 0
	v_mul_f32_e32 v6, v6, v0
	s_and_saveexec_b64 s[44:45], s[36:37]
	s_cbranch_execz .LBB0_203
	v_pk_mul_f32 v[10:11], v[22:23], v[22:23]
	v_pk_mul_f32 v[12:13], v[4:5], v[4:5]
	v_add_f32_e32 v0, v10, v11
	v_add_f32_e32 v0, v0, v12
	v_pk_mul_f32 v[14:15], v[8:9], v[8:9]
	v_add_f32_e32 v0, v0, v13
	v_and_b32_e32 v10, 64, v251
	v_add_f32_e32 v0, v0, v14
	v_add_u32_e32 v10, 64, v10
	v_pk_mul_f32 v[16:17], v[6:7], v[6:7]
	v_add_f32_e32 v0, v0, v15
	v_add_f32_e32 v0, v0, v16
	v_add_f32_e32 v0, v0, v17
	s_waitcnt lgkmcnt(0)
	s_nop 1
	v_add_f32_dpp v0, v0, v0 row_ror:8 row_mask:0xf bank_mask:0xf
	s_waitcnt lgkmcnt(0)
	s_nop 1
	v_add_f32_dpp v0, v0, v0 row_ror:4 row_mask:0xf bank_mask:0xf
	s_waitcnt lgkmcnt(0)
	s_nop 1
	v_add_f32_dpp v0, v0, v0 row_ror:2 row_mask:0xf bank_mask:0xf
	s_waitcnt lgkmcnt(0)
	s_nop 1
	v_add_f32_dpp v0, v0, v0 row_ror:1 row_mask:0xf bank_mask:0xf
	v_add_f32_e32 v0, 0x358637bd, v0
	v_mul_f32_e32 v2, 0x4b800000, v0
	v_cmp_gt_f32_e32 vcc, s2, v0
	s_nop 1
	v_cndmask_b32_e32 v0, v0, v2, vcc
	v_rsq_f32_e32 v0, v0
	s_nop 0
	v_mul_f32_e32 v2, 0x45800000, v0
	v_cndmask_b32_e32 v0, v0, v2, vcc
	v_mul_f32_e32 v0, v129, v0
	v_pk_mul_f32 v[22:23], v[22:23], v[0:1] op_sel_hi:[1,0]
	v_pk_mul_f32 v[4:5], v[4:5], v[0:1] op_sel_hi:[1,0]
	v_pk_mul_f32 v[8:9], v[8:9], v[0:1] op_sel_hi:[1,0]
	v_pk_mul_f32 v[6:7], v[6:7], v[0:1] op_sel_hi:[1,0]

; DI F8 ldb8(const bf16_t* p) { return unpack8(*(const uint4*)p); }
; DI void stb8(bf16_t* p, const F8& f) { *(uint4*)p = pack8(f); }
; DI float gsum16(float v) { v += __shfl_xor(v, 8); v += __shfl_xor(v, 4); v += __shfl_xor(v, 2); v += __shfl_xor(v, 1); return v; }
; DI float siluf(float x) { return x / (1.f + __expf(-x)); }
; DI void odd_gate(const Params& p, int o) {
;     ...
;     for (int r = gw; r < MT; r += nw) {
; #pragma unroll
;         for (int it = 0; it < 2; ++it) {
;             const int c = it * 512 + lane * 8;
;             F8 x = ldb8(OB + (size_t)r * 1024 + c); const F8 z = ldb8(ZAB + (size_t)r * 1152 + c), gg = ldf8(go + (c & 127));
;             float ss = 0.f;
;             for (int k = 0; k < 8; ++k) ss += x.v[k] * x.v[k];
;             const float rs = rsqrtf(gsum16(ss) * (1.f / 128.f) + EPS);
;             for (int k = 0; k < 8; ++k) x.v[k] = x.v[k] * rs * gg.v[k] * siluf(z.v[k]);
;             stb8(OB + (size_t)r * 1024 + c, x);
;         }
.LBB0_425:
	v_lshl_add_u64 v[0:1], v[12:13], 0, v[212:213]
	v_add_co_u32_e32 v16, vcc, 0x7800000, v0
	v_lshl_add_u64 v[26:27], v[14:15], 0, v[212:213]
	s_nop 0
	v_addc_co_u32_e32 v17, vcc, 0, v1, vcc
	global_load_dwordx4 v[0:3], v[16:17], off
	v_add_u32_e32 v8, s6, v8
	v_lshl_add_u64 v[12:13], v[12:13], 0, s[14:15]
	v_lshl_add_u64 v[14:15], v[14:15], 0, s[18:19]
	s_waitcnt vmcnt(0)
	v_lshlrev_b32_e32 v24, 16, v0
	v_and_b32_e32 v25, 0xffff0000, v0
	v_lshlrev_b32_e32 v22, 16, v1
	v_and_b32_e32 v23, 0xffff0000, v1
	v_lshlrev_b32_e32 v20, 16, v2
	v_and_b32_e32 v21, 0xffff0000, v2
	v_lshlrev_b32_e32 v18, 16, v3
	v_and_b32_e32 v19, 0xffff0000, v3
	global_load_dwordx4 v[0:3], v[26:27], off
	v_mov_b32_e32 v63, v25
	v_pk_mul_f32 v[54:55], v[22:23], v[22:23]
	v_mov_b32_e32 v61, v24
	v_pk_mul_f32 v[52:53], v[20:21], v[20:21]
	v_pk_mul_f32 v[50:51], v[18:19], v[18:19]
	s_waitcnt vmcnt(0)
	v_lshlrev_b32_e32 v33, 16, v2
	v_and_b32_e32 v34, 0xffff0000, v2
	v_mul_f32_e32 v28, 0xbfb8aa3b, v33
	v_mul_f32_e32 v29, 0xbfb8aa3b, v34
	v_exp_f32_e32 v28, v28
	v_exp_f32_e32 v29, v29
	v_lshlrev_b32_e32 v31, 16, v1
	v_and_b32_e32 v32, 0xffff0000, v1
	v_lshlrev_b32_e32 v9, 16, v0
	v_pk_add_f32 v[28:29], v[28:29], 1.0 op_sel_hi:[1,0]
	v_and_b32_e32 v30, 0xffff0000, v0
	v_lshlrev_b32_e32 v35, 16, v3
	v_and_b32_e32 v46, 0xffff0000, v3
	global_load_dwordx4 v[0:3], v[10:11], off offset:16
	global_load_dwordx4 v[4:7], v[10:11], off
	v_rcp_f32_e32 v36, v29
	s_nop 0
	v_mul_f32_e32 v37, v34, v36
	v_rcp_f32_e32 v29, v28
	s_nop 0
	v_mul_f32_e32 v36, v33, v29
	v_mul_f32_e32 v28, 0xbfb8aa3b, v31
	v_mul_f32_e32 v29, 0xbfb8aa3b, v32
	v_exp_f32_e32 v28, v28
	v_exp_f32_e32 v29, v29
	s_nop 0
	v_pk_add_f32 v[28:29], v[28:29], 1.0 op_sel_hi:[1,0]
	s_nop 0
	v_rcp_f32_e32 v33, v29
	s_nop 0
	v_mul_f32_e32 v39, v32, v33
	v_rcp_f32_e32 v29, v28
	s_nop 0
	v_mul_f32_e32 v38, v31, v29
	v_mul_f32_e32 v28, 0xbfb8aa3b, v9
	v_mul_f32_e32 v29, 0xbfb8aa3b, v30
	v_exp_f32_e32 v28, v28
	v_exp_f32_e32 v29, v29
	s_nop 0
	v_pk_add_f32 v[28:29], v[28:29], 1.0 op_sel_hi:[1,0]
	s_nop 0
	v_rcp_f32_e32 v31, v29
	s_nop 0
	v_mul_f32_e32 v41, v30, v31
	v_rcp_f32_e32 v29, v28
	s_nop 0
	v_mul_f32_e32 v40, v9, v29
	v_mul_f32_e32 v9, 0xbfb8aa3b, v35
	v_exp_f32_e32 v28, v9
	v_mul_f32_e32 v9, 0xbfb8aa3b, v46
	v_exp_f32_e32 v29, v9
	s_nop 0
	v_pk_add_f32 v[28:29], v[28:29], 1.0 op_sel_hi:[1,0]
	s_nop 0
	v_rcp_f32_e32 v9, v29
	s_nop 0
	v_mul_f32_e32 v57, v46, v9
	global_load_dwordx4 v[46:49], v[16:17], off offset:1024
	s_brev_b32 s26, 60
	v_rcp_f32_e32 v9, v28
	s_nop 0
	v_mul_f32_e32 v56, v35, v9
	s_waitcnt vmcnt(0)
	v_and_b32_e32 v35, 0xffff0000, v46
	v_lshlrev_b32_e32 v34, 16, v46
	v_lshlrev_b32_e32 v32, 16, v47
	v_and_b32_e32 v33, 0xffff0000, v47
	v_mov_b32_e32 v62, v35
	v_pk_mul_f32 v[58:59], v[32:33], v[32:33]
	v_mov_b32_e32 v60, v34
	v_pk_mul_f32 v[62:63], v[62:63], v[62:63]
	v_lshlrev_b32_e32 v30, 16, v48
	v_and_b32_e32 v31, 0xffff0000, v48
	v_pk_fma_f32 v[60:61], v[60:61], v[60:61], v[62:63]
	v_mov_b32_e32 v62, v58
	v_mov_b32_e32 v63, v54
	v_lshlrev_b32_e32 v28, 16, v49
	v_and_b32_e32 v29, 0xffff0000, v49
	v_pk_mul_f32 v[48:49], v[30:31], v[30:31]
	v_pk_add_f32 v[60:61], v[60:61], v[62:63]
	v_mov_b32_e32 v54, v59
	v_pk_add_f32 v[54:55], v[54:55], v[60:61]
	v_mov_b32_e32 v58, v48
	v_mov_b32_e32 v59, v52
	v_pk_mul_f32 v[46:47], v[28:29], v[28:29]
	v_pk_add_f32 v[54:55], v[58:59], v[54:55]
	v_mov_b32_e32 v52, v49
	v_pk_add_f32 v[48:49], v[52:53], v[54:55]
	v_mov_b32_e32 v52, v46
	v_mov_b32_e32 v53, v50
	v_pk_add_f32 v[48:49], v[52:53], v[48:49]
	v_mov_b32_e32 v50, v47
	v_pk_add_f32 v[46:47], v[50:51], v[48:49]
	s_waitcnt lgkmcnt(0)
	s_nop 1
	v_add_f32_dpp v46, v46, v46 row_ror:8 row_mask:0xf bank_mask:0xf
	v_add_f32_dpp v47, v47, v47 row_ror:8 row_mask:0xf bank_mask:0xf
	s_waitcnt lgkmcnt(0)
	s_nop 1
	v_add_f32_dpp v46, v46, v46 row_ror:4 row_mask:0xf bank_mask:0xf
	v_add_f32_dpp v47, v47, v47 row_ror:4 row_mask:0xf bank_mask:0xf
	s_waitcnt lgkmcnt(0)
; DI F8 ldb8(const bf16_t* p) { return unpack8(*(const uint4*)p); }
; DI void stb8(bf16_t* p, const F8& f) { *(uint4*)p = pack8(f); }
; DI float gsum16(float v) { v += __shfl_xor(v, 8); v += __shfl_xor(v, 4); v += __shfl_xor(v, 2); v += __shfl_xor(v, 1); return v; }
; DI float siluf(float x) { return x / (1.f + __expf(-x)); }
; DI void odd_gate(const Params& p, int o) {
;     ...
;     for (int r = gw; r < MT; r += nw) {
; #pragma unroll
;         for (int it = 0; it < 2; ++it) {
;             const int c = it * 512 + lane * 8;
;             F8 x = ldb8(OB + (size_t)r * 1024 + c); const F8 z = ldb8(ZAB + (size_t)r * 1152 + c), gg = ldf8(go + (c & 127));
;             float ss = 0.f;
;             for (int k = 0; k < 8; ++k) ss += x.v[k] * x.v[k];
;             const float rs = rsqrtf(gsum16(ss) * (1.f / 128.f) + EPS);
;             for (int k = 0; k < 8; ++k) x.v[k] = x.v[k] * rs * gg.v[k] * siluf(z.v[k]);
;             stb8(OB + (size_t)r * 1024 + c, x);
;         }
	s_nop 1
	v_add_f32_dpp v46, v46, v46 row_ror:2 row_mask:0xf bank_mask:0xf
	v_add_f32_dpp v47, v47, v47 row_ror:2 row_mask:0xf bank_mask:0xf
	ds_bpermute_b32 v49, v45, v47
	ds_bpermute_b32 v48, v45, v46
	s_waitcnt lgkmcnt(0)
	v_pk_add_f32 v[46:47], v[46:47], v[48:49]
	s_nop 0
	v_pk_fma_f32 v[46:47], v[46:47], s[26:27], v[64:65] op_sel_hi:[1,0,0]
	s_nop 0
	v_mul_f32_e32 v9, 0x4b800000, v47
	v_cmp_gt_f32_e32 vcc, s2, v47
	v_cmp_gt_f32_e64 s[36:37], s2, v46
	s_nop 0
	v_cndmask_b32_e32 v9, v47, v9, vcc
	v_rsq_f32_e32 v9, v9
	s_nop 0
	v_mul_f32_e32 v47, 0x45800000, v9
	v_cndmask_b32_e32 v48, v9, v47, vcc
	v_pk_mul_f32 v[20:21], v[48:49], v[20:21] op_sel_hi:[0,1]
	v_pk_mul_f32 v[0:1], v[0:1], v[20:21]
	v_pk_mul_f32 v[24:25], v[48:49], v[24:25] op_sel_hi:[0,1]
	v_pk_mul_f32 v[22:23], v[48:49], v[22:23] op_sel_hi:[0,1]
	v_pk_mul_f32 v[20:21], v[36:37], v[0:1]
	v_pk_mul_f32 v[0:1], v[48:49], v[18:19] op_sel_hi:[0,1]
	v_pk_mul_f32 v[4:5], v[4:5], v[24:25]
	v_pk_mul_f32 v[6:7], v[6:7], v[22:23]
	v_pk_mul_f32 v[0:1], v[2:3], v[0:1]
	v_pk_mul_f32 v[4:5], v[40:41], v[4:5]
	v_pk_mul_f32 v[6:7], v[38:39], v[6:7]
	v_pk_mul_f32 v[18:19], v[56:57], v[0:1]
	v_cvt_pk_bf16_f32 v0, v4, v5
	v_cvt_pk_bf16_f32 v1, v6, v7
	v_cvt_pk_bf16_f32 v2, v20, v21
	v_cvt_pk_bf16_f32 v3, v18, v19
	global_store_dwordx4 v[16:17], v[0:3], off
	global_load_dwordx4 v[0:3], v[26:27], off offset:1024
	s_waitcnt vmcnt(0)
	v_lshlrev_b32_e32 v20, 16, v2
	v_and_b32_e32 v21, 0xffff0000, v2
	v_mul_f32_e32 v18, 0xbfb8aa3b, v20
	v_mul_f32_e32 v19, 0xbfb8aa3b, v21
	v_exp_f32_e32 v18, v18
	v_exp_f32_e32 v19, v19
	v_lshlrev_b32_e32 v9, 16, v0
	v_and_b32_e32 v24, 0xffff0000, v0
	v_lshlrev_b32_e32 v22, 16, v1
	v_pk_add_f32 v[18:19], v[18:19], 1.0 op_sel_hi:[1,0]
	v_and_b32_e32 v23, 0xffff0000, v1
	v_lshlrev_b32_e32 v25, 16, v3
	v_and_b32_e32 v36, 0xffff0000, v3
	global_load_dwordx4 v[0:3], v[10:11], off offset:16
	global_load_dwordx4 v[4:7], v[10:11], off
	v_rcp_f32_e32 v26, v19
	s_nop 0
	v_mul_f32_e32 v19, v21, v26
	v_rcp_f32_e32 v21, v18
	s_nop 0
	v_mul_f32_e32 v18, v20, v21
	v_mul_f32_e32 v20, 0xbfb8aa3b, v22
	v_mul_f32_e32 v21, 0xbfb8aa3b, v23
	v_exp_f32_e32 v20, v20
	v_exp_f32_e32 v21, v21
	s_nop 0
	v_pk_add_f32 v[20:21], v[20:21], 1.0 op_sel_hi:[1,0]
	s_nop 0
	v_rcp_f32_e32 v26, v21
	s_nop 0
	v_mul_f32_e32 v21, v23, v26
	v_rcp_f32_e32 v23, v20
	s_nop 0
	v_mul_f32_e32 v20, v22, v23
	v_mul_f32_e32 v22, 0xbfb8aa3b, v9
	v_mul_f32_e32 v23, 0xbfb8aa3b, v24
	v_exp_f32_e32 v22, v22
	v_exp_f32_e32 v23, v23
	s_nop 0
	v_pk_add_f32 v[22:23], v[22:23], 1.0 op_sel_hi:[1,0]
	s_nop 0
	v_rcp_f32_e32 v26, v23
	s_nop 0
	v_mul_f32_e32 v23, v24, v26
	v_rcp_f32_e32 v24, v22
	s_nop 0
	v_mul_f32_e32 v22, v9, v24
	v_mul_f32_e32 v9, 0x4b800000, v46
	v_cndmask_b32_e64 v9, v46, v9, s[36:37]
	v_rsq_f32_e32 v9, v9
	s_nop 0
	v_mul_f32_e32 v24, 0x45800000, v9
	v_cndmask_b32_e64 v24, v9, v24, s[36:37]
	v_pk_mul_f32 v[26:27], v[24:25], v[34:35] op_sel_hi:[0,1]
	s_waitcnt vmcnt(0)
	v_pk_mul_f32 v[4:5], v[4:5], v[26:27]
	s_nop 0
	v_pk_mul_f32 v[4:5], v[22:23], v[4:5]
	v_pk_mul_f32 v[22:23], v[24:25], v[32:33] op_sel_hi:[0,1]
	v_pk_mul_f32 v[6:7], v[6:7], v[22:23]
	s_nop 0
	v_pk_mul_f32 v[6:7], v[20:21], v[6:7]
	v_pk_mul_f32 v[20:21], v[24:25], v[30:31] op_sel_hi:[0,1]
	v_pk_mul_f32 v[0:1], v[0:1], v[20:21]
	v_pk_mul_f32 v[20:21], v[24:25], v[28:29] op_sel_hi:[0,1]
	v_pk_mul_f32 v[18:19], v[18:19], v[0:1]
	v_mul_f32_e32 v0, 0xbfb8aa3b, v25
	v_mul_f32_e32 v1, 0xbfb8aa3b, v36
	v_exp_f32_e32 v0, v0
	v_exp_f32_e32 v1, v1
	v_pk_mul_f32 v[2:3], v[2:3], v[20:21]
	v_pk_add_f32 v[0:1], v[0:1], 1.0 op_sel_hi:[1,0]
	s_nop 0
	v_rcp_f32_e32 v9, v1
	s_nop 0
	v_mul_f32_e32 v1, v36, v9
	v_rcp_f32_e32 v9, v0
	s_nop 0
	v_mul_f32_e32 v0, v25, v9
	v_pk_mul_f32 v[20:21], v[0:1], v[2:3]
	v_cmp_lt_i32_e32 vcc, s30, v8
	v_cvt_pk_bf16_f32 v0, v4, v5
	v_cvt_pk_bf16_f32 v1, v6, v7
	v_cvt_pk_bf16_f32 v2, v18, v19
	v_cvt_pk_bf16_f32 v3, v20, v21
	s_or_b64 s[22:23], vcc, s[22:23]
	global_store_dwordx4 v[16:17], v[0:3], off offset:1024
	s_andn2_b64 exec, exec, s[22:23]
	s_cbranch_execnz .LBB0_425

; DI F8 unpack8(uint4 u) { F8 r; r.v[0] = lo16(u.x); r.v[1] = hi16(u.x); r.v[2] = lo16(u.y); r.v[3] = hi16(u.y); r.v[4] = lo16(u.z); r.v[5] = hi16(u.z); r.v[6] = lo16(u.w); r.v[7] = hi16(u.w); return r; }
; DI void stf8(float* p, const F8& f) { *(float4*)p = make_float4(f.v[0], f.v[1], f.v[2], f.v[3]); *(float4*)(p + 4) = make_float4(f.v[4], f.v[5], f.v[6], f.v[7]); }
; DI void stb8(bf16_t* p, const F8& f) { *(uint4*)p = pack8(f); }
; DI float wsum(float v) { v += __shfl_xor(v, 32); v += __shfl_xor(v, 16); v += __shfl_xor(v, 8); v += __shfl_xor(v, 4); v += __shfl_xor(v, 2); v += __shfl_xor(v, 1); return v; }
; DI void rowinfo(int r, int& sq, int& pos, int& len) { if (r < MP) { sq = r >> 13; pos = r & 8191; len = 8192; } else { sq = 4 + ((r - MP) >> 6); pos = r & 63; len = 64; } }
; DI void even_elem(const Params& p, int e) {
;     ...
;             for (int q = 0; q < 2; ++q) { const bf16_t* hr = H1 + (size_t)rr[q] * 2304;
;                 xq[q] = *(const uint4*)(hr + lq * 8); xkv[q] = *(const uint4*)(hr + 384 + lk * 8); x1[q] = *(const uint4*)(hr + 640 + lr * 8); x2[q] = *(const uint4*)(hr + 656 + lr * 8); }
; #pragma unroll
;             for (int q = 0; q < 2; ++q) {
;                 if (q == 1 && !two) break;
;                 const int r = rr[q]; int sq, pos, len; rowinfo(r, sq, pos, len);
;                 const int kvr = kvrow_of(r), apos = sq >= 4 ? pos + 2048 : pos;
;                 { F8 x = unpack8(xq[q]); float ss = 0.f;
;                   if (lane < 48) { for (int k = 0; k < 8; ++k) ss += x.v[k] * x.v[k]; }
;                   const float rs = rsqrtf(wsum(ss) * (1.f / 384.f) + EPS);
;                   if (lane < 48) { for (int k = 0; k < 8; ++k) x.v[k] *= rs * gqv.v[k]; stb8(QN + (size_t)r * 384 + lane * 8, x); } }
;                 { F8 x = unpack8(xkv[q]); float ss = 0.f;
;                   if (lane < 32) { for (int k = 0; k < 8; ++k) ss += x.v[k] * x.v[k]; }
;                   const float rs = rsqrtf(wsum(ss) * (1.f / 256.f) + EPS);
;                   if (lane < 32) { for (int k = 0; k < 8; ++k) x.v[k] *= rs * gkvv.v[k];
;                       float* lo = sq < 4 ? p.out + O_PLAT + (((size_t)e * 4 + sq) * 8192 + pos) * 256 : p.out + O_SLAT + (((size_t)e * 8 + (sq - 4)) * 64 + pos) * 256;
;                       stf8(lo + lane * 8, x); stb8(LAT + (size_t)kvr * 256 + lane * 8, x); } }
.LBB0_619:
	s_waitcnt vmcnt(2)
	v_lshl_add_u64 v[16:17], s[62:63], 0, v[70:71]
	v_add_co_u32_e32 v16, vcc, 0x7800000, v16
	v_add_u32_e32 v89, s54, v88
	s_nop 0
	v_addc_co_u32_e32 v17, vcc, 0, v17, vcc
	global_load_dwordx4 v[52:55], v[16:17], off
	v_lshl_add_u64 v[16:17], s[62:63], 0, v[66:67]
	s_mov_b32 s44, 0x8200
	v_cmp_gt_i32_e64 s[44:45], s44, v89
	v_add_co_u32_e32 v16, vcc, 0x7800000, v16
	v_lshl_add_u64 v[18:19], s[62:63], 0, v[68:69]
	v_mov_b64_e32 v[20:21], s[84:85]
	v_cndmask_b32_e64 v90, v88, v89, s[44:45]
	s_movk_i32 s46, 0x1200
	v_addc_co_u32_e32 v17, vcc, 0, v17, vcc
	v_mov_b32_e32 v73, v213
	v_mov_b32_e32 v75, v213
	v_mad_i64_i32 v[20:21], s[46:47], v90, s46, v[20:21]
	s_waitcnt vmcnt(1)
	v_add_co_u32_e32 v32, vcc, 0x7800000, v18
	v_lshl_add_u64 v[22:23], v[20:21], 0, v[212:213]
	v_lshl_add_u64 v[24:25], v[20:21], 0, v[72:73]
	s_waitcnt lgkmcnt(0)
	v_lshl_add_u64 v[34:35], v[20:21], 0, v[74:75]
	v_addc_co_u32_e32 v33, vcc, 0, v19, vcc
	global_load_dwordx4 v[40:43], v[16:17], off offset:768
	global_load_dwordx4 v[28:31], v[22:23], off
	s_nop 0
	global_load_dwordx4 v[24:27], v[24:25], off offset:768
	s_nop 0
	global_load_dwordx4 v[20:23], v[34:35], off offset:1280
	global_load_dwordx4 v[16:19], v[34:35], off offset:1312
	global_load_dwordx4 v[36:39], v[32:33], off offset:1280
	s_nop 0
	global_load_dwordx4 v[32:35], v[32:33], off offset:1312
	s_waitcnt vmcnt(7)
	v_lshlrev_b32_e32 v50, 16, v52
	v_and_b32_e32 v51, 0xffff0000, v52
	v_lshlrev_b32_e32 v48, 16, v53
	v_and_b32_e32 v49, 0xffff0000, v53
	v_pk_mul_f32 v[52:53], v[50:51], v[50:51]
	v_lshlrev_b32_e32 v46, 16, v54
	v_and_b32_e32 v47, 0xffff0000, v54
	v_lshlrev_b32_e32 v44, 16, v55
	v_and_b32_e32 v45, 0xffff0000, v55
	v_pk_mul_f32 v[54:55], v[48:49], v[48:49]
	v_add_f32_e32 v52, v52, v53
	v_add_f32_e32 v52, v52, v54
	v_pk_mul_f32 v[76:77], v[46:47], v[46:47]
	v_add_f32_e32 v52, v55, v52
	v_add_f32_e32 v52, v76, v52
	v_pk_mul_f32 v[78:79], v[44:45], v[44:45]
	v_add_f32_e32 v52, v77, v52
	v_add_f32_e32 v52, v78, v52
	v_add_f32_e32 v52, v79, v52
	v_cndmask_b32_e64 v52, 0, v52, s[40:41]
	v_mov_b32_e32 v53, v52
	s_waitcnt lgkmcnt(0)
	s_nop 1
	v_permlane32_swap_b32_e32 v52, v53
	v_add_f32_e32 v52, v52, v53
	v_mov_b32_e32 v53, v52
	s_waitcnt lgkmcnt(0)
	s_nop 1
	v_permlane16_swap_b32_e32 v52, v53
	v_add_f32_e32 v52, v52, v53
	s_waitcnt lgkmcnt(0)
	s_nop 1
	v_add_f32_dpp v52, v52, v52 row_ror:8 row_mask:0xf bank_mask:0xf
	s_waitcnt lgkmcnt(0)
	s_nop 1
	v_add_f32_dpp v52, v52, v52 row_ror:4 row_mask:0xf bank_mask:0xf
	s_waitcnt lgkmcnt(0)
	s_nop 1
	v_add_f32_dpp v52, v52, v52 row_ror:2 row_mask:0xf bank_mask:0xf
	ds_bpermute_b32 v53, v87, v52
	s_and_saveexec_b64 s[46:47], s[40:41]
	s_cbranch_execz .LBB0_621
	s_waitcnt lgkmcnt(0)
	v_add_f32_e32 v52, v52, v53
	v_mov_b32_e32 v54, 0x358637bd
	v_fmamk_f32 v52, v52, 0x3b2aaaab, v54
	v_cmp_gt_f32_e32 vcc, s2, v52
	v_mul_f32_e32 v53, 0x4b800000, v52
	s_nop 0
	v_cndmask_b32_e32 v52, v52, v53, vcc
	v_rsq_f32_e32 v52, v52
	s_nop 0
	v_mul_f32_e32 v53, 0x45800000, v52
	v_cndmask_b32_e32 v52, v52, v53, vcc
	v_pk_mul_f32 v[54:55], v[4:5], v[52:53] op_sel_hi:[1,0]
	s_nop 0
	v_pk_mul_f32 v[50:51], v[54:55], v[50:51]
	v_pk_mul_f32 v[54:55], v[6:7], v[52:53] op_sel_hi:[1,0]
	s_nop 0
	v_pk_mul_f32 v[48:49], v[54:55], v[48:49]
	v_pk_mul_f32 v[54:55], v[0:1], v[52:53] op_sel_hi:[1,0]
	v_pk_mul_f32 v[52:53], v[2:3], v[52:53] op_sel_hi:[1,0]
	v_pk_mul_f32 v[46:47], v[54:55], v[46:47]
	v_lshl_add_u64 v[54:55], s[62:63], 0, v[64:65]
	v_pk_mul_f32 v[52:53], v[52:53], v[44:45]
	v_cvt_pk_bf16_f32 v45, v48, v49
	v_add_co_u32_e32 v48, vcc, 0x10a40000, v54
	v_cvt_pk_bf16_f32 v44, v50, v51
	v_cvt_pk_bf16_f32 v46, v46, v47
	v_cvt_pk_bf16_f32 v47, v52, v53
	v_addc_co_u32_e32 v49, vcc, 0, v55, vcc
	global_store_dwordx4 v[48:49], v[44:47], off
.LBB0_621:
	s_or_b64 exec, exec, s[46:47]
	s_waitcnt vmcnt(6)
	v_lshlrev_b32_e32 v48, 16, v40
	v_and_b32_e32 v49, 0xffff0000, v40
	v_lshlrev_b32_e32 v46, 16, v41
	v_and_b32_e32 v47, 0xffff0000, v41
	v_lshlrev_b32_e32 v44, 16, v42
	v_and_b32_e32 v45, 0xffff0000, v42
	v_lshlrev_b32_e32 v40, 16, v43
	v_and_b32_e32 v41, 0xffff0000, v43
	v_pk_mul_f32 v[42:43], v[48:49], v[48:49]
	v_pk_mul_f32 v[50:51], v[46:47], v[46:47]
	v_add_f32_e32 v42, v42, v43
	v_add_f32_e32 v42, v42, v50
	s_waitcnt lgkmcnt(0)
	v_pk_mul_f32 v[52:53], v[44:45], v[44:45]
	v_add_f32_e32 v42, v51, v42
	v_add_f32_e32 v42, v52, v42
	v_pk_mul_f32 v[54:55], v[40:41], v[40:41]
	v_add_f32_e32 v42, v53, v42
	v_add_f32_e32 v42, v54, v42
	v_add_f32_e32 v42, v55, v42
	v_cndmask_b32_e64 v42, 0, v42, s[38:39]
	v_mov_b32_e32 v43, v42
	v_add_u32_e32 v50, 0xffff8000, v88
	v_lshrrev_b32_e32 v52, 6, v50
	v_add_u32_e32 v50, 4, v52
	v_ashrrev_i32_e32 v51, 13, v88
	s_waitcnt lgkmcnt(0)
	s_nop 1
	v_permlane32_swap_b32_e32 v42, v43
	v_add_f32_e32 v42, v42, v43
	v_mov_b32_e32 v43, v42
	v_cmp_gt_i32_e32 vcc, s53, v88
	s_movk_i32 s46, 0x840
	v_mov_b32_e32 v53, 0x1fff
	v_cndmask_b32_e32 v78, v50, v51, vcc
	s_waitcnt lgkmcnt(0)
	s_nop 1
	v_permlane16_swap_b32_e32 v42, v43
	v_add_f32_e32 v42, v42, v43
	v_cndmask_b32_e32 v53, 63, v53, vcc
	v_and_b32_e32 v73, v53, v88
	s_waitcnt lgkmcnt(0)
	s_nop 1
	v_add_f32_dpp v42, v42, v42 row_ror:8 row_mask:0xf bank_mask:0xf
	s_waitcnt lgkmcnt(0)
	s_nop 1
	v_add_f32_dpp v42, v42, v42 row_ror:4 row_mask:0xf bank_mask:0xf
	s_waitcnt lgkmcnt(0)
	s_nop 1
	v_add_f32_dpp v50, v42, v42 row_ror:2 row_mask:0xf bank_mask:0xf
	ds_bpermute_b32 v51, v87, v50
	v_mul_lo_u32 v42, v52, s46
	v_and_or_b32 v42, v88, 63, v42
	v_add_u32_e32 v42, 0x8800, v42
	v_cndmask_b32_e32 v76, v42, v88, vcc
	s_and_saveexec_b64 s[46:47], s[38:39]
	s_cbranch_execnz .LBB0_624
	s_or_b64 exec, exec, s[46:47]
	s_and_saveexec_b64 s[46:47], s[42:43]
	s_cbranch_execnz .LBB0_629

; DI F8 unpack8(uint4 u) { F8 r; r.v[0] = lo16(u.x); r.v[1] = hi16(u.x); r.v[2] = lo16(u.y); r.v[3] = hi16(u.y); r.v[4] = lo16(u.z); r.v[5] = hi16(u.z); r.v[6] = lo16(u.w); r.v[7] = hi16(u.w); return r; }
; DI void stf8(float* p, const F8& f) { *(float4*)p = make_float4(f.v[0], f.v[1], f.v[2], f.v[3]); *(float4*)(p + 4) = make_float4(f.v[4], f.v[5], f.v[6], f.v[7]); }
; DI void stb8(bf16_t* p, const F8& f) { *(uint4*)p = pack8(f); }
; DI float wsum(float v) { v += __shfl_xor(v, 32); v += __shfl_xor(v, 16); v += __shfl_xor(v, 8); v += __shfl_xor(v, 4); v += __shfl_xor(v, 2); v += __shfl_xor(v, 1); return v; }
; DI void rowinfo(int r, int& sq, int& pos, int& len) { if (r < MP) { sq = r >> 13; pos = r & 8191; len = 8192; } else { sq = 4 + ((r - MP) >> 6); pos = r & 63; len = 64; } }
; DI void even_elem(const Params& p, int e) {
;     ...
;             for (int q = 0; q < 2; ++q) {
;                 if (q == 1 && !two) break;
;                 const int r = rr[q]; int sq, pos, len; rowinfo(r, sq, pos, len);
;                 const int kvr = kvrow_of(r), apos = sq >= 4 ? pos + 2048 : pos;
;                 { F8 x = unpack8(xq[q]); float ss = 0.f;
;                   if (lane < 48) { for (int k = 0; k < 8; ++k) ss += x.v[k] * x.v[k]; }
;                   const float rs = rsqrtf(wsum(ss) * (1.f / 384.f) + EPS);
;                   if (lane < 48) { for (int k = 0; k < 8; ++k) x.v[k] *= rs * gqv.v[k]; stb8(QN + (size_t)r * 384 + lane * 8, x); } }
;                 { F8 x = unpack8(xkv[q]); float ss = 0.f;
;                   if (lane < 32) { for (int k = 0; k < 8; ++k) ss += x.v[k] * x.v[k]; }
;                   const float rs = rsqrtf(wsum(ss) * (1.f / 256.f) + EPS);
;                   if (lane < 32) { for (int k = 0; k < 8; ++k) x.v[k] *= rs * gkvv.v[k];
;                       float* lo = sq < 4 ? p.out + O_PLAT + (((size_t)e * 4 + sq) * 8192 + pos) * 256 : p.out + O_SLAT + (((size_t)e * 8 + (sq - 4)) * 64 + pos) * 256;
;                       stf8(lo + lane * 8, x); stb8(LAT + (size_t)kvr * 256 + lane * 8, x); } }
.LBB0_634:
	s_waitcnt vmcnt(1)
	v_lshlrev_b32_e32 v36, 16, v28
	v_and_b32_e32 v37, 0xffff0000, v28
	s_waitcnt vmcnt(0)
	v_lshlrev_b32_e32 v34, 16, v29
	v_and_b32_e32 v35, 0xffff0000, v29
	v_lshlrev_b32_e32 v32, 16, v30
	v_and_b32_e32 v33, 0xffff0000, v30
	v_lshlrev_b32_e32 v28, 16, v31
	v_and_b32_e32 v29, 0xffff0000, v31
	v_pk_mul_f32 v[30:31], v[36:37], v[36:37]
	v_pk_mul_f32 v[38:39], v[34:35], v[34:35]
	v_add_f32_e32 v30, v30, v31
	v_add_f32_e32 v30, v30, v38
	v_pk_mul_f32 v[40:41], v[32:33], v[32:33]
	v_add_f32_e32 v30, v39, v30
	v_add_f32_e32 v30, v40, v30
	v_pk_mul_f32 v[42:43], v[28:29], v[28:29]
	v_add_f32_e32 v30, v41, v30
	v_add_f32_e32 v30, v42, v30
	v_add_f32_e32 v30, v43, v30
	v_cndmask_b32_e64 v30, 0, v30, s[40:41]
	v_mov_b32_e32 v31, v30
	s_waitcnt lgkmcnt(0)
	s_nop 1
	v_permlane32_swap_b32_e32 v30, v31
	v_add_f32_e32 v30, v30, v31
	v_mov_b32_e32 v31, v30
	s_waitcnt lgkmcnt(0)
	s_nop 1
	v_permlane16_swap_b32_e32 v30, v31
	v_add_f32_e32 v30, v30, v31
	s_waitcnt lgkmcnt(0)
	s_nop 1
	v_add_f32_dpp v30, v30, v30 row_ror:8 row_mask:0xf bank_mask:0xf
	s_waitcnt lgkmcnt(0)
	s_nop 1
	v_add_f32_dpp v30, v30, v30 row_ror:4 row_mask:0xf bank_mask:0xf
	s_waitcnt lgkmcnt(0)
	s_nop 1
	v_add_f32_dpp v30, v30, v30 row_ror:2 row_mask:0xf bank_mask:0xf
	ds_bpermute_b32 v31, v87, v30
	s_and_saveexec_b64 s[44:45], s[40:41]
	s_cbranch_execz .LBB0_636
	s_waitcnt lgkmcnt(0)
	v_add_f32_e32 v30, v30, v31
	v_mov_b32_e32 v38, 0x358637bd
	v_fmamk_f32 v30, v30, 0x3b2aaaab, v38
	v_cmp_gt_f32_e32 vcc, s2, v30
	v_mul_f32_e32 v31, 0x4b800000, v30
	s_movk_i32 s48, 0x300
	v_cndmask_b32_e32 v30, v30, v31, vcc
	v_rsq_f32_e32 v30, v30
	v_mad_i64_i32 v[40:41], s[48:49], v90, s48, v[56:57]
	v_mul_f32_e32 v31, 0x45800000, v30
	v_cndmask_b32_e32 v30, v30, v31, vcc
	v_pk_mul_f32 v[38:39], v[4:5], v[30:31] op_sel_hi:[1,0]
	s_nop 0
	v_pk_mul_f32 v[36:37], v[38:39], v[36:37]
	v_pk_mul_f32 v[38:39], v[6:7], v[30:31] op_sel_hi:[1,0]
	s_nop 0
	v_pk_mul_f32 v[34:35], v[38:39], v[34:35]
	v_pk_mul_f32 v[38:39], v[0:1], v[30:31] op_sel_hi:[1,0]
	v_pk_mul_f32 v[30:31], v[2:3], v[30:31] op_sel_hi:[1,0]
	v_pk_mul_f32 v[32:33], v[38:39], v[32:33]
	v_pk_mul_f32 v[38:39], v[30:31], v[28:29]
	v_cvt_pk_bf16_f32 v28, v36, v37
	v_cvt_pk_bf16_f32 v29, v34, v35
	v_cvt_pk_bf16_f32 v30, v32, v33
	v_cvt_pk_bf16_f32 v31, v38, v39
	global_store_dwordx4 v[40:41], v[28:31], off
.LBB0_636:
	s_or_b64 exec, exec, s[44:45]
	v_lshlrev_b32_e32 v32, 16, v24
	v_and_b32_e32 v33, 0xffff0000, v24
	v_lshlrev_b32_e32 v30, 16, v25
	s_waitcnt lgkmcnt(0)
	v_and_b32_e32 v31, 0xffff0000, v25
	v_lshlrev_b32_e32 v28, 16, v26
	v_and_b32_e32 v29, 0xffff0000, v26
	v_lshlrev_b32_e32 v24, 16, v27
	v_and_b32_e32 v25, 0xffff0000, v27
	v_pk_mul_f32 v[26:27], v[32:33], v[32:33]
	v_pk_mul_f32 v[34:35], v[30:31], v[30:31]
	v_add_f32_e32 v26, v26, v27
	v_add_f32_e32 v26, v26, v34
	v_pk_mul_f32 v[36:37], v[28:29], v[28:29]
	v_add_f32_e32 v26, v35, v26
	v_add_f32_e32 v26, v36, v26
	v_pk_mul_f32 v[38:39], v[24:25], v[24:25]
	v_add_f32_e32 v26, v37, v26
	v_add_f32_e32 v26, v38, v26
	v_add_f32_e32 v26, v39, v26
	v_cndmask_b32_e64 v26, 0, v26, s[38:39]
	v_mov_b32_e32 v27, v26
	v_add_u32_e32 v34, 0xffff8000, v89
	v_lshrrev_b32_e32 v36, 6, v34
	v_add_u32_e32 v34, 4, v36
	v_ashrrev_i32_e32 v35, 13, v89
	s_waitcnt lgkmcnt(0)
	s_nop 1
	v_permlane32_swap_b32_e32 v26, v27
	v_add_f32_e32 v26, v26, v27
	v_mov_b32_e32 v27, v26
	v_cmp_gt_i32_e32 vcc, s53, v89
	s_movk_i32 s44, 0x840
	v_mov_b32_e32 v37, 0x1fff
	v_cndmask_b32_e32 v42, v34, v35, vcc
	s_waitcnt lgkmcnt(0)
	s_nop 1
	v_permlane16_swap_b32_e32 v26, v27
	v_add_f32_e32 v26, v26, v27
	v_cndmask_b32_e32 v37, 63, v37, vcc
	v_and_b32_e32 v46, v37, v89
	s_waitcnt lgkmcnt(0)
	s_nop 1
	v_add_f32_dpp v26, v26, v26 row_ror:8 row_mask:0xf bank_mask:0xf
	s_waitcnt lgkmcnt(0)
	s_nop 1
	v_add_f32_dpp v26, v26, v26 row_ror:4 row_mask:0xf bank_mask:0xf
	s_waitcnt lgkmcnt(0)
	s_nop 1
	v_add_f32_dpp v34, v26, v26 row_ror:2 row_mask:0xf bank_mask:0xf
	ds_bpermute_b32 v35, v87, v34
	v_mul_lo_u32 v26, v36, s44
	v_and_or_b32 v26, v89, 63, v26
	v_add_u32_e32 v26, 0x8800, v26
	v_cndmask_b32_e32 v40, v26, v89, vcc
	s_and_saveexec_b64 s[44:45], s[38:39]
	s_cbranch_execz .LBB0_642
	v_cmp_lt_i32_e32 vcc, 3, v42
	s_and_saveexec_b64 s[48:49], vcc
	s_xor_b64 s[48:49], exec, s[48:49]
	v_add_u32_e32 v26, -4, v42
	v_mov_b32_e32 v27, v213
	v_lshlrev_b64 v[26:27], 16, v[26:27]
	v_lshlrev_b32_e32 v36, 10, v46
	v_mov_b32_e32 v37, v213
	v_lshl_add_u64 v[26:27], s[14:15], 0, v[26:27]
	v_lshl_add_u64 v[26:27], v[26:27], 0, v[36:37]
	s_andn2_saveexec_b64 s[48:49], s[48:49]
	s_cbranch_execz .LBB0_641
	v_ashrrev_i32_e32 v43, 31, v42
	v_lshlrev_b64 v[26:27], 13, v[42:43]
	v_lshl_add_u64 v[26:27], v[26:27], 0, s[6:7]
	v_or_b32_e32 v26, v26, v46
	v_readlane_b32 s58, v254, 24
	v_lshlrev_b64 v[26:27], 10, v[26:27]
	v_readlane_b32 s59, v254, 25
	s_nop 1
	v_lshl_add_u64 v[26:27], s[58:59], 0, v[26:27]

; DI unsigned pack2(float lo, float hi) { const f32n2 v = {lo, hi}; return __builtin_bit_cast(unsigned, __builtin_convertvector(v, bf16n2)); }
; DI void attn_phase(const Params& p, unsigned char* smem) {
;     ...
;         if (wtiles > 0) {
; #pragma unroll
;             for (int qs = 0; qs < 2; ++qs) {
;                 float l = lrow[qs]; l += __shfl_xor(l, 16); l += __shfl_xor(l, 32);
;                 const float inv = 1.f / l;
;                 const int row = qrow0 + 32 * wave + 16 * qs + fr;
; #pragma unroll
;                 for (int dt = 0; dt < 4; ++dt) {
;                     uint2 o; o.x = pack2(ot[dt][qs][0] * inv, ot[dt][qs][1] * inv); o.y = pack2(ot[dt][qs][2] * inv, ot[dt][qs][3] * inv);
;                     *(uint2*)(CAT + (size_t)row * 1024 + h * 64 + 16 * dt + 4 * g) = o;
;                 }
;             }
.LBB0_959:
	s_and_saveexec_b64 s[0:1], s[40:41]
	s_cbranch_execz .LBB0_903
	v_and_b32_e32 v1, 64, v251
	v_xor_b32_e32 v0, 16, v251
	v_add_u32_e32 v1, 64, v1
	v_cmp_lt_i32_e32 vcc, v0, v1
	v_xor_b32_e32 v2, 32, v251
	s_lshl_b32 s50, s27, 1
	v_cndmask_b32_e32 v0, v251, v0, vcc
	v_lshlrev_b32_e32 v3, 2, v0
	ds_bpermute_b32 v0, v3, v200
	v_cmp_lt_i32_e32 vcc, v2, v1
	s_waitcnt lgkmcnt(0)
	v_add_f32_e32 v0, v200, v0
	v_cndmask_b32_e32 v1, v251, v2, vcc
	v_lshlrev_b32_e32 v10, 2, v1
	v_mov_b32_e32 v1, v0
	s_waitcnt lgkmcnt(0)
	s_nop 1
	v_permlane32_swap_b32_e32 v0, v1
	v_add_f32_e32 v2, v0, v1
	v_lshl_add_u64 v[0:1], v[176:177], 0, s[50:51]
	v_rcp_f32_e32 v4, v2
	s_nop 0
	v_mul_f32_e32 v2, 1.0, v4
	v_lshlrev_b64 v[4:5], 11, v[190:191]
	v_pk_mul_f32 v[6:7], v[60:61], v[2:3] op_sel_hi:[1,0]
	v_pk_mul_f32 v[8:9], v[62:63], v[2:3] op_sel_hi:[1,0]
	v_lshl_add_u64 v[4:5], v[0:1], 0, v[4:5]
	v_cvt_pk_bf16_f32 v6, v6, v7
	v_cvt_pk_bf16_f32 v7, v8, v9
	global_store_dwordx2 v[4:5], v[6:7], off
	v_pk_mul_f32 v[6:7], v[48:49], v[2:3] op_sel_hi:[1,0]
	v_pk_mul_f32 v[8:9], v[50:51], v[2:3] op_sel_hi:[1,0]
	ds_bpermute_b32 v3, v3, v201
	v_cvt_pk_bf16_f32 v6, v6, v7
	v_cvt_pk_bf16_f32 v7, v8, v9
	global_store_dwordx2 v[4:5], v[6:7], off offset:32
	s_waitcnt lgkmcnt(0)
	v_pk_mul_f32 v[6:7], v[72:73], v[2:3] op_sel_hi:[1,0]
	v_pk_mul_f32 v[8:9], v[74:75], v[2:3] op_sel_hi:[1,0]
	v_add_f32_e32 v3, v201, v3
	ds_bpermute_b32 v10, v10, v3
	v_cvt_pk_bf16_f32 v6, v6, v7
	v_cvt_pk_bf16_f32 v7, v8, v9
	global_store_dwordx2 v[4:5], v[6:7], off offset:64
	v_pk_mul_f32 v[6:7], v[68:69], v[2:3] op_sel_hi:[1,0]
	s_waitcnt lgkmcnt(0)
	v_add_f32_e32 v8, v3, v10
	v_div_scale_f32 v9, s[6:7], v8, v8, 1.0
	v_rcp_f32_e32 v10, v9
	v_pk_mul_f32 v[2:3], v[70:71], v[2:3] op_sel_hi:[1,0]
	v_cvt_pk_bf16_f32 v6, v6, v7
	v_cvt_pk_bf16_f32 v7, v2, v3
	v_fma_f32 v2, -v9, v10, 1.0
	v_fmac_f32_e32 v10, v2, v10
	v_div_scale_f32 v2, vcc, 1.0, v8, 1.0
	v_mul_f32_e32 v3, v2, v10
	global_store_dwordx2 v[4:5], v[6:7], off offset:96
	v_fma_f32 v4, -v9, v3, v2
	v_fmac_f32_e32 v3, v4, v10
	v_fma_f32 v2, -v9, v3, v2
	v_div_fmas_f32 v2, v2, v10, v3
	v_div_fixup_f32 v2, v2, v8, 1.0
	v_lshlrev_b64 v[4:5], 11, v[192:193]
	v_lshl_add_u64 v[0:1], v[0:1], 0, v[4:5]
	v_pk_mul_f32 v[4:5], v[64:65], v[2:3] op_sel_hi:[1,0]
	v_pk_mul_f32 v[6:7], v[66:67], v[2:3] op_sel_hi:[1,0]
	v_cvt_pk_bf16_f32 v4, v4, v5
	v_cvt_pk_bf16_f32 v5, v6, v7
	global_store_dwordx2 v[0:1], v[4:5], off
	v_pk_mul_f32 v[4:5], v[56:57], v[2:3] op_sel_hi:[1,0]
	v_pk_mul_f32 v[6:7], v[58:59], v[2:3] op_sel_hi:[1,0]
	v_cvt_pk_bf16_f32 v4, v4, v5
	v_cvt_pk_bf16_f32 v5, v6, v7
	global_store_dwordx2 v[0:1], v[4:5], off offset:32
	v_pk_mul_f32 v[4:5], v[52:53], v[2:3] op_sel_hi:[1,0]
	v_pk_mul_f32 v[6:7], v[54:55], v[2:3] op_sel_hi:[1,0]
	v_cvt_pk_bf16_f32 v4, v4, v5
	v_cvt_pk_bf16_f32 v5, v6, v7
	global_store_dwordx2 v[0:1], v[4:5], off offset:64
	v_pk_mul_f32 v[4:5], v[44:45], v[2:3] op_sel_hi:[1,0]
	v_pk_mul_f32 v[2:3], v[46:47], v[2:3] op_sel_hi:[1,0]
	v_cvt_pk_bf16_f32 v4, v4, v5
	v_cvt_pk_bf16_f32 v5, v2, v3
	global_store_dwordx2 v[0:1], v[4:5], off offset:96
	s_branch .LBB0_903

; DI F8 unpack8(uint4 u) { F8 r; r.v[0] = lo16(u.x); r.v[1] = hi16(u.x); r.v[2] = lo16(u.y); r.v[3] = hi16(u.y); r.v[4] = lo16(u.z); r.v[5] = hi16(u.z); r.v[6] = lo16(u.w); r.v[7] = hi16(u.w); return r; }
; DI float wsum(float v) { v += __shfl_xor(v, 32); v += __shfl_xor(v, 16); v += __shfl_xor(v, 8); v += __shfl_xor(v, 4); v += __shfl_xor(v, 2); v += __shfl_xor(v, 1); return v; }
; DI void ln_phase(const Params& p, const bf16_t* __restrict__ Y, const float* __restrict__ g, const float* __restrict__ b, bool final_out) {
;     ...
;     for (int r0 = gw; r0 < MT; r0 += 2 * nw) {
;         const int r1 = r0 + nw; const bool two = r1 < MT; const int rr[2] = {r0, two ? r1 : r0};
;         uint4 xr[2][2], yr[2][2];
; #pragma unroll
;         for (int q = 0; q < 2; ++q)
; #pragma unroll
;             for (int it = 0; it < 2; ++it) { const size_t off = (size_t)rr[q] * 1024 + it * 512 + lane * 8; xr[q][it] = *(const uint4*)(XB + off); yr[q][it] = *(const uint4*)(Y + off); }
;         float v[2][16];
; #pragma unroll
;         for (int q = 0; q < 2; ++q)
; #pragma unroll
;             for (int it = 0; it < 2; ++it) { const F8 x = unpack8(xr[q][it]), y = unpack8(yr[q][it]);
; #pragma unroll
;                 for (int e = 0; e < 8; ++e) v[q][it * 8 + e] = ALPHA * x.v[e] + y.v[e]; }
;         float s0 = 0.f, s1 = 0.f;
; #pragma unroll
;         for (int e = 0; e < 16; ++e) { s0 += v[0][e]; s1 += v[1][e]; }
;         const float mu0 = wsum(s0) * (1.f / 1024.f), mu1 = wsum(s1) * (1.f / 1024.f);
.LBB0_1085:
	v_add_u32_e32 v32, s26, v40
	s_mov_b32 s7, 0x8200
	v_cmp_gt_i32_e64 s[36:37], s7, v32
	global_load_dwordx4 v[54:57], v[46:47], off
	s_waitcnt lgkmcnt(0)
	global_load_dwordx4 v[60:63], v[46:47], off offset:1024
	v_cndmask_b32_e64 v36, v40, v32, s[36:37]
	v_ashrrev_i32_e32 v37, 31, v36
	v_lshlrev_b64 v[48:49], 11, v[36:37]
	v_lshl_or_b32 v36, v42, 1, v48
	v_mov_b32_e32 v37, v49
	v_lshl_add_u64 v[38:39], s[82:83], 0, v[36:37]
	global_load_dwordx4 v[64:67], v[38:39], off
	v_lshl_add_u64 v[38:39], s[76:77], 0, v[36:37]
	v_or_b32_e32 v36, 0x400, v36
	global_load_dwordx4 v[70:73], v[38:39], off
	v_lshl_add_u64 v[38:39], s[82:83], 0, v[36:37]
	global_load_dwordx4 v[74:77], v[38:39], off
	v_lshl_add_u64 v[36:37], s[76:77], 0, v[36:37]
	global_load_dwordx4 v[94:97], v[36:37], off
	v_add_co_u32_e32 v50, vcc, 0xee400000, v46
	s_waitcnt vmcnt(5)
	v_lshlrev_b32_e32 v82, 16, v54
	v_addc_co_u32_e32 v51, vcc, -1, v47, vcc
	v_add_co_u32_e32 v52, vcc, 0xee401000, v46
	global_load_dwordx4 v[32:35], v[50:51], off
	s_nop 0
	v_addc_co_u32_e32 v53, vcc, -1, v47, vcc
	global_load_dwordx4 v[36:39], v[52:53], off offset:-3072
	v_and_b32_e32 v83, 0xffff0000, v54
	v_lshlrev_b32_e32 v78, 16, v55
	v_and_b32_e32 v79, 0xffff0000, v55
	s_waitcnt vmcnt(6)
	v_lshlrev_b32_e32 v58, 16, v60
	v_and_b32_e32 v59, 0xffff0000, v60
	v_lshlrev_b32_e32 v54, 16, v61
	v_and_b32_e32 v55, 0xffff0000, v61
	s_waitcnt vmcnt(5)
	v_lshlrev_b32_e32 v60, 16, v64
	v_and_b32_e32 v61, 0xffff0000, v64
	s_waitcnt vmcnt(4)
	v_lshlrev_b32_e32 v98, 16, v70
	v_and_b32_e32 v99, 0xffff0000, v70
	s_waitcnt vmcnt(3)
	v_lshlrev_b32_e32 v108, 16, v76
	v_and_b32_e32 v109, 0xffff0000, v76
	v_lshlrev_b32_e32 v110, 16, v77
	v_and_b32_e32 v111, 0xffff0000, v77
	v_pk_fma_f32 v[76:77], v[60:61], s[52:53], v[98:99] op_sel_hi:[1,0,1]
	v_lshlrev_b32_e32 v81, 16, v62
	v_and_b32_e32 v80, 0xffff0000, v62
	v_lshlrev_b32_e32 v85, 16, v63
	v_and_b32_e32 v84, 0xffff0000, v63
	v_lshlrev_b32_e32 v62, 16, v65
	v_and_b32_e32 v63, 0xffff0000, v65
	v_lshlrev_b32_e32 v70, 16, v71
	v_and_b32_e32 v71, 0xffff0000, v71
	v_add_f32_e32 v41, 0, v76
	v_lshlrev_b32_e32 v104, 16, v74
	v_and_b32_e32 v105, 0xffff0000, v74
	v_lshlrev_b32_e32 v106, 16, v75
	v_and_b32_e32 v107, 0xffff0000, v75
	v_pk_fma_f32 v[74:75], v[62:63], s[52:53], v[70:71] op_sel_hi:[1,0,1]
	v_add_f32_e32 v41, v77, v41
	v_lshlrev_b32_e32 v64, 16, v66
	v_and_b32_e32 v65, 0xffff0000, v66
	v_lshlrev_b32_e32 v100, 16, v72
	v_and_b32_e32 v101, 0xffff0000, v72
	v_add_f32_e32 v41, v74, v41
	v_lshlrev_b32_e32 v102, 16, v73
	v_and_b32_e32 v103, 0xffff0000, v73
	v_pk_fma_f32 v[72:73], v[64:65], s[52:53], v[100:101] op_sel_hi:[1,0,1]
	v_add_f32_e32 v41, v75, v41
	v_lshlrev_b32_e32 v66, 16, v67
	v_and_b32_e32 v67, 0xffff0000, v67
	v_add_f32_e32 v41, v72, v41
	v_pk_fma_f32 v[70:71], v[66:67], s[52:53], v[102:103] op_sel_hi:[1,0,1]
	v_add_f32_e32 v41, v73, v41
	s_waitcnt vmcnt(2)
	v_lshlrev_b32_e32 v112, 16, v94
	v_and_b32_e32 v113, 0xffff0000, v94
	v_add_f32_e32 v41, v70, v41
	v_pk_fma_f32 v[66:67], v[104:105], s[52:53], v[112:113] op_sel_hi:[1,0,1]
	v_add_f32_e32 v41, v71, v41
	v_lshlrev_b32_e32 v94, 16, v95
	v_and_b32_e32 v95, 0xffff0000, v95
	v_add_f32_e32 v41, v41, v66
	v_pk_fma_f32 v[64:65], v[106:107], s[52:53], v[94:95] op_sel_hi:[1,0,1]
	v_add_f32_e32 v41, v67, v41
	v_lshlrev_b32_e32 v114, 16, v96
	v_and_b32_e32 v115, 0xffff0000, v96
	v_add_f32_e32 v41, v64, v41
	v_pk_fma_f32 v[62:63], v[108:109], s[52:53], v[114:115] op_sel_hi:[1,0,1]
	v_add_f32_e32 v41, v65, v41
	v_lshlrev_b32_e32 v96, 16, v97
	v_and_b32_e32 v97, 0xffff0000, v97
	v_add_f32_e32 v41, v62, v41
	v_pk_fma_f32 v[60:61], v[110:111], s[52:53], v[96:97] op_sel_hi:[1,0,1]
	v_add_f32_e32 v41, v63, v41
	v_add_f32_e32 v41, v60, v41
	v_add_f32_e32 v41, v61, v41
	v_mov_b32_e32 v93, v41
	v_lshlrev_b32_e32 v68, 16, v56
	v_and_b32_e32 v69, 0xffff0000, v56
	v_lshlrev_b32_e32 v56, 16, v57
	v_and_b32_e32 v57, 0xffff0000, v57
	s_waitcnt lgkmcnt(0)
	s_nop 1
	v_permlane32_swap_b32_e32 v41, v93
	v_add_f32_e32 v41, v41, v93
	v_mov_b32_e32 v93, v41
	s_waitcnt vmcnt(1)
	v_lshlrev_b32_e32 v86, 16, v32
	v_and_b32_e32 v87, 0xffff0000, v32
	s_waitcnt lgkmcnt(0)
	s_nop 1
	v_permlane16_swap_b32_e32 v41, v93
	v_add_f32_e32 v41, v41, v93
	s_waitcnt vmcnt(0)
	v_lshlrev_b32_e32 v99, 16, v38
	v_and_b32_e32 v98, 0xffff0000, v38
	v_lshlrev_b32_e32 v101, 16, v39
	v_and_b32_e32 v100, 0xffff0000, v39
	s_waitcnt lgkmcnt(0)
	s_nop 1
	v_add_f32_dpp v41, v41, v41 row_ror:8 row_mask:0xf bank_mask:0xf
	v_lshlrev_b32_e32 v32, 16, v33
	v_and_b32_e32 v33, 0xffff0000, v33
	v_pk_fma_f32 v[78:79], v[32:33], s[52:53], v[78:79] op_sel_hi:[1,0,1]
	v_pk_fma_f32 v[82:83], v[86:87], s[52:53], v[82:83] op_sel_hi:[1,0,1]
	s_waitcnt lgkmcnt(0)
	s_nop 1
	v_add_f32_dpp v38, v41, v41 row_ror:4 row_mask:0xf bank_mask:0xf
	v_lshlrev_b32_e32 v94, 16, v34
	v_and_b32_e32 v95, 0xffff0000, v34
	v_pk_fma_f32 v[86:87], v[94:95], s[52:53], v[68:69] op_sel_hi:[1,0,1]
	v_lshlrev_b32_e32 v34, 16, v35
	s_waitcnt lgkmcnt(0)
	s_nop 1
	v_add_f32_dpp v32, v38, v38 row_ror:2 row_mask:0xf bank_mask:0xf
	v_add_f32_e32 v38, 0, v82
	v_add_f32_e32 v38, v83, v38
	v_add_f32_e32 v38, v78, v38
	v_add_f32_e32 v39, v79, v38
	s_waitcnt lgkmcnt(0)
; DI float wsum(float v) { v += __shfl_xor(v, 32); v += __shfl_xor(v, 16); v += __shfl_xor(v, 8); v += __shfl_xor(v, 4); v += __shfl_xor(v, 2); v += __shfl_xor(v, 1); return v; }
; DI void ln_phase(const Params& p, const bf16_t* __restrict__ Y, const float* __restrict__ g, const float* __restrict__ b, bool final_out) {
;     ...
;         float s0 = 0.f, s1 = 0.f;
; #pragma unroll
;         for (int e = 0; e < 16; ++e) { s0 += v[0][e]; s1 += v[1][e]; }
;         const float mu0 = wsum(s0) * (1.f / 1024.f), mu1 = wsum(s1) * (1.f / 1024.f);
;         float q0 = 0.f, q1 = 0.f;
; #pragma unroll
;         for (int e = 0; e < 16; ++e) { const float d0 = v[0][e] - mu0, d1 = v[1][e] - mu1; q0 += d0 * d0; q1 += d1 * d1; }
;         const float rs0 = rsqrtf(wsum(q0) * (1.f / 1024.f) + EPS), rs1 = rsqrtf(wsum(q1) * (1.f / 1024.f) + EPS);
	s_nop 1
	v_add_f32_dpp v32, v32, v32 row_ror:1 row_mask:0xf bank_mask:0xf
	v_and_b32_e32 v35, 0xffff0000, v35
	v_mul_f32_e32 v38, 0x3a800000, v32
	v_add_f32_e32 v32, v86, v39
	v_add_f32_e32 v32, v87, v32
	v_pk_fma_f32 v[94:95], v[34:35], s[52:53], v[56:57] op_sel_hi:[1,0,1]
	v_lshlrev_b32_e32 v96, 16, v36
	v_and_b32_e32 v97, 0xffff0000, v36
	v_add_f32_e32 v32, v94, v32
	v_add_f32_e32 v32, v95, v32
	v_pk_fma_f32 v[96:97], v[96:97], s[52:53], v[58:59] op_sel_hi:[1,0,1]
	v_lshlrev_b32_e32 v36, 16, v37
	v_and_b32_e32 v37, 0xffff0000, v37
	v_add_f32_e32 v32, v32, v96
	v_pk_fma_f32 v[80:81], v[98:99], s[52:53], v[80:81] op_sel_hi:[1,0,1]
	v_add_f32_e32 v32, v97, v32
	v_pk_fma_f32 v[98:99], v[36:37], s[52:53], v[54:55] op_sel_hi:[1,0,1]
	v_pk_fma_f32 v[84:85], v[100:101], s[52:53], v[84:85] op_sel_hi:[1,0,1]
	v_add_f32_e32 v32, v98, v32
	v_add_f32_e32 v32, v99, v32
	v_add_f32_e32 v32, v81, v32
	v_add_f32_e32 v32, v80, v32
	v_add_f32_e32 v32, v85, v32
	v_add_f32_e32 v32, v84, v32
	v_mov_b32_e32 v33, v32
	v_pk_add_f32 v[54:55], v[76:77], v[38:39] op_sel_hi:[1,0] neg_lo:[0,1] neg_hi:[0,1]
	v_pk_add_f32 v[56:57], v[74:75], v[38:39] op_sel_hi:[1,0] neg_lo:[0,1] neg_hi:[0,1]
	v_pk_mul_f32 v[76:77], v[54:55], v[54:55]
	v_pk_mul_f32 v[74:75], v[56:57], v[56:57]
	s_waitcnt lgkmcnt(0)
	s_nop 1
	v_permlane32_swap_b32_e32 v32, v33
	v_add_f32_e32 v32, v32, v33
	v_mov_b32_e32 v33, v32
	v_add_f32_e32 v76, v76, v77
	v_pk_add_f32 v[58:59], v[72:73], v[38:39] op_sel_hi:[1,0] neg_lo:[0,1] neg_hi:[0,1]
	v_add_f32_e32 v74, v74, v76
	v_pk_mul_f32 v[72:73], v[58:59], v[58:59]
	s_waitcnt lgkmcnt(0)
	s_nop 1
	v_permlane16_swap_b32_e32 v32, v33
	v_add_f32_e32 v36, v32, v33
	v_add_f32_e32 v74, v75, v74
	v_add_f32_e32 v72, v72, v74
	v_pk_add_f32 v[68:69], v[70:71], v[38:39] op_sel_hi:[1,0] neg_lo:[0,1] neg_hi:[0,1]
	v_add_f32_e32 v72, v73, v72
	s_waitcnt lgkmcnt(0)
	s_nop 1
	v_add_f32_dpp v41, v36, v36 row_ror:8 row_mask:0xf bank_mask:0xf
	v_pk_mul_f32 v[70:71], v[68:69], v[68:69]
	v_pk_add_f32 v[32:33], v[66:67], v[38:39] op_sel_hi:[1,0] neg_lo:[0,1] neg_hi:[0,1]
	v_add_f32_e32 v70, v70, v72
	v_pk_mul_f32 v[66:67], v[32:33], v[32:33]
	s_waitcnt lgkmcnt(0)
	s_nop 1
	v_add_f32_dpp v41, v41, v41 row_ror:4 row_mask:0xf bank_mask:0xf
	v_add_f32_e32 v70, v71, v70
	v_pk_add_f32 v[34:35], v[64:65], v[38:39] op_sel_hi:[1,0] neg_lo:[0,1] neg_hi:[0,1]
	v_pk_add_f32 v[36:37], v[62:63], v[38:39] op_sel_hi:[1,0] neg_lo:[0,1] neg_hi:[0,1]
	v_pk_mul_f32 v[64:65], v[34:35], v[34:35]
	s_waitcnt lgkmcnt(0)
	s_nop 1
	v_add_f32_dpp v41, v41, v41 row_ror:2 row_mask:0xf bank_mask:0xf
	v_add_f32_e32 v93, v66, v70
	v_pk_mul_f32 v[62:63], v[36:37], v[36:37]
	v_pk_add_f32 v[38:39], v[60:61], v[38:39] op_sel_hi:[1,0] neg_lo:[0,1] neg_hi:[0,1]
	s_waitcnt lgkmcnt(0)
	s_nop 1
	v_add_f32_dpp v41, v41, v41 row_ror:1 row_mask:0xf bank_mask:0xf
	v_mul_f32_e32 v66, 0x3a800000, v41
	v_pk_add_f32 v[70:71], v[82:83], v[66:67] op_sel_hi:[1,0] neg_lo:[0,1] neg_hi:[0,1]
	v_pk_add_f32 v[74:75], v[78:79], v[66:67] op_sel_hi:[1,0] neg_lo:[0,1] neg_hi:[0,1]
	v_pk_mul_f32 v[72:73], v[70:71], v[70:71]
	v_pk_mul_f32 v[76:77], v[74:75], v[74:75]
	v_add_f32_e32 v41, v72, v73
	v_pk_add_f32 v[78:79], v[86:87], v[66:67] op_sel_hi:[1,0] neg_lo:[0,1] neg_hi:[0,1]
	v_add_f32_e32 v41, v76, v41
	v_pk_mul_f32 v[82:83], v[78:79], v[78:79]
	v_add_f32_e32 v41, v77, v41
	v_pk_add_f32 v[86:87], v[94:95], v[66:67] op_sel_hi:[1,0] neg_lo:[0,1] neg_hi:[0,1]
	v_add_f32_e32 v41, v82, v41
	v_pk_mul_f32 v[94:95], v[86:87], v[86:87]
	v_add_f32_e32 v41, v83, v41
	v_pk_add_f32 v[96:97], v[96:97], v[66:67] op_sel_hi:[1,0] neg_lo:[0,1] neg_hi:[0,1]
	v_add_f32_e32 v41, v94, v41
	v_pk_mul_f32 v[100:101], v[96:97], v[96:97]
	v_add_f32_e32 v41, v95, v41
	v_pk_add_f32 v[98:99], v[98:99], v[66:67] op_sel_hi:[1,0] neg_lo:[0,1] neg_hi:[0,1]
	v_add_f32_e32 v41, v100, v41
	v_pk_mul_f32 v[102:103], v[98:99], v[98:99]
	v_add_f32_e32 v41, v101, v41
	v_pk_add_f32 v[80:81], v[80:81], v[66:67] op_sel_hi:[1,0] neg_lo:[0,1] neg_hi:[0,1]
	v_add_f32_e32 v41, v102, v41
	v_pk_mul_f32 v[104:105], v[80:81], v[80:81]
	v_add_f32_e32 v41, v103, v41
	v_pk_add_f32 v[84:85], v[84:85], v[66:67] op_sel_hi:[1,0] neg_lo:[0,1] neg_hi:[0,1]
	v_add_f32_e32 v41, v105, v41
	v_pk_mul_f32 v[106:107], v[84:85], v[84:85]
	v_add_f32_e32 v41, v104, v41
	v_add_f32_e32 v41, v107, v41
	v_add_f32_e32 v41, v106, v41
	v_mov_b32_e32 v66, v41
	v_add_f32_e32 v67, v67, v93
	v_add_f32_e32 v64, v64, v67
	v_add_f32_e32 v64, v65, v64
	v_add_f32_e32 v62, v62, v64
	s_waitcnt lgkmcnt(0)
; DI void stf8(float* p, const F8& f) { *(float4*)p = make_float4(f.v[0], f.v[1], f.v[2], f.v[3]); *(float4*)(p + 4) = make_float4(f.v[4], f.v[5], f.v[6], f.v[7]); }
; DI void stb8(bf16_t* p, const F8& f) { *(uint4*)p = pack8(f); }
; DI float wsum(float v) { v += __shfl_xor(v, 32); v += __shfl_xor(v, 16); v += __shfl_xor(v, 8); v += __shfl_xor(v, 4); v += __shfl_xor(v, 2); v += __shfl_xor(v, 1); return v; }
; DI void ln_phase(const Params& p, const bf16_t* __restrict__ Y, const float* __restrict__ g, const float* __restrict__ b, bool final_out) {
;     ...
;         const float mu0 = wsum(s0) * (1.f / 1024.f), mu1 = wsum(s1) * (1.f / 1024.f);
;         float q0 = 0.f, q1 = 0.f;
; #pragma unroll
;         for (int e = 0; e < 16; ++e) { const float d0 = v[0][e] - mu0, d1 = v[1][e] - mu1; q0 += d0 * d0; q1 += d1 * d1; }
;         const float rs0 = rsqrtf(wsum(q0) * (1.f / 1024.f) + EPS), rs1 = rsqrtf(wsum(q1) * (1.f / 1024.f) + EPS);
; #pragma unroll
;         for (int q = 0; q < 2; ++q) {
;             if (q == 1 && !two) break;
;             const float mu = q ? mu1 : mu0, rs = q ? rs1 : rs0;
; #pragma unroll
;             for (int it = 0; it < 2; ++it) {
;                 const int c = it * 512 + lane * 8;
;                 F8 o;
; #pragma unroll
;                 for (int e = 0; e < 8; ++e) o.v[e] = (v[q][it * 8 + e] - mu) * rs * gg[it].v[e] + bb[it].v[e];
;                 if (final_out) stf8(p.out + (size_t)rr[q] * 1024 + c, o);
;                 else stb8(XB + (size_t)rr[q] * 1024 + c, o);
;             }
;         }
	s_nop 1
	v_permlane32_swap_b32_e32 v41, v66
	v_add_f32_e32 v41, v41, v66
	v_mov_b32_e32 v64, v41
	v_pk_mul_f32 v[60:61], v[38:39], v[38:39]
	v_add_f32_e32 v62, v63, v62
	v_add_f32_e32 v60, v60, v62
	v_add_f32_e32 v60, v61, v60
	s_waitcnt lgkmcnt(0)
	s_nop 1
	v_permlane16_swap_b32_e32 v41, v64
	v_add_f32_e32 v41, v41, v64
	v_mov_b32_e32 v61, v60
	s_waitcnt lgkmcnt(1)
	s_nop 1
	v_add_f32_dpp v41, v41, v41 row_ror:8 row_mask:0xf bank_mask:0xf
	s_waitcnt lgkmcnt(1)
	s_nop 1
	v_permlane32_swap_b32_e32 v60, v61
	v_add_f32_e32 v60, v60, v61
	v_mov_b32_e32 v61, v60
	s_waitcnt lgkmcnt(1)
	s_nop 1
	v_add_f32_dpp v41, v41, v41 row_ror:4 row_mask:0xf bank_mask:0xf
	s_waitcnt lgkmcnt(1)
	s_nop 1
	v_permlane16_swap_b32_e32 v60, v61
	v_add_f32_e32 v60, v60, v61
	s_waitcnt lgkmcnt(1)
	s_nop 1
	v_add_f32_dpp v41, v41, v41 row_ror:2 row_mask:0xf bank_mask:0xf
	s_waitcnt lgkmcnt(1)
	s_nop 1
	v_add_f32_dpp v60, v60, v60 row_ror:8 row_mask:0xf bank_mask:0xf
	s_waitcnt lgkmcnt(1)
	s_nop 1
	v_add_f32_dpp v41, v41, v41 row_ror:1 row_mask:0xf bank_mask:0xf
	v_mov_b32_e32 v62, 0x358637bd
	v_fmamk_f32 v41, v41, 0x3a800000, v62
	s_waitcnt lgkmcnt(0)
	s_nop 1
	v_add_f32_dpp v60, v60, v60 row_ror:4 row_mask:0xf bank_mask:0xf
	v_mul_f32_e32 v62, 0x4b800000, v41
	v_cmp_gt_f32_e32 vcc, s2, v41
	s_nop 0
	v_cndmask_b32_e32 v41, v41, v62, vcc
	v_rsq_f32_e32 v62, v41
	s_waitcnt lgkmcnt(0)
	s_nop 1
	v_add_f32_dpp v41, v60, v60 row_ror:2 row_mask:0xf bank_mask:0xf
	ds_bpermute_b32 v60, v92, v41
	v_mul_f32_e32 v61, 0x45800000, v62
	v_cndmask_b32_e32 v66, v62, v61, vcc
	v_pk_mul_f32 v[62:63], v[70:71], v[66:67] op_sel_hi:[1,0]
	v_pk_mul_f32 v[64:65], v[74:75], v[66:67] op_sel_hi:[1,0]
	v_pk_mul_f32 v[70:71], v[78:79], v[66:67] op_sel_hi:[1,0]
	v_pk_mul_f32 v[72:73], v[86:87], v[66:67] op_sel_hi:[1,0]
	v_pk_fma_f32 v[62:63], v[4:5], v[62:63], v[12:13]
	v_pk_fma_f32 v[64:65], v[6:7], v[64:65], v[14:15]
	v_pk_fma_f32 v[70:71], v[0:1], v[70:71], v[8:9]
	v_pk_fma_f32 v[72:73], v[2:3], v[72:73], v[10:11]
	v_cvt_pk_bf16_f32 v62, v62, v63
	v_cvt_pk_bf16_f32 v63, v64, v65
	v_cvt_pk_bf16_f32 v64, v70, v71
	v_cvt_pk_bf16_f32 v65, v72, v73
	global_store_dwordx4 v[50:51], v[62:65], off
	v_pk_mul_f32 v[50:51], v[96:97], v[66:67] op_sel_hi:[1,0]
	s_nop 0
	v_pk_mul_f32 v[62:63], v[98:99], v[66:67] op_sel_hi:[1,0]
	v_pk_fma_f32 v[50:51], v[20:21], v[50:51], v[28:29]
	v_pk_fma_f32 v[64:65], v[22:23], v[62:63], v[30:31]
	v_pk_mul_f32 v[62:63], v[80:81], v[66:67] op_sel_hi:[1,0]
	s_nop 0
	v_pk_fma_f32 v[70:71], v[16:17], v[62:63], v[24:25] op_sel:[0,1,0] op_sel_hi:[1,0,1]
	v_pk_mul_f32 v[62:63], v[84:85], v[66:67] op_sel_hi:[1,0]
	s_nop 0
	v_pk_fma_f32 v[66:67], v[18:19], v[62:63], v[26:27] op_sel:[0,1,0] op_sel_hi:[1,0,1]
	v_cvt_pk_bf16_f32 v62, v50, v51
	v_cvt_pk_bf16_f32 v63, v64, v65
	v_cvt_pk_bf16_f32 v64, v70, v71
	v_cvt_pk_bf16_f32 v65, v66, v67
	global_store_dwordx4 v[52:53], v[62:65], off offset:-3072
	s_and_saveexec_b64 s[22:23], s[36:37]
	s_cbranch_execz .LBB0_1084
	s_waitcnt lgkmcnt(0)
	v_add_f32_e32 v41, v41, v60
	v_mov_b32_e32 v50, 0x358637bd
	v_fmamk_f32 v41, v41, 0x3a800000, v50
	v_mul_f32_e32 v50, 0x4b800000, v41
	v_cmp_gt_f32_e32 vcc, s2, v41
	v_lshl_add_u64 v[60:61], v[44:45], 0, v[48:49]
	s_nop 0
	v_cndmask_b32_e32 v41, v41, v50, vcc
	v_rsq_f32_e32 v41, v41
	s_nop 0
	v_mul_f32_e32 v50, 0x45800000, v41
	v_cndmask_b32_e32 v52, v41, v50, vcc
	v_pk_mul_f32 v[50:51], v[54:55], v[52:53] op_sel_hi:[1,0]
	v_pk_mul_f32 v[54:55], v[56:57], v[52:53] op_sel_hi:[1,0]
	v_pk_mul_f32 v[56:57], v[58:59], v[52:53] op_sel_hi:[1,0]
	v_pk_mul_f32 v[58:59], v[68:69], v[52:53] op_sel_hi:[1,0]
	v_pk_mul_f32 v[32:33], v[32:33], v[52:53] op_sel_hi:[1,0]
	v_pk_mul_f32 v[34:35], v[34:35], v[52:53] op_sel_hi:[1,0]
	v_pk_mul_f32 v[36:37], v[36:37], v[52:53] op_sel_hi:[1,0]
	v_pk_mul_f32 v[38:39], v[38:39], v[52:53] op_sel_hi:[1,0]
	v_pk_fma_f32 v[50:51], v[4:5], v[50:51], v[12:13]
	v_pk_fma_f32 v[54:55], v[6:7], v[54:55], v[14:15]
	v_pk_fma_f32 v[56:57], v[0:1], v[56:57], v[8:9]
	v_pk_fma_f32 v[58:59], v[2:3], v[58:59], v[10:11]
	v_pk_fma_f32 v[32:33], v[20:21], v[32:33], v[28:29]
	v_pk_fma_f32 v[34:35], v[22:23], v[34:35], v[30:31]
	v_pk_fma_f32 v[36:37], v[16:17], v[36:37], v[24:25]
	v_pk_fma_f32 v[38:39], v[18:19], v[38:39], v[26:27]
	v_cvt_pk_bf16_f32 v48, v50, v51
	v_cvt_pk_bf16_f32 v49, v54, v55
	v_cvt_pk_bf16_f32 v50, v56, v57
	v_cvt_pk_bf16_f32 v51, v58, v59
	v_cvt_pk_bf16_f32 v32, v32, v33
	v_cvt_pk_bf16_f32 v33, v34, v35
	v_cvt_pk_bf16_f32 v34, v36, v37
	v_cvt_pk_bf16_f32 v35, v38, v39
	global_store_dwordx4 v[60:61], v[48:51], off
	global_store_dwordx4 v[60:61], v[32:35], off offset:1024
	s_branch .LBB0_1084

; DI void stf8(float* p, const F8& f) { *(float4*)p = make_float4(f.v[0], f.v[1], f.v[2], f.v[3]); *(float4*)(p + 4) = make_float4(f.v[4], f.v[5], f.v[6], f.v[7]); }
; DI void stb8(bf16_t* p, const F8& f) { *(uint4*)p = pack8(f); }
; DI float siluf(float x) { return x / (1.f + __expf(-x)); }
; template <int MODE>
; DI void gemm_epilogue(const float* Cs, int m0, int n0, const Epi& ep) {
;     ...
;         const int mt = m0 >> 7, ch0 = (n0 >> 7) * 64, c8 = (tid & 7) * 8, ch = ch0 + c8;
;         const float* cw = ep.c0;
;         const F8 w0 = ldf8(cw + ch), w1 = ldf8(cw + 2816 + ch), w2 = ldf8(cw + 2 * 2816 + ch);
;         const bool defer01 = (m0 < MP) && ((m0 & 8191) != 0);
; #pragma unroll
;         for (int it = 0; it < 2; ++it) {
;             const int i = (tid >> 3) + 64 * it, r = m0 + i;
;             int sq, pos, len; rowinfo(r, sq, pos, len);
;             const F8 g0 = ldf8(Cs + i * LDC + c8), up = ldf8(Cs + i * LDC + 64 + c8);
;             if (i >= 126) stf8(ep.f0 + ((size_t)mt * 2 + (i - 126)) * 2816 + ch, g0);
;             if (i < 2) { stf8(ep.f1 + ((size_t)mt * 2 + i) * 2816 + ch, g0); stf8(ep.f2 + ((size_t)mt * 2 + i) * 2816 + ch, up); }
;             if (pos >= len - 2) {
;                 float* so = sq < 4 ? ep.out + O_PFF + (((size_t)ep.layer * 4 + sq) * 2 + (pos - (len - 2))) * 2816
;                                    : ep.out + O_SFF + (((size_t)ep.layer * 8 + (sq - 4)) * 2 + (pos - (len - 2))) * 2816;
;                 stf8(so + ch, g0);
;             }
;             if (i < 2 && defer01) continue;
;             F8 g1, g2;
;             const float* hist = sq >= 4 ? ep.c1 + ((size_t)ep.layer * 8 + (sq - 4)) * 2 * 2816 + ch : nullptr;
;             if (pos >= 1) g1 = ldf8(Cs + (i - 1) * LDC + c8);
;             else if (hist) g1 = ldf8(hist + 2816);
;             else { for (int e = 0; e < 8; ++e) g1.v[e] = 0.f; }
;             if (pos >= 2) g2 = ldf8(Cs + (i - 2) * LDC + c8);
;             else if (hist) g2 = ldf8(hist + (size_t)pos * 2816);
;             else { for (int e = 0; e < 8; ++e) g2.v[e] = 0.f; }
;             F8 o;
; #pragma unroll
;             for (int e = 0; e < 8; ++e) o.v[e] = siluf(w0.v[e] * g2.v[e] + w1.v[e] * g1.v[e] + w2.v[e] * g0.v[e]) * up.v[e];
;             stb8(ep.b0 + (size_t)r * 2816 + ch, o);
.Lffn_fast:
	s_lshl_b32 s54, s27, 8
	s_lshl_b32 s30, s26, 7
	s_lshl_b32 s31, s27, 2
	v_lshrrev_b32_e32 v195, 3, v250
	v_and_b32_e32 v212, 7, v250
	v_lshlrev_b32_e32 v212, 3, v212
	v_add_u32_e32 v64, s30, v212
	v_add_u32_e32 v65, s54, v195
	s_movk_i32 s0, 0x1600
	v_add_u32_e32 v66, s31, v195
	v_mul_lo_u32 v65, v65, s0
	v_mul_lo_u32 v66, v66, s3
	v_mul_u32_u24_e32 v197, 0x210, v195
	v_lshl_add_u32 v65, v64, 1, v65
	v_lshlrev_b32_e32 v64, 2, v64
	v_lshl_add_u32 v67, v212, 2, 16
	v_add_u32_e32 v66, v66, v64
	v_add_u32_e32 v197, v197, v67
	v_cmp_lt_u32_e64 s[40:41], 1, v195
	v_cmp_gt_u32_e64 s[42:43], 2, v195
	v_cmp_lt_u32_e64 s[44:45], 61, v195
	v_add_u32_e32 v196, 0xfffffbe0, v197
	v_max_i32_e32 v196, v196, v67
	global_load_dwordx4 v[128:131], v64, s[6:7] offset:0
	global_load_dwordx4 v[132:135], v64, s[6:7] offset:16
	global_load_dwordx4 v[136:139], v64, s[14:15] offset:0
	global_load_dwordx4 v[140:143], v64, s[14:15] offset:16
	global_load_dwordx4 v[144:147], v64, s[18:19] offset:0
	global_load_dwordx4 v[148:151], v64, s[18:19] offset:16
	ds_write_b128 v194, v[96:99]
	ds_write_b128 v194, v[100:103] offset:64
	ds_write_b128 v194, v[104:107] offset:8448
	ds_write_b128 v194, v[108:111] offset:8512
	ds_write_b128 v194, v[112:115] offset:16896
	ds_write_b128 v194, v[116:119] offset:16960
	ds_write_b128 v194, v[120:123] offset:25344
	ds_write_b128 v194, v[124:127] offset:25408
	s_waitcnt lgkmcnt(0)
	s_barrier
	ds_read_b128 v[96:99], v197
	ds_read_b128 v[100:103], v197 offset:16
	ds_read_b128 v[104:107], v197 offset:256
	ds_read_b128 v[108:111], v197 offset:272
	ds_read_b128 v[112:115], v196 offset:528
	ds_read_b128 v[116:119], v196 offset:544
	ds_read_b128 v[120:123], v196
	ds_read_b128 v[124:127], v196 offset:16
	s_waitcnt vmcnt(0)
	s_mov_b64 exec, s[42:43]
	s_cbranch_execz .Lffn_f1
	s_waitcnt lgkmcnt(4)
	global_store_dwordx4 v66, v[96:99], s[80:81] offset:0
	global_store_dwordx4 v66, v[100:103], s[80:81] offset:16
	global_store_dwordx4 v66, v[104:107], s[82:83] offset:0
	global_store_dwordx4 v66, v[108:111], s[82:83] offset:16
.Lffn_f1:
	s_mov_b64 exec, -1
	s_waitcnt lgkmcnt(0)
	v_pk_mul_f32 v[120:121], v[128:129], v[120:121]
	v_pk_mul_f32 v[122:123], v[130:131], v[122:123]
	v_pk_mul_f32 v[124:125], v[132:133], v[124:125]
	v_pk_mul_f32 v[126:127], v[134:135], v[126:127]
	v_pk_fma_f32 v[120:121], v[136:137], v[112:113], v[120:121]
	v_pk_fma_f32 v[122:123], v[138:139], v[114:115], v[122:123]
	v_pk_fma_f32 v[124:125], v[140:141], v[116:117], v[124:125]
	v_pk_fma_f32 v[126:127], v[142:143], v[118:119], v[126:127]
	v_pk_fma_f32 v[120:121], v[144:145], v[96:97], v[120:121]
	v_pk_fma_f32 v[122:123], v[146:147], v[98:99], v[122:123]
	v_pk_fma_f32 v[124:125], v[148:149], v[100:101], v[124:125]
	v_pk_fma_f32 v[126:127], v[150:151], v[102:103], v[126:127]
	v_mul_f32_e32 v152, 0xbfb8aa3b, v120
	v_mul_f32_e32 v153, 0xbfb8aa3b, v121
	v_mul_f32_e32 v154, 0xbfb8aa3b, v122
	v_mul_f32_e32 v155, 0xbfb8aa3b, v123
	v_mul_f32_e32 v164, 0xbfb8aa3b, v124
	v_mul_f32_e32 v165, 0xbfb8aa3b, v125
	v_mul_f32_e32 v166, 0xbfb8aa3b, v126
	v_mul_f32_e32 v167, 0xbfb8aa3b, v127
	v_exp_f32_e32 v152, v152
	v_exp_f32_e32 v153, v153
	v_exp_f32_e32 v154, v154
	v_exp_f32_e32 v155, v155
	v_exp_f32_e32 v164, v164
	v_exp_f32_e32 v165, v165
	v_exp_f32_e32 v166, v166
	v_exp_f32_e32 v167, v167
	v_pk_add_f32 v[152:153], v[152:153], 1.0 op_sel_hi:[1,0]
	v_pk_add_f32 v[154:155], v[154:155], 1.0 op_sel_hi:[1,0]
	v_pk_add_f32 v[164:165], v[164:165], 1.0 op_sel_hi:[1,0]
	v_pk_add_f32 v[166:167], v[166:167], 1.0 op_sel_hi:[1,0]
	v_rcp_f32_e32 v152, v152
	v_rcp_f32_e32 v153, v153
	v_rcp_f32_e32 v154, v154
	v_rcp_f32_e32 v155, v155
	v_rcp_f32_e32 v164, v164
	v_rcp_f32_e32 v165, v165
	v_rcp_f32_e32 v166, v166
	v_rcp_f32_e32 v167, v167
	v_mul_f32_e32 v120, v120, v152
	v_mul_f32_e32 v121, v121, v153
	v_mul_f32_e32 v122, v122, v154
	v_mul_f32_e32 v123, v123, v155
	v_mul_f32_e32 v124, v124, v164
	v_mul_f32_e32 v125, v125, v165
	v_mul_f32_e32 v126, v126, v166
	v_mul_f32_e32 v127, v127, v167
	v_pk_mul_f32 v[120:121], v[104:105], v[120:121]
	v_pk_mul_f32 v[122:123], v[106:107], v[122:123]
	v_pk_mul_f32 v[124:125], v[108:109], v[124:125]
	v_pk_mul_f32 v[126:127], v[110:111], v[126:127]
	v_cvt_pk_bf16_f32 v152, v120, v121
	v_cvt_pk_bf16_f32 v153, v122, v123
	v_cvt_pk_bf16_f32 v154, v124, v125
	v_cvt_pk_bf16_f32 v155, v126, v127
	s_mov_b64 exec, s[40:41]
	global_store_dwordx4 v65, v[152:155], s[84:85] offset:0
	s_mov_b64 exec, -1
	ds_read_b128 v[96:99], v197 offset:33792
	ds_read_b128 v[100:103], v197 offset:33808
	ds_read_b128 v[104:107], v197 offset:34048
	ds_read_b128 v[108:111], v197 offset:34064
	ds_read_b128 v[112:115], v197 offset:33264
	ds_read_b128 v[116:119], v197 offset:33280
	ds_read_b128 v[120:123], v197 offset:32736
	ds_read_b128 v[124:127], v197 offset:32752
	v_add_u32_e32 v67, 0x58000, v65
	s_mov_b64 exec, s[44:45]
	s_cbranch_execz .Lffn_f2
	v_add_u32_e32 v212, 0xfff55800, v66
	s_waitcnt lgkmcnt(6)
	global_store_dwordx4 v212, v[96:99], s[72:73] offset:0
	global_store_dwordx4 v212, v[100:103], s[72:73] offset:16
; DI void stf8(float* p, const F8& f) { *(float4*)p = make_float4(f.v[0], f.v[1], f.v[2], f.v[3]); *(float4*)(p + 4) = make_float4(f.v[4], f.v[5], f.v[6], f.v[7]); }
; DI void stb8(bf16_t* p, const F8& f) { *(uint4*)p = pack8(f); }
; DI float siluf(float x) { return x / (1.f + __expf(-x)); }
; template <int MODE>
; DI void gemm_epilogue(const float* Cs, int m0, int n0, const Epi& ep) {
;     ...
;         const int mt = m0 >> 7, ch0 = (n0 >> 7) * 64, c8 = (tid & 7) * 8, ch = ch0 + c8;
;         const float* cw = ep.c0;
;         const F8 w0 = ldf8(cw + ch), w1 = ldf8(cw + 2816 + ch), w2 = ldf8(cw + 2 * 2816 + ch);
;         const bool defer01 = (m0 < MP) && ((m0 & 8191) != 0);
; #pragma unroll
;         for (int it = 0; it < 2; ++it) {
;             const int i = (tid >> 3) + 64 * it, r = m0 + i;
;             int sq, pos, len; rowinfo(r, sq, pos, len);
;             const F8 g0 = ldf8(Cs + i * LDC + c8), up = ldf8(Cs + i * LDC + 64 + c8);
;             if (i >= 126) stf8(ep.f0 + ((size_t)mt * 2 + (i - 126)) * 2816 + ch, g0);
;             if (i < 2) { stf8(ep.f1 + ((size_t)mt * 2 + i) * 2816 + ch, g0); stf8(ep.f2 + ((size_t)mt * 2 + i) * 2816 + ch, up); }
;             if (pos >= len - 2) {
;                 float* so = sq < 4 ? ep.out + O_PFF + (((size_t)ep.layer * 4 + sq) * 2 + (pos - (len - 2))) * 2816
;                                    : ep.out + O_SFF + (((size_t)ep.layer * 8 + (sq - 4)) * 2 + (pos - (len - 2))) * 2816;
;                 stf8(so + ch, g0);
;             }
;             if (i < 2 && defer01) continue;
;             F8 g1, g2;
;             const float* hist = sq >= 4 ? ep.c1 + ((size_t)ep.layer * 8 + (sq - 4)) * 2 * 2816 + ch : nullptr;
;             if (pos >= 1) g1 = ldf8(Cs + (i - 1) * LDC + c8);
;             else if (hist) g1 = ldf8(hist + 2816);
;             else { for (int e = 0; e < 8; ++e) g1.v[e] = 0.f; }
;             if (pos >= 2) g2 = ldf8(Cs + (i - 2) * LDC + c8);
;             else if (hist) g2 = ldf8(hist + (size_t)pos * 2816);
;             else { for (int e = 0; e < 8; ++e) g2.v[e] = 0.f; }
;             F8 o;
; #pragma unroll
;             for (int e = 0; e < 8; ++e) o.v[e] = siluf(w0.v[e] * g2.v[e] + w1.v[e] * g1.v[e] + w2.v[e] * g0.v[e]) * up.v[e];
;             stb8(ep.b0 + (size_t)r * 2816 + ch, o);
.Lffn_f2:
	s_mov_b64 exec, -1
	s_waitcnt lgkmcnt(0)
	v_pk_mul_f32 v[120:121], v[128:129], v[120:121]
	v_pk_mul_f32 v[122:123], v[130:131], v[122:123]
	v_pk_mul_f32 v[124:125], v[132:133], v[124:125]
	v_pk_mul_f32 v[126:127], v[134:135], v[126:127]
	v_pk_fma_f32 v[120:121], v[136:137], v[112:113], v[120:121]
	v_pk_fma_f32 v[122:123], v[138:139], v[114:115], v[122:123]
	v_pk_fma_f32 v[124:125], v[140:141], v[116:117], v[124:125]
	v_pk_fma_f32 v[126:127], v[142:143], v[118:119], v[126:127]
	v_pk_fma_f32 v[120:121], v[144:145], v[96:97], v[120:121]
	v_pk_fma_f32 v[122:123], v[146:147], v[98:99], v[122:123]
	v_pk_fma_f32 v[124:125], v[148:149], v[100:101], v[124:125]
	v_pk_fma_f32 v[126:127], v[150:151], v[102:103], v[126:127]
	v_mul_f32_e32 v152, 0xbfb8aa3b, v120
	v_mul_f32_e32 v153, 0xbfb8aa3b, v121
	v_mul_f32_e32 v154, 0xbfb8aa3b, v122
	v_mul_f32_e32 v155, 0xbfb8aa3b, v123
	v_mul_f32_e32 v164, 0xbfb8aa3b, v124
	v_mul_f32_e32 v165, 0xbfb8aa3b, v125
	v_mul_f32_e32 v166, 0xbfb8aa3b, v126
	v_mul_f32_e32 v167, 0xbfb8aa3b, v127
	v_exp_f32_e32 v152, v152
	v_exp_f32_e32 v153, v153
	v_exp_f32_e32 v154, v154
	v_exp_f32_e32 v155, v155
	v_exp_f32_e32 v164, v164
	v_exp_f32_e32 v165, v165
	v_exp_f32_e32 v166, v166
	v_exp_f32_e32 v167, v167
	v_pk_add_f32 v[152:153], v[152:153], 1.0 op_sel_hi:[1,0]
	v_pk_add_f32 v[154:155], v[154:155], 1.0 op_sel_hi:[1,0]
	v_pk_add_f32 v[164:165], v[164:165], 1.0 op_sel_hi:[1,0]
	v_pk_add_f32 v[166:167], v[166:167], 1.0 op_sel_hi:[1,0]
	v_rcp_f32_e32 v152, v152
	v_rcp_f32_e32 v153, v153
	v_rcp_f32_e32 v154, v154
	v_rcp_f32_e32 v155, v155
	v_rcp_f32_e32 v164, v164
	v_rcp_f32_e32 v165, v165
	v_rcp_f32_e32 v166, v166
	v_rcp_f32_e32 v167, v167
	v_mul_f32_e32 v120, v120, v152
	v_mul_f32_e32 v121, v121, v153
	v_mul_f32_e32 v122, v122, v154
	v_mul_f32_e32 v123, v123, v155
	v_mul_f32_e32 v124, v124, v164
	v_mul_f32_e32 v125, v125, v165
	v_mul_f32_e32 v126, v126, v166
	v_mul_f32_e32 v127, v127, v167
	v_pk_mul_f32 v[120:121], v[104:105], v[120:121]
	v_pk_mul_f32 v[122:123], v[106:107], v[122:123]
	v_pk_mul_f32 v[124:125], v[108:109], v[124:125]
	v_pk_mul_f32 v[126:127], v[110:111], v[126:127]
	v_cvt_pk_bf16_f32 v152, v120, v121
	v_cvt_pk_bf16_f32 v153, v122, v123
	v_cvt_pk_bf16_f32 v154, v124, v125
	v_cvt_pk_bf16_f32 v155, v126, v127
	global_store_dwordx4 v67, v[152:155], s[84:85] offset:0
	global_load_dwordx4 v[128:131], v64, s[6:7] offset:256
	global_load_dwordx4 v[132:135], v64, s[6:7] offset:272
	global_load_dwordx4 v[136:139], v64, s[14:15] offset:256
	global_load_dwordx4 v[140:143], v64, s[14:15] offset:272
	global_load_dwordx4 v[144:147], v64, s[18:19] offset:256
	global_load_dwordx4 v[148:151], v64, s[18:19] offset:272
	s_barrier
	ds_write_b128 v194, v[222:225]
	ds_write_b128 v194, v[68:71] offset:64
	ds_write_b128 v194, v[72:75] offset:8448
	ds_write_b128 v194, v[76:79] offset:8512
	ds_write_b128 v194, v[80:83] offset:16896
	ds_write_b128 v194, v[84:87] offset:16960
	ds_write_b128 v194, v[88:91] offset:25344
	ds_write_b128 v194, v[92:95] offset:25408
	s_waitcnt lgkmcnt(0)
	s_barrier
	ds_read_b128 v[96:99], v197
	ds_read_b128 v[100:103], v197 offset:16
	ds_read_b128 v[104:107], v197 offset:256
	ds_read_b128 v[108:111], v197 offset:272
	ds_read_b128 v[112:115], v196 offset:528
	ds_read_b128 v[116:119], v196 offset:544
	ds_read_b128 v[120:123], v196
	ds_read_b128 v[124:127], v196 offset:16
	s_waitcnt vmcnt(0)
	s_mov_b64 exec, s[42:43]
	s_cbranch_execz .Lffn_f3
	s_waitcnt lgkmcnt(4)
	global_store_dwordx4 v66, v[96:99], s[80:81] offset:256
	global_store_dwordx4 v66, v[100:103], s[80:81] offset:272
	global_store_dwordx4 v66, v[104:107], s[82:83] offset:256
	global_store_dwordx4 v66, v[108:111], s[82:83] offset:272
.Lffn_f3:
	s_mov_b64 exec, -1
	s_waitcnt lgkmcnt(0)
	v_pk_mul_f32 v[120:121], v[128:129], v[120:121]
	v_pk_mul_f32 v[122:123], v[130:131], v[122:123]
	v_pk_mul_f32 v[124:125], v[132:133], v[124:125]
	v_pk_mul_f32 v[126:127], v[134:135], v[126:127]
	v_pk_fma_f32 v[120:121], v[136:137], v[112:113], v[120:121]
	v_pk_fma_f32 v[122:123], v[138:139], v[114:115], v[122:123]
	v_pk_fma_f32 v[124:125], v[140:141], v[116:117], v[124:125]
	v_pk_fma_f32 v[126:127], v[142:143], v[118:119], v[126:127]
	v_pk_fma_f32 v[120:121], v[144:145], v[96:97], v[120:121]
	v_pk_fma_f32 v[122:123], v[146:147], v[98:99], v[122:123]
	v_pk_fma_f32 v[124:125], v[148:149], v[100:101], v[124:125]
	v_pk_fma_f32 v[126:127], v[150:151], v[102:103], v[126:127]
	v_mul_f32_e32 v152, 0xbfb8aa3b, v120
	v_mul_f32_e32 v153, 0xbfb8aa3b, v121
	v_mul_f32_e32 v154, 0xbfb8aa3b, v122
	v_mul_f32_e32 v155, 0xbfb8aa3b, v123
	v_mul_f32_e32 v164, 0xbfb8aa3b, v124
	v_mul_f32_e32 v165, 0xbfb8aa3b, v125
	v_mul_f32_e32 v166, 0xbfb8aa3b, v126
	v_mul_f32_e32 v167, 0xbfb8aa3b, v127
	v_exp_f32_e32 v152, v152
	v_exp_f32_e32 v153, v153
	v_exp_f32_e32 v154, v154
	v_exp_f32_e32 v155, v155
	v_exp_f32_e32 v164, v164
	v_exp_f32_e32 v165, v165
	v_exp_f32_e32 v166, v166
	v_exp_f32_e32 v167, v167
	v_pk_add_f32 v[152:153], v[152:153], 1.0 op_sel_hi:[1,0]
	v_pk_add_f32 v[154:155], v[154:155], 1.0 op_sel_hi:[1,0]
	v_pk_add_f32 v[164:165], v[164:165], 1.0 op_sel_hi:[1,0]
	v_pk_add_f32 v[166:167], v[166:167], 1.0 op_sel_hi:[1,0]
	v_rcp_f32_e32 v152, v152
	v_rcp_f32_e32 v153, v153
	v_rcp_f32_e32 v154, v154
	v_rcp_f32_e32 v155, v155
	v_rcp_f32_e32 v164, v164
	v_rcp_f32_e32 v165, v165
	v_rcp_f32_e32 v166, v166
	v_rcp_f32_e32 v167, v167
	v_mul_f32_e32 v120, v120, v152
	v_mul_f32_e32 v121, v121, v153
	v_mul_f32_e32 v122, v122, v154
	v_mul_f32_e32 v123, v123, v155
	v_mul_f32_e32 v124, v124, v164
	v_mul_f32_e32 v125, v125, v165
	v_mul_f32_e32 v126, v126, v166
	v_mul_f32_e32 v127, v127, v167
	v_pk_mul_f32 v[120:121], v[104:105], v[120:121]
	v_pk_mul_f32 v[122:123], v[106:107], v[122:123]
	v_pk_mul_f32 v[124:125], v[108:109], v[124:125]
	v_pk_mul_f32 v[126:127], v[110:111], v[126:127]
	v_cvt_pk_bf16_f32 v152, v120, v121
	v_cvt_pk_bf16_f32 v153, v122, v123
	v_cvt_pk_bf16_f32 v154, v124, v125
	v_cvt_pk_bf16_f32 v155, v126, v127
	s_mov_b64 exec, s[40:41]
	global_store_dwordx4 v65, v[152:155], s[84:85] offset:128
	s_mov_b64 exec, -1
	ds_read_b128 v[96:99], v197 offset:33792
	ds_read_b128 v[100:103], v197 offset:33808
	ds_read_b128 v[104:107], v197 offset:34048
	ds_read_b128 v[108:111], v197 offset:34064
	ds_read_b128 v[112:115], v197 offset:33264
	ds_read_b128 v[116:119], v197 offset:33280
	ds_read_b128 v[120:123], v197 offset:32736
	ds_read_b128 v[124:127], v197 offset:32752
	v_add_u32_e32 v67, 0x58000, v65
	s_mov_b64 exec, s[44:45]
	s_cbranch_execz .Lffn_f4
	v_add_u32_e32 v212, 0xfff55800, v66
	s_waitcnt lgkmcnt(6)
	global_store_dwordx4 v212, v[96:99], s[72:73] offset:256
	global_store_dwordx4 v212, v[100:103], s[72:73] offset:272
; DI void stf8(float* p, const F8& f) { *(float4*)p = make_float4(f.v[0], f.v[1], f.v[2], f.v[3]); *(float4*)(p + 4) = make_float4(f.v[4], f.v[5], f.v[6], f.v[7]); }
; DI void stb8(bf16_t* p, const F8& f) { *(uint4*)p = pack8(f); }
; DI float siluf(float x) { return x / (1.f + __expf(-x)); }
; template <int MODE>
; DI void gemm_epilogue(const float* Cs, int m0, int n0, const Epi& ep) {
;     ...
;         const int mt = m0 >> 7, ch0 = (n0 >> 7) * 64, c8 = (tid & 7) * 8, ch = ch0 + c8;
;         const float* cw = ep.c0;
;         const F8 w0 = ldf8(cw + ch), w1 = ldf8(cw + 2816 + ch), w2 = ldf8(cw + 2 * 2816 + ch);
;         const bool defer01 = (m0 < MP) && ((m0 & 8191) != 0);
; #pragma unroll
;         for (int it = 0; it < 2; ++it) {
;             const int i = (tid >> 3) + 64 * it, r = m0 + i;
;             int sq, pos, len; rowinfo(r, sq, pos, len);
;             const F8 g0 = ldf8(Cs + i * LDC + c8), up = ldf8(Cs + i * LDC + 64 + c8);
;             if (i >= 126) stf8(ep.f0 + ((size_t)mt * 2 + (i - 126)) * 2816 + ch, g0);
;             if (i < 2) { stf8(ep.f1 + ((size_t)mt * 2 + i) * 2816 + ch, g0); stf8(ep.f2 + ((size_t)mt * 2 + i) * 2816 + ch, up); }
;             if (pos >= len - 2) {
;                 float* so = sq < 4 ? ep.out + O_PFF + (((size_t)ep.layer * 4 + sq) * 2 + (pos - (len - 2))) * 2816
;                                    : ep.out + O_SFF + (((size_t)ep.layer * 8 + (sq - 4)) * 2 + (pos - (len - 2))) * 2816;
;                 stf8(so + ch, g0);
;             }
;             if (i < 2 && defer01) continue;
;             F8 g1, g2;
;             const float* hist = sq >= 4 ? ep.c1 + ((size_t)ep.layer * 8 + (sq - 4)) * 2 * 2816 + ch : nullptr;
;             if (pos >= 1) g1 = ldf8(Cs + (i - 1) * LDC + c8);
;             else if (hist) g1 = ldf8(hist + 2816);
;             else { for (int e = 0; e < 8; ++e) g1.v[e] = 0.f; }
;             if (pos >= 2) g2 = ldf8(Cs + (i - 2) * LDC + c8);
;             else if (hist) g2 = ldf8(hist + (size_t)pos * 2816);
;             else { for (int e = 0; e < 8; ++e) g2.v[e] = 0.f; }
;             F8 o;
; #pragma unroll
;             for (int e = 0; e < 8; ++e) o.v[e] = siluf(w0.v[e] * g2.v[e] + w1.v[e] * g1.v[e] + w2.v[e] * g0.v[e]) * up.v[e];
;             stb8(ep.b0 + (size_t)r * 2816 + ch, o);
.Lffn_f4:
	s_mov_b64 exec, -1
	s_waitcnt lgkmcnt(0)
	v_pk_mul_f32 v[120:121], v[128:129], v[120:121]
	v_pk_mul_f32 v[122:123], v[130:131], v[122:123]
	v_pk_mul_f32 v[124:125], v[132:133], v[124:125]
	v_pk_mul_f32 v[126:127], v[134:135], v[126:127]
	v_pk_fma_f32 v[120:121], v[136:137], v[112:113], v[120:121]
	v_pk_fma_f32 v[122:123], v[138:139], v[114:115], v[122:123]
	v_pk_fma_f32 v[124:125], v[140:141], v[116:117], v[124:125]
	v_pk_fma_f32 v[126:127], v[142:143], v[118:119], v[126:127]
	v_pk_fma_f32 v[120:121], v[144:145], v[96:97], v[120:121]
	v_pk_fma_f32 v[122:123], v[146:147], v[98:99], v[122:123]
	v_pk_fma_f32 v[124:125], v[148:149], v[100:101], v[124:125]
	v_pk_fma_f32 v[126:127], v[150:151], v[102:103], v[126:127]
	v_mul_f32_e32 v152, 0xbfb8aa3b, v120
	v_mul_f32_e32 v153, 0xbfb8aa3b, v121
	v_mul_f32_e32 v154, 0xbfb8aa3b, v122
	v_mul_f32_e32 v155, 0xbfb8aa3b, v123
	v_mul_f32_e32 v164, 0xbfb8aa3b, v124
	v_mul_f32_e32 v165, 0xbfb8aa3b, v125
	v_mul_f32_e32 v166, 0xbfb8aa3b, v126
	v_mul_f32_e32 v167, 0xbfb8aa3b, v127
	v_exp_f32_e32 v152, v152
	v_exp_f32_e32 v153, v153
	v_exp_f32_e32 v154, v154
	v_exp_f32_e32 v155, v155
	v_exp_f32_e32 v164, v164
	v_exp_f32_e32 v165, v165
	v_exp_f32_e32 v166, v166
	v_exp_f32_e32 v167, v167
	v_pk_add_f32 v[152:153], v[152:153], 1.0 op_sel_hi:[1,0]
	v_pk_add_f32 v[154:155], v[154:155], 1.0 op_sel_hi:[1,0]
	v_pk_add_f32 v[164:165], v[164:165], 1.0 op_sel_hi:[1,0]
	v_pk_add_f32 v[166:167], v[166:167], 1.0 op_sel_hi:[1,0]
	v_rcp_f32_e32 v152, v152
	v_rcp_f32_e32 v153, v153
	v_rcp_f32_e32 v154, v154
	v_rcp_f32_e32 v155, v155
	v_rcp_f32_e32 v164, v164
	v_rcp_f32_e32 v165, v165
	v_rcp_f32_e32 v166, v166
	v_rcp_f32_e32 v167, v167
	v_mul_f32_e32 v120, v120, v152
	v_mul_f32_e32 v121, v121, v153
	v_mul_f32_e32 v122, v122, v154
	v_mul_f32_e32 v123, v123, v155
	v_mul_f32_e32 v124, v124, v164
	v_mul_f32_e32 v125, v125, v165
	v_mul_f32_e32 v126, v126, v166
	v_mul_f32_e32 v127, v127, v167
	v_pk_mul_f32 v[120:121], v[104:105], v[120:121]
	v_pk_mul_f32 v[122:123], v[106:107], v[122:123]
	v_pk_mul_f32 v[124:125], v[108:109], v[124:125]
	v_pk_mul_f32 v[126:127], v[110:111], v[126:127]
	v_cvt_pk_bf16_f32 v152, v120, v121
	v_cvt_pk_bf16_f32 v153, v122, v123
	v_cvt_pk_bf16_f32 v154, v124, v125
	v_cvt_pk_bf16_f32 v155, v126, v127
	global_store_dwordx4 v67, v[152:155], s[84:85] offset:128
	global_load_dwordx4 v[128:131], v64, s[6:7] offset:0
	global_load_dwordx4 v[132:135], v64, s[6:7] offset:16
	global_load_dwordx4 v[136:139], v64, s[14:15] offset:0
	global_load_dwordx4 v[140:143], v64, s[14:15] offset:16
	global_load_dwordx4 v[144:147], v64, s[18:19] offset:0
	global_load_dwordx4 v[148:151], v64, s[18:19] offset:16
	s_barrier
	ds_write_b128 v194, v[32:35]
	ds_write_b128 v194, v[36:39] offset:64
	ds_write_b128 v194, v[40:43] offset:8448
	ds_write_b128 v194, v[44:47] offset:8512
	ds_write_b128 v194, v[48:51] offset:16896
	ds_write_b128 v194, v[52:55] offset:16960
	ds_write_b128 v194, v[56:59] offset:25344
	ds_write_b128 v194, v[60:63] offset:25408
	s_waitcnt lgkmcnt(0)
	s_barrier
	ds_read_b128 v[96:99], v197
	ds_read_b128 v[100:103], v197 offset:16
	ds_read_b128 v[104:107], v197 offset:256
	ds_read_b128 v[108:111], v197 offset:272
	ds_read_b128 v[112:115], v196 offset:528
	ds_read_b128 v[116:119], v196 offset:544
	ds_read_b128 v[120:123], v196
	ds_read_b128 v[124:127], v196 offset:16
	v_add_u32_e32 v67, 0xb0000, v65
	s_waitcnt vmcnt(0)
	s_mov_b64 exec, s[42:43]
	s_cbranch_execz .Lffn_f5
	v_add_u32_e32 v212, 0x5800, v66
	s_waitcnt lgkmcnt(4)
	global_store_dwordx4 v212, v[96:99], s[80:81] offset:0
	global_store_dwordx4 v212, v[100:103], s[80:81] offset:16
	global_store_dwordx4 v212, v[104:107], s[82:83] offset:0
	global_store_dwordx4 v212, v[108:111], s[82:83] offset:16
.Lffn_f5:
	s_mov_b64 exec, -1
	s_waitcnt lgkmcnt(0)
	v_pk_mul_f32 v[120:121], v[128:129], v[120:121]
	v_pk_mul_f32 v[122:123], v[130:131], v[122:123]
	v_pk_mul_f32 v[124:125], v[132:133], v[124:125]
	v_pk_mul_f32 v[126:127], v[134:135], v[126:127]
	v_pk_fma_f32 v[120:121], v[136:137], v[112:113], v[120:121]
	v_pk_fma_f32 v[122:123], v[138:139], v[114:115], v[122:123]
	v_pk_fma_f32 v[124:125], v[140:141], v[116:117], v[124:125]
	v_pk_fma_f32 v[126:127], v[142:143], v[118:119], v[126:127]
	v_pk_fma_f32 v[120:121], v[144:145], v[96:97], v[120:121]
	v_pk_fma_f32 v[122:123], v[146:147], v[98:99], v[122:123]
	v_pk_fma_f32 v[124:125], v[148:149], v[100:101], v[124:125]
	v_pk_fma_f32 v[126:127], v[150:151], v[102:103], v[126:127]
	v_mul_f32_e32 v152, 0xbfb8aa3b, v120
	v_mul_f32_e32 v153, 0xbfb8aa3b, v121
	v_mul_f32_e32 v154, 0xbfb8aa3b, v122
	v_mul_f32_e32 v155, 0xbfb8aa3b, v123
	v_mul_f32_e32 v164, 0xbfb8aa3b, v124
	v_mul_f32_e32 v165, 0xbfb8aa3b, v125
	v_mul_f32_e32 v166, 0xbfb8aa3b, v126
	v_mul_f32_e32 v167, 0xbfb8aa3b, v127
	v_exp_f32_e32 v152, v152
	v_exp_f32_e32 v153, v153
	v_exp_f32_e32 v154, v154
	v_exp_f32_e32 v155, v155
	v_exp_f32_e32 v164, v164
	v_exp_f32_e32 v165, v165
	v_exp_f32_e32 v166, v166
	v_exp_f32_e32 v167, v167
	v_pk_add_f32 v[152:153], v[152:153], 1.0 op_sel_hi:[1,0]
	v_pk_add_f32 v[154:155], v[154:155], 1.0 op_sel_hi:[1,0]
	v_pk_add_f32 v[164:165], v[164:165], 1.0 op_sel_hi:[1,0]
	v_pk_add_f32 v[166:167], v[166:167], 1.0 op_sel_hi:[1,0]
	v_rcp_f32_e32 v152, v152
	v_rcp_f32_e32 v153, v153
	v_rcp_f32_e32 v154, v154
	v_rcp_f32_e32 v155, v155
	v_rcp_f32_e32 v164, v164
	v_rcp_f32_e32 v165, v165
	v_rcp_f32_e32 v166, v166
	v_rcp_f32_e32 v167, v167
	v_mul_f32_e32 v120, v120, v152
	v_mul_f32_e32 v121, v121, v153
	v_mul_f32_e32 v122, v122, v154
	v_mul_f32_e32 v123, v123, v155
	v_mul_f32_e32 v124, v124, v164
	v_mul_f32_e32 v125, v125, v165
	v_mul_f32_e32 v126, v126, v166
	v_mul_f32_e32 v127, v127, v167
	v_pk_mul_f32 v[120:121], v[104:105], v[120:121]
	v_pk_mul_f32 v[122:123], v[106:107], v[122:123]
	v_pk_mul_f32 v[124:125], v[108:109], v[124:125]
	v_pk_mul_f32 v[126:127], v[110:111], v[126:127]
	v_cvt_pk_bf16_f32 v152, v120, v121
	v_cvt_pk_bf16_f32 v153, v122, v123
	v_cvt_pk_bf16_f32 v154, v124, v125
	v_cvt_pk_bf16_f32 v155, v126, v127
	s_mov_b64 exec, s[40:41]
	global_store_dwordx4 v67, v[152:155], s[84:85] offset:0
	s_mov_b64 exec, -1
	ds_read_b128 v[96:99], v197 offset:33792
	ds_read_b128 v[100:103], v197 offset:33808
	ds_read_b128 v[104:107], v197 offset:34048
	ds_read_b128 v[108:111], v197 offset:34064
	ds_read_b128 v[112:115], v197 offset:33264
	ds_read_b128 v[116:119], v197 offset:33280
	ds_read_b128 v[120:123], v197 offset:32736
	ds_read_b128 v[124:127], v197 offset:32752
	v_add_u32_e32 v67, 0x108000, v65
	s_mov_b64 exec, s[44:45]
	s_cbranch_execz .Lffn_f6
	v_add_u32_e32 v212, 0xfff5b000, v66
	s_waitcnt lgkmcnt(6)
	global_store_dwordx4 v212, v[96:99], s[72:73] offset:0
	global_store_dwordx4 v212, v[100:103], s[72:73] offset:16
; DI void stf8(float* p, const F8& f) { *(float4*)p = make_float4(f.v[0], f.v[1], f.v[2], f.v[3]); *(float4*)(p + 4) = make_float4(f.v[4], f.v[5], f.v[6], f.v[7]); }
; DI void stb8(bf16_t* p, const F8& f) { *(uint4*)p = pack8(f); }
; DI float siluf(float x) { return x / (1.f + __expf(-x)); }
; template <int MODE>
; DI void gemm_epilogue(const float* Cs, int m0, int n0, const Epi& ep) {
;     ...
;         const int mt = m0 >> 7, ch0 = (n0 >> 7) * 64, c8 = (tid & 7) * 8, ch = ch0 + c8;
;         const float* cw = ep.c0;
;         const F8 w0 = ldf8(cw + ch), w1 = ldf8(cw + 2816 + ch), w2 = ldf8(cw + 2 * 2816 + ch);
;         const bool defer01 = (m0 < MP) && ((m0 & 8191) != 0);
; #pragma unroll
;         for (int it = 0; it < 2; ++it) {
;             const int i = (tid >> 3) + 64 * it, r = m0 + i;
;             int sq, pos, len; rowinfo(r, sq, pos, len);
;             const F8 g0 = ldf8(Cs + i * LDC + c8), up = ldf8(Cs + i * LDC + 64 + c8);
;             if (i >= 126) stf8(ep.f0 + ((size_t)mt * 2 + (i - 126)) * 2816 + ch, g0);
;             if (i < 2) { stf8(ep.f1 + ((size_t)mt * 2 + i) * 2816 + ch, g0); stf8(ep.f2 + ((size_t)mt * 2 + i) * 2816 + ch, up); }
;             if (pos >= len - 2) {
;                 float* so = sq < 4 ? ep.out + O_PFF + (((size_t)ep.layer * 4 + sq) * 2 + (pos - (len - 2))) * 2816
;                                    : ep.out + O_SFF + (((size_t)ep.layer * 8 + (sq - 4)) * 2 + (pos - (len - 2))) * 2816;
;                 stf8(so + ch, g0);
;             }
;             if (i < 2 && defer01) continue;
;             F8 g1, g2;
;             const float* hist = sq >= 4 ? ep.c1 + ((size_t)ep.layer * 8 + (sq - 4)) * 2 * 2816 + ch : nullptr;
;             if (pos >= 1) g1 = ldf8(Cs + (i - 1) * LDC + c8);
;             else if (hist) g1 = ldf8(hist + 2816);
;             else { for (int e = 0; e < 8; ++e) g1.v[e] = 0.f; }
;             if (pos >= 2) g2 = ldf8(Cs + (i - 2) * LDC + c8);
;             else if (hist) g2 = ldf8(hist + (size_t)pos * 2816);
;             else { for (int e = 0; e < 8; ++e) g2.v[e] = 0.f; }
;             F8 o;
; #pragma unroll
;             for (int e = 0; e < 8; ++e) o.v[e] = siluf(w0.v[e] * g2.v[e] + w1.v[e] * g1.v[e] + w2.v[e] * g0.v[e]) * up.v[e];
;             stb8(ep.b0 + (size_t)r * 2816 + ch, o);
.Lffn_f6:
	s_mov_b64 exec, -1
	s_waitcnt lgkmcnt(0)
	v_pk_mul_f32 v[120:121], v[128:129], v[120:121]
	v_pk_mul_f32 v[122:123], v[130:131], v[122:123]
	v_pk_mul_f32 v[124:125], v[132:133], v[124:125]
	v_pk_mul_f32 v[126:127], v[134:135], v[126:127]
	v_pk_fma_f32 v[120:121], v[136:137], v[112:113], v[120:121]
	v_pk_fma_f32 v[122:123], v[138:139], v[114:115], v[122:123]
	v_pk_fma_f32 v[124:125], v[140:141], v[116:117], v[124:125]
	v_pk_fma_f32 v[126:127], v[142:143], v[118:119], v[126:127]
	v_pk_fma_f32 v[120:121], v[144:145], v[96:97], v[120:121]
	v_pk_fma_f32 v[122:123], v[146:147], v[98:99], v[122:123]
	v_pk_fma_f32 v[124:125], v[148:149], v[100:101], v[124:125]
	v_pk_fma_f32 v[126:127], v[150:151], v[102:103], v[126:127]
	v_mul_f32_e32 v152, 0xbfb8aa3b, v120
	v_mul_f32_e32 v153, 0xbfb8aa3b, v121
	v_mul_f32_e32 v154, 0xbfb8aa3b, v122
	v_mul_f32_e32 v155, 0xbfb8aa3b, v123
	v_mul_f32_e32 v164, 0xbfb8aa3b, v124
	v_mul_f32_e32 v165, 0xbfb8aa3b, v125
	v_mul_f32_e32 v166, 0xbfb8aa3b, v126
	v_mul_f32_e32 v167, 0xbfb8aa3b, v127
	v_exp_f32_e32 v152, v152
	v_exp_f32_e32 v153, v153
	v_exp_f32_e32 v154, v154
	v_exp_f32_e32 v155, v155
	v_exp_f32_e32 v164, v164
	v_exp_f32_e32 v165, v165
	v_exp_f32_e32 v166, v166
	v_exp_f32_e32 v167, v167
	v_pk_add_f32 v[152:153], v[152:153], 1.0 op_sel_hi:[1,0]
	v_pk_add_f32 v[154:155], v[154:155], 1.0 op_sel_hi:[1,0]
	v_pk_add_f32 v[164:165], v[164:165], 1.0 op_sel_hi:[1,0]
	v_pk_add_f32 v[166:167], v[166:167], 1.0 op_sel_hi:[1,0]
	v_rcp_f32_e32 v152, v152
	v_rcp_f32_e32 v153, v153
	v_rcp_f32_e32 v154, v154
	v_rcp_f32_e32 v155, v155
	v_rcp_f32_e32 v164, v164
	v_rcp_f32_e32 v165, v165
	v_rcp_f32_e32 v166, v166
	v_rcp_f32_e32 v167, v167
	v_mul_f32_e32 v120, v120, v152
	v_mul_f32_e32 v121, v121, v153
	v_mul_f32_e32 v122, v122, v154
	v_mul_f32_e32 v123, v123, v155
	v_mul_f32_e32 v124, v124, v164
	v_mul_f32_e32 v125, v125, v165
	v_mul_f32_e32 v126, v126, v166
	v_mul_f32_e32 v127, v127, v167
	v_pk_mul_f32 v[120:121], v[104:105], v[120:121]
	v_pk_mul_f32 v[122:123], v[106:107], v[122:123]
	v_pk_mul_f32 v[124:125], v[108:109], v[124:125]
	v_pk_mul_f32 v[126:127], v[110:111], v[126:127]
	v_cvt_pk_bf16_f32 v152, v120, v121
	v_cvt_pk_bf16_f32 v153, v122, v123
	v_cvt_pk_bf16_f32 v154, v124, v125
	v_cvt_pk_bf16_f32 v155, v126, v127
	global_store_dwordx4 v67, v[152:155], s[84:85] offset:0
	global_load_dwordx4 v[128:131], v64, s[6:7] offset:256
	global_load_dwordx4 v[132:135], v64, s[6:7] offset:272
	global_load_dwordx4 v[136:139], v64, s[14:15] offset:256
	global_load_dwordx4 v[140:143], v64, s[14:15] offset:272
	global_load_dwordx4 v[144:147], v64, s[18:19] offset:256
	global_load_dwordx4 v[148:151], v64, s[18:19] offset:272
	s_barrier
	ds_write_b128 v194, v[0:3]
	ds_write_b128 v194, v[4:7] offset:64
	ds_write_b128 v194, v[8:11] offset:8448
	ds_write_b128 v194, v[12:15] offset:8512
	ds_write_b128 v194, v[16:19] offset:16896
	ds_write_b128 v194, v[20:23] offset:16960
	ds_write_b128 v194, v[24:27] offset:25344
	ds_write_b128 v194, v[28:31] offset:25408
	s_waitcnt lgkmcnt(0)
	s_barrier
	ds_read_b128 v[96:99], v197
	ds_read_b128 v[100:103], v197 offset:16
	ds_read_b128 v[104:107], v197 offset:256
	ds_read_b128 v[108:111], v197 offset:272
	ds_read_b128 v[112:115], v196 offset:528
	ds_read_b128 v[116:119], v196 offset:544
	ds_read_b128 v[120:123], v196
	ds_read_b128 v[124:127], v196 offset:16
	v_add_u32_e32 v67, 0xb0000, v65
	s_waitcnt vmcnt(0)
	s_mov_b64 exec, s[42:43]
	s_cbranch_execz .Lffn_f7
	v_add_u32_e32 v212, 0x5800, v66
	s_waitcnt lgkmcnt(4)
	global_store_dwordx4 v212, v[96:99], s[80:81] offset:256
	global_store_dwordx4 v212, v[100:103], s[80:81] offset:272
	global_store_dwordx4 v212, v[104:107], s[82:83] offset:256
	global_store_dwordx4 v212, v[108:111], s[82:83] offset:272
; DI void stf8(float* p, const F8& f) { *(float4*)p = make_float4(f.v[0], f.v[1], f.v[2], f.v[3]); *(float4*)(p + 4) = make_float4(f.v[4], f.v[5], f.v[6], f.v[7]); }
; DI void stb8(bf16_t* p, const F8& f) { *(uint4*)p = pack8(f); }
; DI float siluf(float x) { return x / (1.f + __expf(-x)); }
; template <int MODE>
; DI void gemm_epilogue(const float* Cs, int m0, int n0, const Epi& ep) {
;     ...
;         const int mt = m0 >> 7, ch0 = (n0 >> 7) * 64, c8 = (tid & 7) * 8, ch = ch0 + c8;
;         const float* cw = ep.c0;
;         const F8 w0 = ldf8(cw + ch), w1 = ldf8(cw + 2816 + ch), w2 = ldf8(cw + 2 * 2816 + ch);
;         const bool defer01 = (m0 < MP) && ((m0 & 8191) != 0);
; #pragma unroll
;         for (int it = 0; it < 2; ++it) {
;             const int i = (tid >> 3) + 64 * it, r = m0 + i;
;             int sq, pos, len; rowinfo(r, sq, pos, len);
;             const F8 g0 = ldf8(Cs + i * LDC + c8), up = ldf8(Cs + i * LDC + 64 + c8);
;             if (i >= 126) stf8(ep.f0 + ((size_t)mt * 2 + (i - 126)) * 2816 + ch, g0);
;             if (i < 2) { stf8(ep.f1 + ((size_t)mt * 2 + i) * 2816 + ch, g0); stf8(ep.f2 + ((size_t)mt * 2 + i) * 2816 + ch, up); }
;             if (pos >= len - 2) {
;                 float* so = sq < 4 ? ep.out + O_PFF + (((size_t)ep.layer * 4 + sq) * 2 + (pos - (len - 2))) * 2816
;                                    : ep.out + O_SFF + (((size_t)ep.layer * 8 + (sq - 4)) * 2 + (pos - (len - 2))) * 2816;
;                 stf8(so + ch, g0);
;             }
;             if (i < 2 && defer01) continue;
;             F8 g1, g2;
;             const float* hist = sq >= 4 ? ep.c1 + ((size_t)ep.layer * 8 + (sq - 4)) * 2 * 2816 + ch : nullptr;
;             if (pos >= 1) g1 = ldf8(Cs + (i - 1) * LDC + c8);
;             else if (hist) g1 = ldf8(hist + 2816);
;             else { for (int e = 0; e < 8; ++e) g1.v[e] = 0.f; }
;             if (pos >= 2) g2 = ldf8(Cs + (i - 2) * LDC + c8);
;             else if (hist) g2 = ldf8(hist + (size_t)pos * 2816);
;             else { for (int e = 0; e < 8; ++e) g2.v[e] = 0.f; }
;             F8 o;
; #pragma unroll
;             for (int e = 0; e < 8; ++e) o.v[e] = siluf(w0.v[e] * g2.v[e] + w1.v[e] * g1.v[e] + w2.v[e] * g0.v[e]) * up.v[e];
;             stb8(ep.b0 + (size_t)r * 2816 + ch, o);
.Lffn_f7:
	s_mov_b64 exec, -1
	s_waitcnt lgkmcnt(0)
	v_pk_mul_f32 v[120:121], v[128:129], v[120:121]
	v_pk_mul_f32 v[122:123], v[130:131], v[122:123]
	v_pk_mul_f32 v[124:125], v[132:133], v[124:125]
	v_pk_mul_f32 v[126:127], v[134:135], v[126:127]
	v_pk_fma_f32 v[120:121], v[136:137], v[112:113], v[120:121]
	v_pk_fma_f32 v[122:123], v[138:139], v[114:115], v[122:123]
	v_pk_fma_f32 v[124:125], v[140:141], v[116:117], v[124:125]
	v_pk_fma_f32 v[126:127], v[142:143], v[118:119], v[126:127]
	v_pk_fma_f32 v[120:121], v[144:145], v[96:97], v[120:121]
	v_pk_fma_f32 v[122:123], v[146:147], v[98:99], v[122:123]
	v_pk_fma_f32 v[124:125], v[148:149], v[100:101], v[124:125]
	v_pk_fma_f32 v[126:127], v[150:151], v[102:103], v[126:127]
	v_mul_f32_e32 v152, 0xbfb8aa3b, v120
	v_mul_f32_e32 v153, 0xbfb8aa3b, v121
	v_mul_f32_e32 v154, 0xbfb8aa3b, v122
	v_mul_f32_e32 v155, 0xbfb8aa3b, v123
	v_mul_f32_e32 v164, 0xbfb8aa3b, v124
	v_mul_f32_e32 v165, 0xbfb8aa3b, v125
	v_mul_f32_e32 v166, 0xbfb8aa3b, v126
	v_mul_f32_e32 v167, 0xbfb8aa3b, v127
	v_exp_f32_e32 v152, v152
	v_exp_f32_e32 v153, v153
	v_exp_f32_e32 v154, v154
	v_exp_f32_e32 v155, v155
	v_exp_f32_e32 v164, v164
	v_exp_f32_e32 v165, v165
	v_exp_f32_e32 v166, v166
	v_exp_f32_e32 v167, v167
	v_pk_add_f32 v[152:153], v[152:153], 1.0 op_sel_hi:[1,0]
	v_pk_add_f32 v[154:155], v[154:155], 1.0 op_sel_hi:[1,0]
	v_pk_add_f32 v[164:165], v[164:165], 1.0 op_sel_hi:[1,0]
	v_pk_add_f32 v[166:167], v[166:167], 1.0 op_sel_hi:[1,0]
	v_rcp_f32_e32 v152, v152
	v_rcp_f32_e32 v153, v153
	v_rcp_f32_e32 v154, v154
	v_rcp_f32_e32 v155, v155
	v_rcp_f32_e32 v164, v164
	v_rcp_f32_e32 v165, v165
	v_rcp_f32_e32 v166, v166
	v_rcp_f32_e32 v167, v167
	v_mul_f32_e32 v120, v120, v152
	v_mul_f32_e32 v121, v121, v153
	v_mul_f32_e32 v122, v122, v154
	v_mul_f32_e32 v123, v123, v155
	v_mul_f32_e32 v124, v124, v164
	v_mul_f32_e32 v125, v125, v165
	v_mul_f32_e32 v126, v126, v166
	v_mul_f32_e32 v127, v127, v167
	v_pk_mul_f32 v[120:121], v[104:105], v[120:121]
	v_pk_mul_f32 v[122:123], v[106:107], v[122:123]
	v_pk_mul_f32 v[124:125], v[108:109], v[124:125]
	v_pk_mul_f32 v[126:127], v[110:111], v[126:127]
	v_cvt_pk_bf16_f32 v152, v120, v121
	v_cvt_pk_bf16_f32 v153, v122, v123
	v_cvt_pk_bf16_f32 v154, v124, v125
	v_cvt_pk_bf16_f32 v155, v126, v127
	s_mov_b64 exec, s[40:41]
	global_store_dwordx4 v67, v[152:155], s[84:85] offset:128
	s_mov_b64 exec, -1
	ds_read_b128 v[96:99], v197 offset:33792
	ds_read_b128 v[100:103], v197 offset:33808
	ds_read_b128 v[104:107], v197 offset:34048
	ds_read_b128 v[108:111], v197 offset:34064
	ds_read_b128 v[112:115], v197 offset:33264
	ds_read_b128 v[116:119], v197 offset:33280
	ds_read_b128 v[120:123], v197 offset:32736
	ds_read_b128 v[124:127], v197 offset:32752
	v_add_u32_e32 v67, 0x108000, v65
	s_mov_b64 exec, s[44:45]
	s_cbranch_execz .Lffn_f8
	v_add_u32_e32 v212, 0xfff5b000, v66
	s_waitcnt lgkmcnt(6)
	global_store_dwordx4 v212, v[96:99], s[72:73] offset:256
	global_store_dwordx4 v212, v[100:103], s[72:73] offset:272
.Lffn_f8:
	s_mov_b64 exec, -1
	s_waitcnt lgkmcnt(0)
	v_pk_mul_f32 v[120:121], v[128:129], v[120:121]
	v_pk_mul_f32 v[122:123], v[130:131], v[122:123]
	v_pk_mul_f32 v[124:125], v[132:133], v[124:125]
	v_pk_mul_f32 v[126:127], v[134:135], v[126:127]
	v_pk_fma_f32 v[120:121], v[136:137], v[112:113], v[120:121]
	v_pk_fma_f32 v[122:123], v[138:139], v[114:115], v[122:123]
	v_pk_fma_f32 v[124:125], v[140:141], v[116:117], v[124:125]
	v_pk_fma_f32 v[126:127], v[142:143], v[118:119], v[126:127]
	v_pk_fma_f32 v[120:121], v[144:145], v[96:97], v[120:121]
	v_pk_fma_f32 v[122:123], v[146:147], v[98:99], v[122:123]
	v_pk_fma_f32 v[124:125], v[148:149], v[100:101], v[124:125]
	v_pk_fma_f32 v[126:127], v[150:151], v[102:103], v[126:127]
	v_mul_f32_e32 v152, 0xbfb8aa3b, v120
	v_mul_f32_e32 v153, 0xbfb8aa3b, v121
	v_mul_f32_e32 v154, 0xbfb8aa3b, v122
	v_mul_f32_e32 v155, 0xbfb8aa3b, v123
	v_mul_f32_e32 v164, 0xbfb8aa3b, v124
	v_mul_f32_e32 v165, 0xbfb8aa3b, v125
	v_mul_f32_e32 v166, 0xbfb8aa3b, v126
	v_mul_f32_e32 v167, 0xbfb8aa3b, v127
	v_exp_f32_e32 v152, v152
	v_exp_f32_e32 v153, v153
	v_exp_f32_e32 v154, v154
	v_exp_f32_e32 v155, v155
	v_exp_f32_e32 v164, v164
	v_exp_f32_e32 v165, v165
	v_exp_f32_e32 v166, v166
	v_exp_f32_e32 v167, v167
	v_pk_add_f32 v[152:153], v[152:153], 1.0 op_sel_hi:[1,0]
	v_pk_add_f32 v[154:155], v[154:155], 1.0 op_sel_hi:[1,0]
	v_pk_add_f32 v[164:165], v[164:165], 1.0 op_sel_hi:[1,0]
	v_pk_add_f32 v[166:167], v[166:167], 1.0 op_sel_hi:[1,0]
	v_rcp_f32_e32 v152, v152
	v_rcp_f32_e32 v153, v153
	v_rcp_f32_e32 v154, v154
	v_rcp_f32_e32 v155, v155
	v_rcp_f32_e32 v164, v164
	v_rcp_f32_e32 v165, v165
	v_rcp_f32_e32 v166, v166
	v_rcp_f32_e32 v167, v167
	v_mul_f32_e32 v120, v120, v152
	v_mul_f32_e32 v121, v121, v153
	v_mul_f32_e32 v122, v122, v154
	v_mul_f32_e32 v123, v123, v155
	v_mul_f32_e32 v124, v124, v164
	v_mul_f32_e32 v125, v125, v165
	v_mul_f32_e32 v126, v126, v166
	v_mul_f32_e32 v127, v127, v167
	v_pk_mul_f32 v[120:121], v[104:105], v[120:121]
	v_pk_mul_f32 v[122:123], v[106:107], v[122:123]
	v_pk_mul_f32 v[124:125], v[108:109], v[124:125]
	v_pk_mul_f32 v[126:127], v[110:111], v[126:127]
	v_cvt_pk_bf16_f32 v152, v120, v121
	v_cvt_pk_bf16_f32 v153, v122, v123
	v_cvt_pk_bf16_f32 v154, v124, v125
	v_cvt_pk_bf16_f32 v155, v126, v127
	global_store_dwordx4 v67, v[152:155], s[84:85] offset:128
	s_mov_b64 s[0:1], -1
	s_branch .LBB0_1142

; DI void stf8(float* p, const F8& f) { *(float4*)p = make_float4(f.v[0], f.v[1], f.v[2], f.v[3]); *(float4*)(p + 4) = make_float4(f.v[4], f.v[5], f.v[6], f.v[7]); }
; DI void rowinfo(int r, int& sq, int& pos, int& len) { if (r < MP) { sq = r >> 13; pos = r & 8191; len = 8192; } else { sq = 4 + ((r - MP) >> 6); pos = r & 63; len = 64; } }
; template <int MODE>
; DI void gemm_epilogue(const float* Cs, int m0, int n0, const Epi& ep) {
;     ...
;         const int mt = m0 >> 7, ch0 = (n0 >> 7) * 64, c8 = (tid & 7) * 8, ch = ch0 + c8;
;         const float* cw = ep.c0;
;         const F8 w0 = ldf8(cw + ch), w1 = ldf8(cw + 2816 + ch), w2 = ldf8(cw + 2 * 2816 + ch);
;         const bool defer01 = (m0 < MP) && ((m0 & 8191) != 0);
; #pragma unroll
;         for (int it = 0; it < 2; ++it) {
;             const int i = (tid >> 3) + 64 * it, r = m0 + i;
;             int sq, pos, len; rowinfo(r, sq, pos, len);
;             const F8 g0 = ldf8(Cs + i * LDC + c8), up = ldf8(Cs + i * LDC + 64 + c8);
;             if (i >= 126) stf8(ep.f0 + ((size_t)mt * 2 + (i - 126)) * 2816 + ch, g0);
;             if (i < 2) { stf8(ep.f1 + ((size_t)mt * 2 + i) * 2816 + ch, g0); stf8(ep.f2 + ((size_t)mt * 2 + i) * 2816 + ch, up); }
; template <int MODE>
; DI void gemm_phase(const bf16_t* __restrict__ A, const bf16_t* __restrict__ Bt, int M, int N, int K, const Epi& ep) {
;     ...
;                         *(f32x4*)(Cs + (wr * 64 + m * 16 + fr) * LDC + wc * 32 + n * 16 + fq * 4) = acc[ai][bj][m][n];
;                 __syncthreads();
.LBB0_1153:
	s_or_b64 exec, exec, s[0:1]
	s_waitcnt vmcnt(0)
	s_barrier
	s_and_b32 s0, s27, 31
	s_add_i32 s0, s0, -1
	s_cmp_lt_u32 s0, 30
	s_cselect_b32 s0, 1, 0
	s_cmp_lt_u32 s27, 0x80
	s_cselect_b32 s1, 1, 0
	s_and_b32 s0, s0, s1
	s_cmp_lg_u32 s0, 0
	s_cbranch_scc1 .Lffn_fast
	ds_write_b128 v194, v[96:99]
	ds_write_b128 v194, v[100:103] offset:64
	ds_write_b128 v194, v[104:107] offset:8448
	ds_write_b128 v194, v[108:111] offset:8512
	ds_write_b128 v194, v[112:115] offset:16896
	ds_write_b128 v194, v[116:119] offset:16960
	ds_write_b128 v194, v[120:123] offset:25344
	ds_write_b128 v194, v[124:127] offset:25408
	v_mov_b32_e32 v120, v250
	s_waitcnt lgkmcnt(0)
	s_barrier
	s_lshl_b32 s26, s26, 7
	v_lshlrev_b32_e32 v64, 3, v120
	v_and_b32_e32 v195, 56, v64
	v_or_b32_e32 v152, s26, v195
	v_ashrrev_i32_e32 v153, 31, v152
	v_lshlrev_b64 v[154:155], 2, v[152:153]
	v_lshl_add_u64 v[64:65], s[6:7], 0, v[154:155]
	v_lshl_add_u64 v[116:117], s[18:19], 0, v[154:155]
	v_lshl_add_u64 v[66:67], s[14:15], 0, v[154:155]
	global_load_dwordx4 v[96:99], v[64:65], off offset:16
	global_load_dwordx4 v[108:111], v[64:65], off
	global_load_dwordx4 v[100:103], v[66:67], off offset:16
	global_load_dwordx4 v[112:115], v[66:67], off
	global_load_dwordx4 v[104:107], v[116:117], off offset:16
	s_nop 0
	global_load_dwordx4 v[116:119], v[116:117], off
	v_ashrrev_i32_e32 v164, 3, v120
	v_mul_lo_u32 v64, v164, s35
	v_add_u32_e32 v196, 16, v64
	v_lshl_add_u32 v64, v195, 2, v196
	ds_read_b128 v[132:135], v64
	ds_read_b128 v[124:127], v64 offset:16
	ds_read_b128 v[128:131], v64 offset:256
	ds_read_b128 v[120:123], v64 offset:272
	s_lshl_b32 s0, s27, 1
	s_ashr_i32 s1, s0, 31
	s_lshl_b64 s[30:31], s[0:1], 1
	v_cmp_lt_i32_e32 vcc, s71, v164
	s_and_saveexec_b64 s[0:1], vcc
	s_cbranch_execz .LBB0_1155
	v_add_u32_e32 v212, 0xffffff82, v164
	v_lshl_add_u64 v[64:65], s[30:31], 0, v[212:213]
	v_mov_b64_e32 v[66:67], s[72:73]
	v_mad_u64_u32 v[66:67], s[40:41], v64, s3, v[66:67]
	v_mad_i32_i24 v67, v65, s3, v67
	v_lshl_add_u64 v[64:65], v[152:153], 2, v[66:67]
	s_waitcnt lgkmcnt(3)
	global_store_dwordx4 v[64:65], v[132:135], off
	s_waitcnt lgkmcnt(2)
	global_store_dwordx4 v[64:65], v[124:127], off offset:16

; DI F8 unpack8(uint4 u) { F8 r; r.v[0] = lo16(u.x); r.v[1] = hi16(u.x); r.v[2] = lo16(u.y); r.v[3] = hi16(u.y); r.v[4] = lo16(u.z); r.v[5] = hi16(u.z); r.v[6] = lo16(u.w); r.v[7] = hi16(u.w); return r; }
; DI float wsum(float v) { v += __shfl_xor(v, 32); v += __shfl_xor(v, 16); v += __shfl_xor(v, 8); v += __shfl_xor(v, 4); v += __shfl_xor(v, 2); v += __shfl_xor(v, 1); return v; }
; DI void ln_phase(const Params& p, const bf16_t* __restrict__ Y, const float* __restrict__ g, const float* __restrict__ b, bool final_out) {
;     ...
;     for (int r0 = gw; r0 < MT; r0 += 2 * nw) {
;         const int r1 = r0 + nw; const bool two = r1 < MT; const int rr[2] = {r0, two ? r1 : r0};
;         uint4 xr[2][2], yr[2][2];
; #pragma unroll
;         for (int q = 0; q < 2; ++q)
; #pragma unroll
;             for (int it = 0; it < 2; ++it) { const size_t off = (size_t)rr[q] * 1024 + it * 512 + lane * 8; xr[q][it] = *(const uint4*)(XB + off); yr[q][it] = *(const uint4*)(Y + off); }
;         float v[2][16];
; #pragma unroll
;         for (int q = 0; q < 2; ++q)
; #pragma unroll
;             for (int it = 0; it < 2; ++it) { const F8 x = unpack8(xr[q][it]), y = unpack8(yr[q][it]);
; #pragma unroll
;                 for (int e = 0; e < 8; ++e) v[q][it * 8 + e] = ALPHA * x.v[e] + y.v[e]; }
;         float s0 = 0.f, s1 = 0.f;
; #pragma unroll
;         for (int e = 0; e < 16; ++e) { s0 += v[0][e]; s1 += v[1][e]; }
;         const float mu0 = wsum(s0) * (1.f / 1024.f), mu1 = wsum(s1) * (1.f / 1024.f);
.LBB0_1515:
	v_add_co_u32_e32 v50, vcc, 0xee400000, v46
	v_add_u32_e32 v41, s42, v40
	s_nop 0
	v_addc_co_u32_e32 v51, vcc, -1, v47, vcc
	global_load_dwordx4 v[54:57], v[50:51], off
	v_add_co_u32_e32 v50, vcc, 0xee401000, v46
	s_mov_b32 s15, 0x8200
	s_nop 0
	v_addc_co_u32_e32 v51, vcc, -1, v47, vcc
	v_cmp_gt_i32_e64 s[36:37], s15, v41
	global_load_dwordx4 v[58:61], v[50:51], off offset:-3072
	global_load_dwordx4 v[32:35], v[46:47], off
	global_load_dwordx4 v[36:39], v[46:47], off offset:1024
	v_cndmask_b32_e64 v50, v40, v41, s[36:37]
	v_ashrrev_i32_e32 v51, 31, v50
	v_lshlrev_b64 v[52:53], 11, v[50:51]
	v_lshl_or_b32 v70, v42, 1, v52
	v_mov_b32_e32 v71, v53
	v_mov_b32_e32 v75, v53
	v_or_b32_e32 v74, 0x400, v70
	v_lshl_add_u64 v[62:63], s[82:83], 0, v[70:71]
	v_lshl_add_u64 v[66:67], s[76:77], 0, v[70:71]
	v_lshl_add_u64 v[70:71], s[82:83], 0, v[74:75]
	v_lshl_add_u64 v[74:75], s[76:77], 0, v[74:75]
	global_load_dwordx4 v[62:65], v[62:63], off
	s_mov_b32 s30, 0x3a800000
	global_load_dwordx4 v[66:69], v[66:67], off
	s_waitcnt vmcnt(5)
	v_lshlrev_b32_e32 v90, 16, v54
	global_load_dwordx4 v[70:73], v[70:71], off
	v_and_b32_e32 v91, 0xffff0000, v54
	global_load_dwordx4 v[74:77], v[74:75], off
	v_lshlrev_b32_e32 v54, 16, v55
	v_and_b32_e32 v55, 0xffff0000, v55
	v_lshlrev_b32_e32 v92, 16, v56
	s_waitcnt vmcnt(6)
	v_lshlrev_b32_e32 v94, 16, v58
	s_waitcnt vmcnt(5)
	v_lshlrev_b32_e32 v78, 16, v32
	v_and_b32_e32 v79, 0xffff0000, v32
	s_waitcnt vmcnt(4)
	v_lshlrev_b32_e32 v88, 16, v36
	v_and_b32_e32 v89, 0xffff0000, v36
	v_lshlrev_b32_e32 v36, 16, v37
	v_and_b32_e32 v37, 0xffff0000, v37
	v_and_b32_e32 v95, 0xffff0000, v58
	v_lshlrev_b32_e32 v58, 16, v59
	v_and_b32_e32 v59, 0xffff0000, v59
	v_pk_fma_f32 v[78:79], v[90:91], s[52:53], v[78:79] op_sel_hi:[1,0,1]
	v_lshlrev_b32_e32 v32, 16, v33
	v_and_b32_e32 v33, 0xffff0000, v33
	v_pk_fma_f32 v[36:37], v[58:59], s[52:53], v[36:37] op_sel_hi:[1,0,1]
	s_waitcnt vmcnt(3)
	v_lshlrev_b32_e32 v98, 16, v62
	v_and_b32_e32 v99, 0xffff0000, v62
	s_waitcnt vmcnt(2)
	v_lshlrev_b32_e32 v102, 16, v66
	v_and_b32_e32 v103, 0xffff0000, v66
	v_lshlrev_b32_e32 v62, 16, v63
	v_and_b32_e32 v63, 0xffff0000, v63
	v_lshlrev_b32_e32 v66, 16, v67
	v_and_b32_e32 v67, 0xffff0000, v67
	v_pk_fma_f32 v[62:63], v[62:63], s[52:53], v[66:67] op_sel_hi:[1,0,1]
	v_lshlrev_b32_e32 v100, 16, v64
	v_and_b32_e32 v101, 0xffff0000, v64
	v_lshlrev_b32_e32 v104, 16, v68
	v_and_b32_e32 v105, 0xffff0000, v68
	v_pk_fma_f32 v[66:67], v[100:101], s[52:53], v[104:105] op_sel_hi:[1,0,1]
	v_lshlrev_b32_e32 v64, 16, v65
	v_and_b32_e32 v65, 0xffff0000, v65
	v_lshlrev_b32_e32 v68, 16, v69
	v_and_b32_e32 v69, 0xffff0000, v69
	v_add_f32_e32 v59, 0, v78
	v_add_f32_e32 v59, v79, v59
	v_pk_fma_f32 v[32:33], v[54:55], s[52:53], v[32:33] op_sel_hi:[1,0,1]
	v_lshlrev_b32_e32 v80, 16, v34
	v_and_b32_e32 v81, 0xffff0000, v34
	v_and_b32_e32 v93, 0xffff0000, v56
	v_add_f32_e32 v54, v32, v59
	v_add_f32_e32 v54, v33, v54
	v_pk_fma_f32 v[80:81], v[92:93], s[52:53], v[80:81] op_sel_hi:[1,0,1]
	v_lshlrev_b32_e32 v34, 16, v35
	v_and_b32_e32 v35, 0xffff0000, v35
	v_lshlrev_b32_e32 v56, 16, v57
	v_and_b32_e32 v57, 0xffff0000, v57
	v_add_f32_e32 v54, v80, v54
	v_add_f32_e32 v54, v81, v54
	v_pk_fma_f32 v[34:35], v[56:57], s[52:53], v[34:35] op_sel_hi:[1,0,1]
	v_pk_fma_f32 v[88:89], v[94:95], s[52:53], v[88:89] op_sel_hi:[1,0,1]
	v_add_f32_e32 v54, v34, v54
	v_add_f32_e32 v54, v35, v54
	v_add_f32_e32 v54, v54, v88
	v_add_f32_e32 v54, v89, v54
	v_lshlrev_b32_e32 v96, 16, v60
	v_and_b32_e32 v97, 0xffff0000, v60
	v_add_f32_e32 v54, v36, v54
	v_add_f32_e32 v54, v37, v54
	v_lshlrev_b32_e32 v60, 16, v61
	v_and_b32_e32 v61, 0xffff0000, v61
	s_waitcnt vmcnt(1)
	v_lshlrev_b32_e32 v108, 16, v72
	v_and_b32_e32 v109, 0xffff0000, v72
	v_lshlrev_b32_e32 v72, 16, v73
	v_and_b32_e32 v73, 0xffff0000, v73
	s_waitcnt vmcnt(0)
	v_lshlrev_b32_e32 v112, 16, v76
	v_and_b32_e32 v113, 0xffff0000, v76
	v_lshlrev_b32_e32 v76, 16, v77
	v_and_b32_e32 v77, 0xffff0000, v77
	v_pk_fma_f32 v[72:73], v[72:73], s[52:53], v[76:77] op_sel_hi:[1,0,1]
	v_pk_fma_f32 v[76:77], v[98:99], s[52:53], v[102:103] op_sel_hi:[1,0,1]
	v_pk_fma_f32 v[98:99], v[64:65], s[52:53], v[68:69] op_sel_hi:[1,0,1]
	v_add_f32_e32 v41, 0, v76
	v_add_f32_e32 v41, v77, v41
	v_add_f32_e32 v41, v62, v41
	v_add_f32_e32 v41, v63, v41
	v_add_f32_e32 v41, v66, v41
	v_add_f32_e32 v41, v67, v41
	v_lshlrev_b32_e32 v106, 16, v70
	v_and_b32_e32 v107, 0xffff0000, v70
	v_lshlrev_b32_e32 v110, 16, v74
	v_and_b32_e32 v111, 0xffff0000, v74
	v_add_f32_e32 v41, v98, v41
	v_pk_fma_f32 v[106:107], v[106:107], s[52:53], v[110:111] op_sel_hi:[1,0,1]
	v_add_f32_e32 v41, v99, v41
	v_lshlrev_b32_e32 v70, 16, v71
	v_and_b32_e32 v71, 0xffff0000, v71
	v_lshlrev_b32_e32 v74, 16, v75
	v_and_b32_e32 v75, 0xffff0000, v75
	v_add_f32_e32 v41, v41, v106
	v_pk_fma_f32 v[70:71], v[70:71], s[52:53], v[74:75] op_sel_hi:[1,0,1]
	v_add_f32_e32 v41, v107, v41
	v_add_f32_e32 v41, v70, v41
	v_pk_fma_f32 v[74:75], v[108:109], s[52:53], v[112:113] op_sel_hi:[1,0,1]
	v_add_f32_e32 v41, v71, v41
	v_add_f32_e32 v41, v74, v41
	v_add_f32_e32 v41, v75, v41
	v_add_f32_e32 v41, v72, v41
	v_add_f32_e32 v41, v73, v41
	v_mov_b32_e32 v68, v41
	v_lshlrev_b32_e32 v64, 16, v38
	v_and_b32_e32 v65, 0xffff0000, v38
	v_pk_fma_f32 v[94:95], v[96:97], s[52:53], v[64:65] op_sel_hi:[1,0,1]
	v_lshlrev_b32_e32 v38, 16, v39
	s_waitcnt lgkmcnt(0)
	s_nop 1
	v_permlane32_swap_b32_e32 v41, v68
	v_add_f32_e32 v41, v41, v68
	v_mov_b32_e32 v68, v41
	v_and_b32_e32 v39, 0xffff0000, v39
	v_add_f32_e32 v54, v94, v54
	v_pk_fma_f32 v[38:39], v[60:61], s[52:53], v[38:39] op_sel_hi:[1,0,1]
	v_add_f32_e32 v54, v95, v54
	s_waitcnt lgkmcnt(0)
; DI float wsum(float v) { v += __shfl_xor(v, 32); v += __shfl_xor(v, 16); v += __shfl_xor(v, 8); v += __shfl_xor(v, 4); v += __shfl_xor(v, 2); v += __shfl_xor(v, 1); return v; }
; DI void ln_phase(const Params& p, const bf16_t* __restrict__ Y, const float* __restrict__ g, const float* __restrict__ b, bool final_out) {
;     ...
;         const float mu0 = wsum(s0) * (1.f / 1024.f), mu1 = wsum(s1) * (1.f / 1024.f);
;         float q0 = 0.f, q1 = 0.f;
; #pragma unroll
;         for (int e = 0; e < 16; ++e) { const float d0 = v[0][e] - mu0, d1 = v[1][e] - mu1; q0 += d0 * d0; q1 += d1 * d1; }
;         const float rs0 = rsqrtf(wsum(q0) * (1.f / 1024.f) + EPS), rs1 = rsqrtf(wsum(q1) * (1.f / 1024.f) + EPS);
; #pragma unroll
;         for (int q = 0; q < 2; ++q) {
;             if (q == 1 && !two) break;
;             const float mu = q ? mu1 : mu0, rs = q ? rs1 : rs0;
; #pragma unroll
;             for (int it = 0; it < 2; ++it) {
;                 const int c = it * 512 + lane * 8;
;                 F8 o;
; #pragma unroll
;                 for (int e = 0; e < 8; ++e) o.v[e] = (v[q][it * 8 + e] - mu) * rs * gg[it].v[e] + bb[it].v[e];
	s_nop 1
	v_permlane16_swap_b32_e32 v41, v68
	v_add_f32_e32 v41, v41, v68
	v_add_f32_e32 v54, v38, v54
	v_add_f32_e32 v54, v39, v54
	v_mov_b32_e32 v55, v54
	s_waitcnt lgkmcnt(1)
	s_nop 1
	v_add_f32_dpp v41, v41, v41 row_ror:8 row_mask:0xf bank_mask:0xf
	s_waitcnt lgkmcnt(1)
	s_nop 1
	v_permlane32_swap_b32_e32 v54, v55
	v_add_f32_e32 v54, v54, v55
	v_mov_b32_e32 v55, v54
	s_waitcnt lgkmcnt(1)
	s_nop 1
	v_add_f32_dpp v41, v41, v41 row_ror:4 row_mask:0xf bank_mask:0xf
	s_waitcnt lgkmcnt(1)
	s_nop 1
	v_permlane16_swap_b32_e32 v54, v55
	v_add_f32_e32 v54, v54, v55
	s_waitcnt lgkmcnt(1)
	s_nop 1
	v_add_f32_dpp v41, v41, v41 row_ror:2 row_mask:0xf bank_mask:0xf
	s_waitcnt lgkmcnt(1)
	s_nop 1
	v_add_f32_dpp v54, v54, v54 row_ror:8 row_mask:0xf bank_mask:0xf
	s_waitcnt lgkmcnt(1)
	s_nop 1
	v_add_f32_dpp v41, v41, v41 row_ror:1 row_mask:0xf bank_mask:0xf
	v_mul_f32_e32 v60, 0x3a800000, v41
	s_waitcnt lgkmcnt(0)
	s_nop 1
	v_add_f32_dpp v41, v54, v54 row_ror:4 row_mask:0xf bank_mask:0xf
	v_pk_add_f32 v[54:55], v[70:71], v[60:61] op_sel_hi:[1,0] neg_lo:[0,1] neg_hi:[0,1]
	v_pk_add_f32 v[68:69], v[76:77], v[60:61] op_sel_hi:[1,0] neg_lo:[0,1] neg_hi:[0,1]
	v_pk_add_f32 v[64:65], v[62:63], v[60:61] op_sel_hi:[1,0] neg_lo:[0,1] neg_hi:[0,1]
	v_pk_add_f32 v[66:67], v[66:67], v[60:61] op_sel_hi:[1,0] neg_lo:[0,1] neg_hi:[0,1]
	s_waitcnt lgkmcnt(0)
	s_nop 1
	v_add_f32_dpp v41, v41, v41 row_ror:2 row_mask:0xf bank_mask:0xf
	v_pk_add_f32 v[62:63], v[98:99], v[60:61] op_sel_hi:[1,0] neg_lo:[0,1] neg_hi:[0,1]
	v_pk_add_f32 v[56:57], v[106:107], v[60:61] op_sel_hi:[1,0] neg_lo:[0,1] neg_hi:[0,1]
	v_pk_add_f32 v[58:59], v[74:75], v[60:61] op_sel_hi:[1,0] neg_lo:[0,1] neg_hi:[0,1]
	v_pk_add_f32 v[60:61], v[72:73], v[60:61] op_sel_hi:[1,0] neg_lo:[0,1] neg_hi:[0,1]
	s_waitcnt lgkmcnt(0)
	s_nop 1
	v_add_f32_dpp v41, v41, v41 row_ror:1 row_mask:0xf bank_mask:0xf
	v_mul_f32_e32 v92, 0x3a800000, v41
	v_pk_add_f32 v[96:97], v[78:79], v[92:93] op_sel_hi:[1,0] neg_lo:[0,1] neg_hi:[0,1]
	v_mov_b32_e32 v73, v69
	v_mov_b32_e32 v72, v97
	v_mov_b32_e32 v70, v96
	v_mov_b32_e32 v71, v68
	v_pk_mul_f32 v[72:73], v[72:73], v[72:73]
	v_pk_add_f32 v[32:33], v[32:33], v[92:93] op_sel_hi:[1,0] neg_lo:[0,1] neg_hi:[0,1]
	v_pk_fma_f32 v[78:79], v[70:71], v[70:71], v[72:73]
	v_mov_b32_e32 v98, v32
	v_mov_b32_e32 v99, v64
	v_pk_add_f32 v[100:101], v[80:81], v[92:93] op_sel_hi:[1,0] neg_lo:[0,1] neg_hi:[0,1]
	v_pk_fma_f32 v[78:79], v[98:99], v[98:99], v[78:79]
	v_mov_b32_e32 v80, v33
	v_mov_b32_e32 v81, v65
	v_pk_fma_f32 v[78:79], v[80:81], v[80:81], v[78:79]
	v_mov_b32_e32 v80, v100
	v_mov_b32_e32 v81, v66
	v_pk_add_f32 v[34:35], v[34:35], v[92:93] op_sel_hi:[1,0] neg_lo:[0,1] neg_hi:[0,1]
	v_pk_fma_f32 v[78:79], v[80:81], v[80:81], v[78:79]
	v_mov_b32_e32 v80, v101
	v_mov_b32_e32 v81, v67
	v_pk_fma_f32 v[78:79], v[80:81], v[80:81], v[78:79]
	v_mov_b32_e32 v80, v34
	v_mov_b32_e32 v81, v62
	v_pk_add_f32 v[74:75], v[88:89], v[92:93] op_sel_hi:[1,0] neg_lo:[0,1] neg_hi:[0,1]
	v_pk_fma_f32 v[78:79], v[80:81], v[80:81], v[78:79]
	v_mov_b32_e32 v80, v35
	v_mov_b32_e32 v81, v63
	v_pk_fma_f32 v[78:79], v[80:81], v[80:81], v[78:79]
	v_mov_b32_e32 v80, v74
	v_mov_b32_e32 v81, v56
	v_pk_add_f32 v[72:73], v[36:37], v[92:93] op_sel_hi:[1,0] neg_lo:[0,1] neg_hi:[0,1]
	v_pk_fma_f32 v[78:79], v[80:81], v[80:81], v[78:79]
	v_mov_b32_e32 v80, v75
	v_mov_b32_e32 v81, v57
	v_pk_add_f32 v[70:71], v[94:95], v[92:93] op_sel_hi:[1,0] neg_lo:[0,1] neg_hi:[0,1]
	v_pk_fma_f32 v[78:79], v[80:81], v[80:81], v[78:79]
	v_mov_b32_e32 v80, v72
	v_mov_b32_e32 v81, v54
	v_pk_mul_f32 v[76:77], v[58:59], v[58:59]
	v_pk_mul_f32 v[36:37], v[70:71], v[70:71]
	v_pk_fma_f32 v[78:79], v[80:81], v[80:81], v[78:79]
	v_mov_b32_e32 v80, v73
	v_mov_b32_e32 v81, v55
	v_pk_fma_f32 v[78:79], v[80:81], v[80:81], v[78:79]
	v_mov_b32_e32 v80, v36
	v_mov_b32_e32 v81, v76
	v_pk_add_f32 v[80:81], v[80:81], v[78:79]
	v_pk_add_f32 v[78:79], v[38:39], v[92:93] op_sel_hi:[1,0] neg_lo:[0,1] neg_hi:[0,1]
	v_pk_mul_f32 v[90:91], v[60:61], v[60:61]
	v_pk_mul_f32 v[38:39], v[78:79], v[78:79]
	v_mov_b32_e32 v76, v37
	v_pk_add_f32 v[36:37], v[76:77], v[80:81]
	v_mov_b32_e32 v76, v38
	v_mov_b32_e32 v77, v90
	v_pk_add_f32 v[36:37], v[76:77], v[36:37]
	v_mov_b32_e32 v90, v39
	v_pk_add_f32 v[36:37], v[90:91], v[36:37]
	ds_bpermute_b32 v39, v43, v37
	ds_bpermute_b32 v38, v43, v36
	s_waitcnt lgkmcnt(0)
	v_pk_add_f32 v[36:37], v[36:37], v[38:39]
	ds_bpermute_b32 v39, v82, v37
	ds_bpermute_b32 v38, v82, v36
	s_waitcnt lgkmcnt(0)
	v_pk_add_f32 v[36:37], v[36:37], v[38:39]
	s_waitcnt lgkmcnt(0)
	s_nop 1
	v_add_f32_dpp v36, v36, v36 row_ror:8 row_mask:0xf bank_mask:0xf
	v_add_f32_dpp v37, v37, v37 row_ror:8 row_mask:0xf bank_mask:0xf
	s_waitcnt lgkmcnt(0)
	s_nop 1
	v_add_f32_dpp v36, v36, v36 row_ror:4 row_mask:0xf bank_mask:0xf
	v_add_f32_dpp v37, v37, v37 row_ror:4 row_mask:0xf bank_mask:0xf
	s_waitcnt lgkmcnt(0)
	s_nop 1
	v_add_f32_dpp v36, v36, v36 row_ror:2 row_mask:0xf bank_mask:0xf
	v_add_f32_dpp v37, v37, v37 row_ror:2 row_mask:0xf bank_mask:0xf
	ds_bpermute_b32 v39, v86, v37
	ds_bpermute_b32 v38, v86, v36
	s_waitcnt lgkmcnt(0)
	v_pk_add_f32 v[36:37], v[36:37], v[38:39]
	v_mov_b32_e32 v38, 0x358637bd
	v_pk_fma_f32 v[76:77], v[36:37], s[30:31], v[38:39] op_sel_hi:[1,0,0]
	s_mov_b64 s[30:31], -1
	v_mul_f32_e32 v36, 0x4b800000, v76
	v_cmp_gt_f32_e32 vcc, s2, v76
	v_cmp_gt_f32_e64 s[38:39], s2, v77
	s_nop 0
	v_cndmask_b32_e32 v36, v76, v36, vcc
	v_rsq_f32_e32 v36, v36
	s_nop 0
	v_mul_f32_e32 v37, 0x45800000, v36
	v_cndmask_b32_e32 v80, v36, v37, vcc
	v_pk_mul_f32 v[32:33], v[32:33], v[80:81] op_sel_hi:[1,0]
	v_pk_mul_f32 v[36:37], v[96:97], v[80:81] op_sel_hi:[1,0]
	v_pk_fma_f32 v[38:39], v[6:7], v[32:33], v[14:15]
	v_pk_mul_f32 v[32:33], v[100:101], v[80:81] op_sel_hi:[1,0]
	v_pk_mul_f32 v[34:35], v[34:35], v[80:81] op_sel_hi:[1,0]
	v_pk_fma_f32 v[36:37], v[4:5], v[36:37], v[12:13]
	v_pk_fma_f32 v[32:33], v[0:1], v[32:33], v[8:9]
	v_pk_fma_f32 v[34:35], v[2:3], v[34:35], v[10:11]
	s_and_b64 vcc, exec, s[0:1]
	s_cbranch_vccz .LBB0_1517
	s_mov_b32 s30, 0xee400000
	s_mov_b32 s31, -1
	v_lshl_add_u64 v[92:93], v[46:47], 0, s[30:31]
	v_cvt_pk_bf16_f32 v88, v36, v37
	v_cvt_pk_bf16_f32 v89, v38, v39
	v_cvt_pk_bf16_f32 v90, v32, v33
	v_cvt_pk_bf16_f32 v91, v34, v35
	global_store_dwordx4 v[92:93], v[88:91], off
	s_mov_b64 s[30:31], 0
